# in_o swap K-loop pipelined (3-quad LDS ring, SALU-stepped A chunk bases); ple Wg K-loops with full-iteration A lead
# speedup vs baseline: 1.0288x; 1.0068x over previous
; #define A256_LOADH(kt_, hf_) { a0 = la.ld1(kt_, (hf_) * 4 + 0, tid); a1 = la.ld1(kt_, (hf_) * 4 + 1, tid); a2 = la.ld1(kt_, (hf_) * 4 + 2, tid); a3 = la.ld1(kt_, (hf_) * 4 + 3, tid); }
; #define ZERO_ACC8(a) { _Pragma("unroll") for (int i_ = 0; i_ < 8; i_++) _Pragma("unroll") for (int r_ = 0; r_ < 16; r_++) a[i_][r_] = 0.f; }
; template <bool swap, class LA>
; DI void gemm256_ws(const LA& la, const bf16_t* Wt, const int KS, const int nk, bf16_t* smem, f32x16 (&acc)[8]) {
;     ...
;   A256_LOADH(0, 0) A256_STH(smem, 0)
;   A256_LOADH(0, 1) A256_STH(smem, 1)
;   W256_LD(0, 0, w00, w10) W256_LD(0, 1, w01, w11) W256_LD(0, 2, w02, w12) W256_LD(0, 3, w03, w13)
;   __syncthreads();
;   const int aoff = (tbk * 128 + l32) * LDT + h * 8;
; DI void ph_in_o(const Params& P, int g, bf16_t* smem, float* s_rs) {
;     ...
;   for (int it = 0;; it++) {
;     int mt, nt; if (!tile_sched256(bid, it, 20, 10, mt, nt)) break;
;     const int m0 = mt * 256, n0 = nt * 128;
;     __syncthreads();
;     {
;       const float4* pp = (const float4*)(ssx + (size_t)(m0 + tid) * 16);
;       float4 a = pp[0], b = pp[1], c = pp[2], d = pp[3];
;       float s = a.x + a.y + a.z + a.w + b.x + b.y + b.z + b.w + c.x + c.y + c.z + c.w + d.x + d.y + d.z + d.w;
;       s_rs[tid] = rsqrtf(s * (1.f / 1024.f) + EPS);
;     }
;     f32x16 acc[8]; ZERO_ACC8(acc)
;     LoadTile256 la{x2b + (size_t)(2 * mt) * 16 * 8192, 16 * 8192};
;     const bool isY = (nt >= 8 && nt < 16);
;     gemm256(la, W + (size_t)n0 * 1024, 64, 16, smem, acc, !isY);
.LBB0_181:
	s_lshl_b32 s86, s29, 8
	v_add_u32_e32 v2, s86, v169
	v_ashrrev_i32_e32 v3, 31, v2
	v_readlane_b32 s2, v253, 45
	v_lshlrev_b64 v[2:3], 6, v[2:3]
	v_readlane_b32 s3, v253, 46
	s_barrier
	s_nop 0
	v_lshl_add_u64 v[14:15], s[2:3], 0, v[2:3]
	global_load_dwordx4 v[2:5], v[14:15], off offset:48
	global_load_dwordx4 v[6:9], v[14:15], off offset:32
	global_load_dwordx4 v[10:13], v[14:15], off offset:16
	s_nop 0
	global_load_dwordx4 v[14:17], v[14:15], off
	s_mov_b32 s2, 0x800000
	s_lshl_b32 s12, s6, 7
	v_readlane_b32 s8, v253, 47
	v_readlane_b32 s9, v253, 48
	s_waitcnt vmcnt(0)
	v_add_f32_e32 v0, v14, v15
	v_add_f32_e32 v0, v0, v16
	v_add_f32_e32 v0, v0, v17
	v_add_f32_e32 v0, v0, v10
	v_add_f32_e32 v0, v0, v11
	v_add_f32_e32 v0, v0, v12
	v_add_f32_e32 v0, v0, v13
	v_add_f32_e32 v0, v0, v6
	v_add_f32_e32 v0, v0, v7
	v_add_f32_e32 v0, v0, v8
	v_add_f32_e32 v0, v0, v9
	v_add_f32_e32 v0, v0, v2
	v_add_f32_e32 v0, v0, v3
	v_add_f32_e32 v0, v0, v4
	v_add_f32_e32 v0, v0, v5
	v_fmamk_f32 v0, v0, 0x3a800000, v235
	v_cmp_gt_f32_e32 vcc, s2, v0
	s_lshl_b32 s2, s29, 1
	s_ashr_i32 s3, s2, 31
	s_lshl_b64 s[14:15], s[2:3], 18
	v_mul_f32_e32 v2, 0x4b800000, v0
	s_add_u32 s10, s82, s14
	v_cndmask_b32_e32 v0, v0, v2, vcc
	s_addc_u32 s11, s83, s15
	s_and_b32 s18, s6, -8
	v_rsq_f32_e32 v0, v0
	s_cmp_lg_u32 s18, 8
	s_cselect_b64 s[2:3], -1, 0
	s_ashr_i32 s13, s12, 31
	s_lshl_b64 s[16:17], s[12:13], 11
	s_add_u32 s8, s8, s16
	v_mul_f32_e32 v2, 0x45800000, v0
	s_addc_u32 s9, s9, s17
	v_cndmask_b32_e32 v0, v0, v2, vcc
	v_lshl_add_u32 v2, v169, 2, v244
	s_cmp_eq_u32 s18, 8
	s_mov_b64 s[18:19], -1
	ds_write_b32 v2, v0
	s_cbranch_scc1 .LBB0_194
	v_mov_b32_e32 v0, v234
	s_add_u32 s18, s10, 0x40000
	v_lshlrev_b32_e32 v2, 3, v0
	v_ashrrev_i32_e32 v3, 31, v2
	v_ashrrev_i32_e32 v48, 6, v0
	v_lshlrev_b64 v[196:197], 1, v[2:3]
	v_add_u32_e32 v6, 0x800, v2
	v_add_u32_e32 v8, 0x1000, v2
	v_add_u32_e32 v2, 0x1800, v2
	v_lshlrev_b32_e32 v49, 4, v0
	v_and_b32_e32 v48, -2, v48
	v_ashrrev_i32_e32 v3, 31, v2
	v_and_b32_e32 v15, 31, v0
	v_lshrrev_b32_e32 v51, 3, v0
	v_lshlrev_b32_e32 v52, 1, v0
	v_lshrrev_b32_e32 v53, 1, v0
	v_and_b32_e32 v0, 0x3f0, v49
	v_and_b32_e32 v50, 0x70, v49
	v_ashrrev_i32_e32 v49, 31, v48
	v_ashrrev_i32_e32 v7, 31, v6
	v_ashrrev_i32_e32 v9, 31, v8
	v_lshlrev_b64 v[202:203], 1, v[2:3]
	v_lshlrev_b64 v[48:49], 16, v[48:49]
	v_lshl_add_u64 v[4:5], s[10:11], 0, v[196:197]
	v_lshlrev_b64 v[198:199], 1, v[6:7]
	v_lshlrev_b64 v[200:201], 1, v[8:9]
	v_lshl_add_u64 v[2:3], s[10:11], 0, v[202:203]
	s_addc_u32 s19, s11, 0
	v_lshl_add_u64 v[48:49], s[8:9], 0, v[48:49]
	v_lshl_add_u64 v[6:7], s[10:11], 0, v[198:199]
	v_lshl_add_u64 v[8:9], s[10:11], 0, v[200:201]
	global_load_dwordx4 v[16:19], v[4:5], off
	global_load_dwordx4 v[20:23], v[6:7], off
	global_load_dwordx4 v[24:27], v[8:9], off
	global_load_dwordx4 v[28:31], v[2:3], off
	v_lshl_add_u64 v[2:3], s[18:19], 0, v[196:197]
	v_lshl_add_u64 v[206:207], v[48:49], 0, v[0:1]
	global_load_dwordx4 v[32:35], v[2:3], off
	v_lshl_add_u64 v[2:3], s[18:19], 0, v[198:199]
	v_add_co_u32_e32 v48, vcc, s94, v206
	v_lshl_add_u64 v[4:5], s[18:19], 0, v[200:201]
	v_lshl_add_u64 v[6:7], s[18:19], 0, v[202:203]
	global_load_dwordx4 v[36:39], v[2:3], off
	global_load_dwordx4 v[40:43], v[4:5], off
	global_load_dwordx4 v[44:47], v[6:7], off
	v_addc_co_u32_e32 v49, vcc, 0, v207, vcc
	global_load_dwordx4 v[154:157], v[48:49], off
	global_load_dwordx4 v[158:161], v[206:207], off
	global_load_dwordx4 v[146:149], v[48:49], off offset:1024
	global_load_dwordx4 v[150:153], v[206:207], off offset:1024
	global_load_dwordx4 v[142:145], v[48:49], off offset:2048
	global_load_dwordx4 v[138:141], v[206:207], off offset:2048
	global_load_dwordx4 v[130:133], v[48:49], off offset:3072
	global_load_dwordx4 v[134:137], v[206:207], off offset:3072
	s_movk_i32 s36, 0x80
	v_and_or_b32 v15, v52, s36, v15
	v_mad_u64_u32 v[204:205], s[36:37], v51, s0, v[50:51]
	v_mov_b32_e32 v2, 0
	v_and_b32_e32 v52, 16, v53
	s_mov_b64 s[36:37], 0x10000
	s_mov_b32 s13, 0
	v_mov_b32_e32 v3, v2
	v_mov_b32_e32 v4, v2
	v_mov_b32_e32 v5, v2
	v_mov_b32_e32 v6, v2
	v_mov_b32_e32 v7, v2
	v_mov_b32_e32 v8, v2
	v_mov_b32_e32 v9, v2
	v_mov_b32_e32 v10, v2
	v_mov_b32_e32 v11, v2
	v_mov_b32_e32 v12, v2
	v_mov_b32_e32 v13, v2
	v_mov_b32_e32 v14, v2
	v_mad_u32_u24 v195, v15, s0, v52
	v_lshl_add_u64 v[208:209], v[206:207], 0, s[36:37]
	v_mov_b32_e32 v15, v2
	v_mov_b32_e32 v48, v2
	v_mov_b32_e32 v49, v2
	v_mov_b32_e32 v82, v2
	v_mov_b32_e32 v83, v2
	v_mov_b32_e32 v84, v2
	v_mov_b32_e32 v85, v2
	v_mov_b32_e32 v86, v2
	v_mov_b32_e32 v87, v2
	v_mov_b32_e32 v88, v2
	v_mov_b32_e32 v89, v2
	v_mov_b32_e32 v90, v2
	v_mov_b32_e32 v91, v2
	v_mov_b32_e32 v92, v2
	v_mov_b32_e32 v93, v2
	v_mov_b32_e32 v94, v2
	v_mov_b32_e32 v95, v2
	v_mov_b32_e32 v96, v2
	v_mov_b32_e32 v97, v2
	v_mov_b32_e32 v50, v2
	v_mov_b32_e32 v51, v2
	v_mov_b32_e32 v52, v2
	s_waitcnt vmcnt(15)
	ds_write_b128 v204, v[16:19]
	s_waitcnt vmcnt(11)
	ds_write_b128 v204, v[32:35] offset:18432
	ds_write_b128 v204, v[20:23] offset:4608
	ds_write_b128 v204, v[24:27] offset:9216
	ds_write_b128 v204, v[28:31] offset:13824
	s_waitcnt vmcnt(10)
	ds_write_b128 v204, v[36:39] offset:23040
	s_waitcnt vmcnt(9)
	ds_write_b128 v204, v[40:43] offset:27648
	s_waitcnt vmcnt(8)
; #define A256_LOADH(kt_, hf_) { a0 = la.ld1(kt_, (hf_) * 4 + 0, tid); a1 = la.ld1(kt_, (hf_) * 4 + 1, tid); a2 = la.ld1(kt_, (hf_) * 4 + 2, tid); a3 = la.ld1(kt_, (hf_) * 4 + 3, tid); }
; template <bool swap, class LA>
; DI void gemm256_ws(const LA& la, const bf16_t* Wt, const int KS, const int nk, bf16_t* smem, f32x16 (&acc)[8]) {
;     ...
;   A256_LOADH(0, 0) A256_STH(smem, 0)
;   A256_LOADH(0, 1) A256_STH(smem, 1)
;   W256_LD(0, 0, w00, w10) W256_LD(0, 1, w01, w11) W256_LD(0, 2, w02, w12) W256_LD(0, 3, w03, w13)
;   __syncthreads();
;   const int aoff = (tbk * 128 + l32) * LDT + h * 8;
	ds_write_b128 v204, v[44:47] offset:32256
	v_mov_b32_e32 v16, v2
	v_mov_b32_e32 v17, v2
	v_mov_b32_e32 v34, v2
	v_mov_b32_e32 v35, v2
	v_mov_b32_e32 v36, v2
	v_mov_b32_e32 v37, v2
	v_mov_b32_e32 v38, v2
	v_mov_b32_e32 v39, v2
	v_mov_b32_e32 v40, v2
	v_mov_b32_e32 v41, v2
	v_mov_b32_e32 v42, v2
	v_mov_b32_e32 v43, v2
	v_mov_b32_e32 v44, v2
	v_mov_b32_e32 v45, v2
	v_mov_b32_e32 v46, v2
	v_mov_b32_e32 v47, v2
	v_mov_b32_e32 v18, v2
	v_mov_b32_e32 v19, v2
	v_mov_b32_e32 v20, v2
	v_mov_b32_e32 v21, v2
	v_mov_b32_e32 v22, v2
	v_mov_b32_e32 v23, v2
	v_mov_b32_e32 v24, v2
	v_mov_b32_e32 v25, v2
	v_mov_b32_e32 v26, v2
	v_mov_b32_e32 v27, v2
	v_mov_b32_e32 v28, v2
	v_mov_b32_e32 v29, v2
	v_mov_b32_e32 v30, v2
	v_mov_b32_e32 v31, v2
	v_mov_b32_e32 v32, v2
	v_mov_b32_e32 v33, v2
	v_mov_b32_e32 v53, v2
	v_mov_b32_e32 v54, v2
	v_mov_b32_e32 v55, v2
	v_mov_b32_e32 v56, v2
	v_mov_b32_e32 v57, v2
	v_mov_b32_e32 v58, v2
	v_mov_b32_e32 v59, v2
	v_mov_b32_e32 v60, v2
	v_mov_b32_e32 v61, v2
	v_mov_b32_e32 v62, v2
	v_mov_b32_e32 v63, v2
	v_mov_b32_e32 v64, v2
	v_mov_b32_e32 v65, v2
	v_mov_b32_e32 v98, v2
	v_mov_b32_e32 v99, v2
	v_mov_b32_e32 v100, v2
	v_mov_b32_e32 v101, v2
	v_mov_b32_e32 v102, v2
	v_mov_b32_e32 v103, v2
	v_mov_b32_e32 v104, v2
	v_mov_b32_e32 v105, v2
	v_mov_b32_e32 v106, v2
	v_mov_b32_e32 v107, v2
	v_mov_b32_e32 v108, v2
	v_mov_b32_e32 v109, v2
	v_mov_b32_e32 v110, v2
	v_mov_b32_e32 v111, v2
	v_mov_b32_e32 v112, v2
	v_mov_b32_e32 v113, v2
	v_mov_b32_e32 v66, v2
	v_mov_b32_e32 v67, v2
	v_mov_b32_e32 v68, v2
	v_mov_b32_e32 v69, v2
	v_mov_b32_e32 v70, v2
	v_mov_b32_e32 v71, v2
	v_mov_b32_e32 v72, v2
	v_mov_b32_e32 v73, v2
	v_mov_b32_e32 v74, v2
	v_mov_b32_e32 v75, v2
	v_mov_b32_e32 v76, v2
	v_mov_b32_e32 v77, v2
	v_mov_b32_e32 v78, v2
	v_mov_b32_e32 v79, v2
	v_mov_b32_e32 v80, v2
	v_mov_b32_e32 v81, v2
	v_mov_b32_e32 v114, v2
	v_mov_b32_e32 v115, v2
	v_mov_b32_e32 v116, v2
	v_mov_b32_e32 v117, v2
	v_mov_b32_e32 v118, v2
	v_mov_b32_e32 v119, v2
	v_mov_b32_e32 v120, v2
	v_mov_b32_e32 v121, v2
	v_mov_b32_e32 v122, v2
	v_mov_b32_e32 v123, v2
	v_mov_b32_e32 v124, v2
	v_mov_b32_e32 v125, v2
	v_mov_b32_e32 v126, v2
	v_mov_b32_e32 v127, v2
	v_mov_b32_e32 v128, v2
	v_mov_b32_e32 v129, v2
	s_waitcnt lgkmcnt(0)
	s_barrier
; #define A256_LOADH(kt_, hf_) { a0 = la.ld1(kt_, (hf_) * 4 + 0, tid); a1 = la.ld1(kt_, (hf_) * 4 + 1, tid); a2 = la.ld1(kt_, (hf_) * 4 + 2, tid); a3 = la.ld1(kt_, (hf_) * 4 + 3, tid); }
; template <bool swap, class LA>
; DI void gemm256_ws(const LA& la, const bf16_t* Wt, const int KS, const int nk, bf16_t* smem, f32x16 (&acc)[8]) {
;     ...
;   for (int kt = 0; kt < nk; kt++) {
;     const int cur = kt & 1; const int kn = (kt + 1 < nk) ? kt + 1 : last;
;     const bf16_t* sp = smem + cur * ATILE_E + aoff;
;     bf16_t* nxt = smem + (cur ^ 1) * ATILE_E;
;     A256_LOADH(kn, 0)
;     MMA256(0, w00, w10) W256_LD(kn, 0, w00, w10)
;     MMA256(1, w01, w11) W256_LD(kn, 1, w01, w11)
;     A256_STH(nxt, 0)
;     A256_LOADH(kn, 1)
;     MMA256(2, w02, w12) W256_LD(kn, 2, w02, w12)
;     MMA256(3, w03, w13) W256_LD(kn, 3, w03, w13)
;     A256_STH(nxt, 1)
;     __syncthreads();
.LBB0_183:
	s_and_b32 s36, s13, 1
	s_mul_i32 s37, s36, 0x9000
	v_add_u32_e32 v0, s37, v195
	ds_read_b128 v[210:213], v0
	ds_read_b128 v[214:217], v0 offset:4608
	ds_read_b128 v[220:223], v0 offset:9216
	s_add_i32 s13, s13, 1
	s_min_u32 s38, s13, 15
	s_xor_b32 s36, s36, 1
	s_mul_i32 s37, s36, 0x9000
	v_add_u32_e32 v205, s37, v204
	s_lshl_b32 s39, s38, 14
	s_lshl_b32 s90, s38, 12
	s_add_u32 s36, s10, s39
	s_addc_u32 s37, s11, 0
	v_lshl_add_u64 v[224:225], s[36:37], 0, v[196:197]
	s_add_u32 s36, s36, 0x1000
	s_addc_u32 s37, s37, 0
	v_lshl_add_u64 v[228:229], s[36:37], 0, v[196:197]
	s_add_u32 s36, s36, 0x1000
	s_addc_u32 s37, s37, 0
	v_lshl_add_u64 v[246:247], s[36:37], 0, v[196:197]
	s_add_u32 s36, s36, 0x1000
	s_addc_u32 s37, s37, 0
	v_lshl_add_u64 v[198:199], s[36:37], 0, v[196:197]
	global_load_dwordx4 v[224:227], v[224:225], off
	global_load_dwordx4 v[228:231], v[228:229], off
	global_load_dwordx4 v[246:249], v[246:247], off
	global_load_dwordx4 v[198:201], v[198:199], off
	s_waitcnt vmcnt(10) lgkmcnt(2)
	v_mfma_f32_32x32x16_bf16 v[82:97], v[154:157], v[210:213], v[82:97]
	v_mfma_f32_32x32x16_bf16 v[114:129], v[158:161], v[210:213], v[114:129]
	ds_read_b128 v[210:213], v0 offset:13824
	s_waitcnt lgkmcnt(2)
	v_mfma_f32_32x32x16_bf16 v[18:33], v[154:157], v[214:217], v[18:33]
	v_mfma_f32_32x32x16_bf16 v[66:81], v[158:161], v[214:217], v[66:81]
	ds_read_b128 v[214:217], v0 offset:32
	s_waitcnt lgkmcnt(2)
	v_mfma_f32_32x32x16_bf16 v[34:49], v[154:157], v[220:223], v[34:49]
	v_mfma_f32_32x32x16_bf16 v[98:113], v[158:161], v[220:223], v[98:113]
	ds_read_b128 v[220:223], v0 offset:4640
	s_waitcnt lgkmcnt(2)
	v_mfma_f32_32x32x16_bf16 v[2:17], v[154:157], v[210:213], v[2:17]
	v_mfma_f32_32x32x16_bf16 v[50:65], v[158:161], v[210:213], v[50:65]
	ds_read_b128 v[210:213], v0 offset:9248
	v_lshl_add_u64 v[154:155], v[208:209], 0, s[90:91]
	global_load_dwordx4 v[154:157], v[154:155], off
	v_lshl_add_u64 v[158:159], v[206:207], 0, s[90:91]
	global_load_dwordx4 v[158:161], v[158:159], off
	s_waitcnt vmcnt(10) lgkmcnt(2)
	v_mfma_f32_32x32x16_bf16 v[82:97], v[146:149], v[214:217], v[82:97]
	v_mfma_f32_32x32x16_bf16 v[114:129], v[150:153], v[214:217], v[114:129]
	ds_read_b128 v[214:217], v0 offset:13856
	s_waitcnt lgkmcnt(2)
	v_mfma_f32_32x32x16_bf16 v[18:33], v[146:149], v[220:223], v[18:33]
	v_mfma_f32_32x32x16_bf16 v[66:81], v[150:153], v[220:223], v[66:81]
	ds_read_b128 v[220:223], v0 offset:64
	s_waitcnt lgkmcnt(2)
	v_mfma_f32_32x32x16_bf16 v[34:49], v[146:149], v[210:213], v[34:49]
	v_mfma_f32_32x32x16_bf16 v[98:113], v[150:153], v[210:213], v[98:113]
	ds_read_b128 v[210:213], v0 offset:4672
	s_waitcnt lgkmcnt(2)
	v_mfma_f32_32x32x16_bf16 v[2:17], v[146:149], v[214:217], v[2:17]
	v_mfma_f32_32x32x16_bf16 v[50:65], v[150:153], v[214:217], v[50:65]
	ds_read_b128 v[214:217], v0 offset:9280
	v_lshl_add_u64 v[146:147], v[208:209], 0, s[90:91]
	global_load_dwordx4 v[146:149], v[146:147], off offset:1024
	v_lshl_add_u64 v[150:151], v[206:207], 0, s[90:91]
	global_load_dwordx4 v[150:153], v[150:151], off offset:1024
	s_waitcnt vmcnt(4)
	ds_write_b128 v205, v[224:227]
	ds_write_b128 v205, v[228:231] offset:4608
	ds_write_b128 v205, v[246:249] offset:9216
	ds_write_b128 v205, v[198:201] offset:13824
	s_add_u32 s36, s18, s39
	s_addc_u32 s37, s19, 0
	v_lshl_add_u64 v[224:225], s[36:37], 0, v[196:197]
	s_add_u32 s36, s36, 0x1000
	s_addc_u32 s37, s37, 0
	v_lshl_add_u64 v[228:229], s[36:37], 0, v[196:197]
	s_add_u32 s36, s36, 0x1000
	s_addc_u32 s37, s37, 0
	v_lshl_add_u64 v[246:247], s[36:37], 0, v[196:197]
	s_add_u32 s36, s36, 0x1000
	s_addc_u32 s37, s37, 0
	v_lshl_add_u64 v[198:199], s[36:37], 0, v[196:197]
	global_load_dwordx4 v[224:227], v[224:225], off
	global_load_dwordx4 v[228:231], v[228:229], off
	global_load_dwordx4 v[246:249], v[246:247], off
	global_load_dwordx4 v[198:201], v[198:199], off
	s_waitcnt lgkmcnt(6)
	v_mfma_f32_32x32x16_bf16 v[82:97], v[142:145], v[220:223], v[82:97]
	v_mfma_f32_32x32x16_bf16 v[114:129], v[138:141], v[220:223], v[114:129]
	ds_read_b128 v[220:223], v0 offset:13888
	s_waitcnt lgkmcnt(6)
	v_mfma_f32_32x32x16_bf16 v[18:33], v[142:145], v[210:213], v[18:33]
	v_mfma_f32_32x32x16_bf16 v[66:81], v[138:141], v[210:213], v[66:81]
	ds_read_b128 v[210:213], v0 offset:96
	s_waitcnt lgkmcnt(6)
	v_mfma_f32_32x32x16_bf16 v[34:49], v[142:145], v[214:217], v[34:49]
	v_mfma_f32_32x32x16_bf16 v[98:113], v[138:141], v[214:217], v[98:113]
	ds_read_b128 v[214:217], v0 offset:4704
	s_waitcnt lgkmcnt(2)
	v_mfma_f32_32x32x16_bf16 v[2:17], v[142:145], v[220:223], v[2:17]
	v_mfma_f32_32x32x16_bf16 v[50:65], v[138:141], v[220:223], v[50:65]
	ds_read_b128 v[220:223], v0 offset:9312
	v_lshl_add_u64 v[142:143], v[208:209], 0, s[90:91]
	global_load_dwordx4 v[142:145], v[142:143], off offset:2048
	v_lshl_add_u64 v[138:139], v[206:207], 0, s[90:91]
	global_load_dwordx4 v[138:141], v[138:139], off offset:2048
	s_waitcnt lgkmcnt(2)
	v_mfma_f32_32x32x16_bf16 v[82:97], v[130:133], v[210:213], v[82:97]
	v_mfma_f32_32x32x16_bf16 v[114:129], v[134:137], v[210:213], v[114:129]
	ds_read_b128 v[210:213], v0 offset:13920
	s_waitcnt lgkmcnt(2)
	v_mfma_f32_32x32x16_bf16 v[18:33], v[130:133], v[214:217], v[18:33]
	v_mfma_f32_32x32x16_bf16 v[66:81], v[134:137], v[214:217], v[66:81]
	s_waitcnt lgkmcnt(1)
	v_mfma_f32_32x32x16_bf16 v[34:49], v[130:133], v[220:223], v[34:49]
	v_mfma_f32_32x32x16_bf16 v[98:113], v[134:137], v[220:223], v[98:113]
	s_waitcnt lgkmcnt(0)
	v_mfma_f32_32x32x16_bf16 v[2:17], v[130:133], v[210:213], v[2:17]
	v_mfma_f32_32x32x16_bf16 v[50:65], v[134:137], v[210:213], v[50:65]
	v_lshl_add_u64 v[130:131], v[208:209], 0, s[90:91]
	global_load_dwordx4 v[130:133], v[130:131], off offset:3072
	v_lshl_add_u64 v[134:135], v[206:207], 0, s[90:91]
	global_load_dwordx4 v[134:137], v[134:135], off offset:3072
	s_waitcnt vmcnt(4)
	ds_write_b128 v205, v[224:227] offset:18432
	ds_write_b128 v205, v[228:231] offset:23040
	ds_write_b128 v205, v[246:249] offset:27648
	ds_write_b128 v205, v[198:201] offset:32256
	s_cmp_eq_u32 s13, 16
	s_waitcnt lgkmcnt(0)
	s_barrier
	s_cbranch_scc0 .LBB0_183
	s_waitcnt vmcnt(0)

; DI size_t tix(size_t t, int f, int KT) { return ((t >> 7) * KT + (f >> 6)) * 8192 + (t & 127) * 64 + (f & 63); }
; DI void rows_out_tiled(const bf16_t* smem, bf16_t* buf, size_t t0, int f0, int KT, int tid) {
; #pragma unroll 8
;   for (int k = 0; k < 16; k++) { const int c = tid + 256 * k; const int ch = c & 7, row = (c >> 3) & 255, fh = c >> 11;
;     *(uint4*)(buf + tix(t0 + row, f0 + fh * 64 + ch * 8, KT)) = *(const uint4*)(smem + row * EPLD + fh * 64 + ch * 8); }
; }
.LBB0_234:
	v_add_u32_e32 v14, s10, v163
	v_ashrrev_i32_e32 v0, 5, v14
	v_lshlrev_b32_e32 v6, 1, v0
	v_and_b32_e32 v6, 0xffffff80, v6
	v_add_u32_e32 v0, s8, v0
	v_add_u32_e32 v8, v175, v6
	v_ashrrev_i32_e32 v6, 6, v0
	v_ashrrev_i32_e32 v7, 31, v6
	v_lshl_add_u64 v[6:7], v[2:3], 0, v[6:7]
	v_lshlrev_b64 v[6:7], 14, v[6:7]
	v_lshl_add_u64 v[10:11], v[4:5], 0, v[6:7]
	ds_read_b128 v[6:9], v8
	v_add_u32_e32 v0, 0x100, v14
	v_mov_b32_e32 v169, v1
	s_addk_i32 s10, 0x800
	s_cmpk_lg_i32 s10, 0x1000
	s_waitcnt lgkmcnt(0)
	global_store_dwordx4 v[10:11], v[6:9], off
	s_nop 1
	v_bfe_u32 v6, v0, 3, 8
	v_ashrrev_i32_e32 v0, 5, v0
	v_lshlrev_b32_e32 v8, 1, v0
	v_mul_u32_u24_e32 v7, 0x110, v6
	v_and_b32_e32 v8, 0xffffff80, v8
	v_add3_u32 v15, v7, v8, v168
	v_or_b32_e32 v6, s18, v6
	v_mov_b32_e32 v7, s19
	v_add_u32_e32 v0, s8, v0
	v_lshrrev_b64 v[8:9], 3, v[6:7]
	v_ashrrev_i32_e32 v10, 6, v0
	v_and_b32_e32 v9, 0x3ffff, v9
	v_and_b32_e32 v8, -16, v8
	v_ashrrev_i32_e32 v11, 31, v10
	v_lshl_add_u64 v[8:9], v[8:9], 0, v[10:11]
	v_lshlrev_b64 v[8:9], 14, v[8:9]
	v_lshlrev_b32_e32 v0, 7, v6
	v_lshl_add_u64 v[8:9], s[82:83], 0, v[8:9]
	v_and_b32_e32 v0, 0x3f80, v0
	v_lshl_add_u64 v[8:9], v[8:9], 0, v[0:1]
	v_lshl_add_u64 v[12:13], v[8:9], 0, v[168:169]
	ds_read_b128 v[8:11], v15
	v_add_u32_e32 v0, 0x200, v14
	v_bfe_u32 v6, v0, 3, 8
	v_ashrrev_i32_e32 v0, 5, v0
	s_waitcnt lgkmcnt(0)
	global_store_dwordx4 v[12:13], v[8:11], off
	s_nop 1
	v_lshlrev_b32_e32 v9, 1, v0
	v_mul_u32_u24_e32 v8, 0x110, v6
	v_and_b32_e32 v9, 0xffffff80, v9
	v_or_b32_e32 v6, s18, v6
	v_add_u32_e32 v0, s8, v0
	v_add3_u32 v15, v8, v9, v168
	v_lshrrev_b64 v[8:9], 3, v[6:7]
	v_ashrrev_i32_e32 v10, 6, v0
	v_and_b32_e32 v9, 0x3ffff, v9
	v_and_b32_e32 v8, -16, v8
	v_ashrrev_i32_e32 v11, 31, v10
	v_lshl_add_u64 v[8:9], v[8:9], 0, v[10:11]
	v_lshlrev_b64 v[8:9], 14, v[8:9]
	v_lshlrev_b32_e32 v0, 7, v6
	v_lshl_add_u64 v[8:9], s[82:83], 0, v[8:9]
	v_and_b32_e32 v0, 0x3f80, v0
	v_lshl_add_u64 v[8:9], v[8:9], 0, v[0:1]
	v_lshl_add_u64 v[12:13], v[8:9], 0, v[168:169]
	ds_read_b128 v[8:11], v15
	v_add_u32_e32 v0, 0x300, v14
	v_bfe_u32 v6, v0, 3, 8
	v_ashrrev_i32_e32 v0, 5, v0
	s_waitcnt lgkmcnt(0)
	global_store_dwordx4 v[12:13], v[8:11], off
	s_nop 1
	v_lshlrev_b32_e32 v9, 1, v0
	v_mul_u32_u24_e32 v8, 0x110, v6
	v_and_b32_e32 v9, 0xffffff80, v9
	v_or_b32_e32 v6, s18, v6
	v_add_u32_e32 v0, s8, v0
	v_add3_u32 v15, v8, v9, v168
	v_lshrrev_b64 v[8:9], 3, v[6:7]
	v_ashrrev_i32_e32 v10, 6, v0
	v_and_b32_e32 v9, 0x3ffff, v9
	v_and_b32_e32 v8, -16, v8
	v_ashrrev_i32_e32 v11, 31, v10
	v_lshl_add_u64 v[8:9], v[8:9], 0, v[10:11]
	v_lshlrev_b64 v[8:9], 14, v[8:9]
	v_lshlrev_b32_e32 v0, 7, v6
	v_lshl_add_u64 v[8:9], s[82:83], 0, v[8:9]
	v_and_b32_e32 v0, 0x3f80, v0
	v_lshl_add_u64 v[8:9], v[8:9], 0, v[0:1]
	v_lshl_add_u64 v[12:13], v[8:9], 0, v[168:169]
	ds_read_b128 v[8:11], v15
	v_add_u32_e32 v0, 0x400, v14
	v_bfe_u32 v6, v0, 3, 8
	v_ashrrev_i32_e32 v0, 5, v0
	s_waitcnt lgkmcnt(0)
	global_store_dwordx4 v[12:13], v[8:11], off
	s_nop 1
	v_lshlrev_b32_e32 v9, 1, v0
	v_mul_u32_u24_e32 v8, 0x110, v6
	v_and_b32_e32 v9, 0xffffff80, v9
	v_or_b32_e32 v6, s18, v6
	v_add_u32_e32 v0, s8, v0
	v_add3_u32 v15, v8, v9, v168
	v_lshrrev_b64 v[8:9], 3, v[6:7]
	v_ashrrev_i32_e32 v10, 6, v0
	v_and_b32_e32 v9, 0x3ffff, v9
	v_and_b32_e32 v8, -16, v8
	v_ashrrev_i32_e32 v11, 31, v10
	v_lshl_add_u64 v[8:9], v[8:9], 0, v[10:11]
	v_lshlrev_b64 v[8:9], 14, v[8:9]
	v_lshlrev_b32_e32 v0, 7, v6
	v_lshl_add_u64 v[8:9], s[82:83], 0, v[8:9]
	v_and_b32_e32 v0, 0x3f80, v0
	v_lshl_add_u64 v[8:9], v[8:9], 0, v[0:1]
	v_lshl_add_u64 v[12:13], v[8:9], 0, v[168:169]
	ds_read_b128 v[8:11], v15
	v_add_u32_e32 v0, 0x500, v14
	v_bfe_u32 v6, v0, 3, 8
	v_ashrrev_i32_e32 v0, 5, v0
	s_waitcnt lgkmcnt(0)
	global_store_dwordx4 v[12:13], v[8:11], off
	s_nop 1
	v_lshlrev_b32_e32 v9, 1, v0
	v_mul_u32_u24_e32 v8, 0x110, v6
	v_and_b32_e32 v9, 0xffffff80, v9
	v_or_b32_e32 v6, s18, v6
	v_add_u32_e32 v0, s8, v0
	v_add3_u32 v15, v8, v9, v168
	v_lshrrev_b64 v[8:9], 3, v[6:7]
	v_ashrrev_i32_e32 v10, 6, v0
	v_and_b32_e32 v9, 0x3ffff, v9
	v_and_b32_e32 v8, -16, v8
	v_ashrrev_i32_e32 v11, 31, v10
	v_lshl_add_u64 v[8:9], v[8:9], 0, v[10:11]
	v_lshlrev_b64 v[8:9], 14, v[8:9]
	v_lshlrev_b32_e32 v0, 7, v6
	v_lshl_add_u64 v[8:9], s[82:83], 0, v[8:9]
	v_and_b32_e32 v0, 0x3f80, v0
	v_lshl_add_u64 v[8:9], v[8:9], 0, v[0:1]
	v_lshl_add_u64 v[12:13], v[8:9], 0, v[168:169]
	ds_read_b128 v[8:11], v15
	v_add_u32_e32 v0, 0x600, v14
	v_bfe_u32 v6, v0, 3, 8
	v_ashrrev_i32_e32 v0, 5, v0
	s_waitcnt lgkmcnt(0)
	global_store_dwordx4 v[12:13], v[8:11], off
	s_nop 1
	v_lshlrev_b32_e32 v9, 1, v0
	v_mul_u32_u24_e32 v8, 0x110, v6
	v_and_b32_e32 v9, 0xffffff80, v9
	v_or_b32_e32 v6, s18, v6
	v_add_u32_e32 v0, s8, v0
	v_add3_u32 v15, v8, v9, v168
	v_lshrrev_b64 v[8:9], 3, v[6:7]
	v_ashrrev_i32_e32 v10, 6, v0
	v_and_b32_e32 v9, 0x3ffff, v9
	v_and_b32_e32 v8, -16, v8
	v_ashrrev_i32_e32 v11, 31, v10
	v_lshl_add_u64 v[8:9], v[8:9], 0, v[10:11]
	v_lshlrev_b64 v[8:9], 14, v[8:9]
	v_lshlrev_b32_e32 v0, 7, v6
	v_lshl_add_u64 v[8:9], s[82:83], 0, v[8:9]
	v_and_b32_e32 v0, 0x3f80, v0
	v_lshl_add_u64 v[8:9], v[8:9], 0, v[0:1]
	v_lshl_add_u64 v[12:13], v[8:9], 0, v[168:169]
	ds_read_b128 v[8:11], v15
	v_add_u32_e32 v0, 0x700, v14
	v_bfe_u32 v6, v0, 3, 8
	v_ashrrev_i32_e32 v0, 5, v0
	s_waitcnt lgkmcnt(0)
	global_store_dwordx4 v[12:13], v[8:11], off
	s_nop 1
	v_lshlrev_b32_e32 v9, 1, v0
	v_mul_u32_u24_e32 v8, 0x110, v6
	v_and_b32_e32 v9, 0xffffff80, v9
	v_or_b32_e32 v6, s18, v6
	v_add_u32_e32 v0, s8, v0
	v_add3_u32 v12, v8, v9, v168
	v_lshrrev_b64 v[8:9], 3, v[6:7]
	v_ashrrev_i32_e32 v10, 6, v0
	v_and_b32_e32 v9, 0x3ffff, v9
	v_and_b32_e32 v8, -16, v8
	v_ashrrev_i32_e32 v11, 31, v10
	v_lshl_add_u64 v[8:9], v[8:9], 0, v[10:11]
	v_lshlrev_b64 v[8:9], 14, v[8:9]
	v_lshlrev_b32_e32 v0, 7, v6
	v_lshl_add_u64 v[8:9], s[82:83], 0, v[8:9]
	v_and_b32_e32 v0, 0x3f80, v0
	v_lshl_add_u64 v[6:7], v[8:9], 0, v[0:1]
	v_lshl_add_u64 v[10:11], v[6:7], 0, v[168:169]
	ds_read_b128 v[6:9], v12
	s_waitcnt lgkmcnt(0)
	global_store_dwordx4 v[10:11], v[6:9], off
	s_cbranch_scc1 .LBB0_234
; #define A256_LOADH(kt_, hf_) { a0 = la.ld1(kt_, (hf_) * 4 + 0, tid); a1 = la.ld1(kt_, (hf_) * 4 + 1, tid); a2 = la.ld1(kt_, (hf_) * 4 + 2, tid); a3 = la.ld1(kt_, (hf_) * 4 + 3, tid); }
; #define ZERO_ACC8(a) { _Pragma("unroll") for (int i_ = 0; i_ < 8; i_++) _Pragma("unroll") for (int r_ = 0; r_ < 16; r_++) a[i_][r_] = 0.f; }
; #define STAGE_SW(scaled_) SW_FOR_TOK(j) { const int tl_ = wn * 128 + j * 32 + l32; const float rs_ = (scaled_) ? s_rs[tl_] : 1.f; \
;     SW_FOR_FEAT(i, rq) { const int c_ = wm * 64 + i * 32 + 8 * rq + 4 * h; \
;       *(uint2*)(smem + tl_ * EPLD + c_) = make_uint2(pk2(SWV(i, j, 4 * rq) * rs_, SWV(i, j, 4 * rq + 1) * rs_), pk2(SWV(i, j, 4 * rq + 2) * rs_, SWV(i, j, 4 * rq + 3) * rs_)); } }
; template <bool swap, class LA>
; DI void gemm256_ws(const LA& la, const bf16_t* Wt, const int KS, const int nk, bf16_t* smem, f32x16 (&acc)[8]) {
;     ...
;   A256_LOADH(0, 0) A256_STH(smem, 0)
;   A256_LOADH(0, 1) A256_STH(smem, 1)
;   W256_LD(0, 0, w00, w10) W256_LD(0, 1, w01, w11) W256_LD(0, 2, w02, w12) W256_LD(0, 3, w03, w13)
;   __syncthreads();
;   const int aoff = (tbk * 128 + l32) * LDT + h * 8;
; DI void ph_ple(const Params& P, int g, int layer, bf16_t* smem) {
;     ...
;     { LoadTile256 la{pb + (size_t)(2 * mt) * 4 * 8192, 4 * 8192}; gemm256_ws<true>(la, We + (size_t)n0 * 256, 16, 4, smem, acc); }
;     STAGE_SW(false)
;     __syncthreads();
;     rows_out_tiled(smem, x2b, (size_t)m0, n0, 16, tid);
;     __syncthreads();
;     ZERO_ACC8(acc)
;     { LoadTile256 la{x1b + (size_t)(2 * mt) * 16 * 8192, 16 * 8192}; gemm256_ws<true>(la, Wg + (size_t)n0 * 1024, 64, 16, smem, acc); }
	s_lshl_b64 s[2:3], s[2:3], 18
	v_mov_b32_e32 v0, v234
	s_barrier
	s_add_u32 s2, s78, s2
	s_addc_u32 s3, s79, s3
	v_lshlrev_b32_e32 v2, 3, v0
	s_lshl_b64 s[10:11], s[8:9], 11
	v_readlane_b32 s12, v253, 49
	v_ashrrev_i32_e32 v3, 31, v2
	v_readlane_b32 s13, v253, 50
	s_add_u32 s12, s12, s10
	v_lshlrev_b64 v[176:177], 1, v[2:3]
	v_add_u32_e32 v6, 0x800, v2
	v_add_u32_e32 v8, 0x1000, v2
	v_add_u32_e32 v2, 0x1800, v2
	s_addc_u32 s13, s13, s11
	v_ashrrev_i32_e32 v7, 31, v6
	v_ashrrev_i32_e32 v9, 31, v8
	v_ashrrev_i32_e32 v3, 31, v2
	v_lshlrev_b64 v[178:179], 1, v[6:7]
	v_lshlrev_b64 v[180:181], 1, v[8:9]
	v_lshlrev_b64 v[182:183], 1, v[2:3]
	s_add_u32 s10, s2, 0x40000
	v_lshl_add_u64 v[4:5], s[2:3], 0, v[176:177]
	v_lshl_add_u64 v[6:7], s[2:3], 0, v[178:179]
	v_lshl_add_u64 v[16:17], s[2:3], 0, v[180:181]
	v_lshl_add_u64 v[2:3], s[2:3], 0, v[182:183]
	s_addc_u32 s11, s3, 0
	v_ashrrev_i32_e32 v40, 6, v0
	global_load_dwordx4 v[8:11], v[4:5], off
	global_load_dwordx4 v[12:15], v[6:7], off
	s_nop 0
	global_load_dwordx4 v[16:19], v[16:17], off
	s_nop 0
	global_load_dwordx4 v[20:23], v[2:3], off
	v_lshl_add_u64 v[2:3], s[10:11], 0, v[176:177]
	v_lshl_add_u64 v[6:7], s[10:11], 0, v[180:181]
	v_lshl_add_u64 v[36:37], s[10:11], 0, v[182:183]
	v_lshlrev_b32_e32 v41, 4, v0
	v_and_b32_e32 v40, -2, v40
	v_lshl_add_u64 v[4:5], s[10:11], 0, v[178:179]
	global_load_dwordx4 v[24:27], v[2:3], off
	global_load_dwordx4 v[28:31], v[4:5], off
	global_load_dwordx4 v[32:35], v[6:7], off
	s_nop 0
	global_load_dwordx4 v[36:39], v[36:37], off
	v_and_b32_e32 v7, 31, v0
	v_lshrrev_b32_e32 v43, 3, v0
	v_lshlrev_b32_e32 v44, 1, v0
	v_lshrrev_b32_e32 v45, 1, v0
	v_and_b32_e32 v0, 0x3f0, v41
	v_and_b32_e32 v42, 0x70, v41
	v_ashrrev_i32_e32 v41, 31, v40
	v_lshlrev_b64 v[40:41], 16, v[40:41]
	v_lshl_add_u64 v[40:41], s[12:13], 0, v[40:41]
	v_lshl_add_u64 v[186:187], v[40:41], 0, v[0:1]
	v_add_co_u32_e32 v40, vcc, s94, v186
	s_movk_i32 s36, 0x80
	s_nop 0
	v_addc_co_u32_e32 v41, vcc, 0, v187, vcc
	global_load_dwordx4 v[154:157], v[40:41], off
	global_load_dwordx4 v[158:161], v[186:187], off
	global_load_dwordx4 v[146:149], v[40:41], off offset:1024
	global_load_dwordx4 v[150:153], v[186:187], off offset:1024
	global_load_dwordx4 v[142:145], v[40:41], off offset:2048
	global_load_dwordx4 v[138:141], v[186:187], off offset:2048
	global_load_dwordx4 v[130:133], v[40:41], off offset:3072
	global_load_dwordx4 v[134:137], v[186:187], off offset:3072
	v_mov_b32_e32 v2, 0
	v_and_or_b32 v7, v44, s36, v7
	v_and_b32_e32 v44, 16, v45
	v_mad_u64_u32 v[184:185], s[36:37], v43, s0, v[42:43]
	s_mov_b64 s[12:13], 0x10000
	s_mov_b32 s9, 0
	v_mov_b32_e32 v3, v2
	v_mov_b32_e32 v4, v2
	v_mov_b32_e32 v5, v2
	v_mov_b32_e32 v6, v2
	v_mad_u32_u24 v169, v7, s0, v44
	v_lshl_add_u64 v[188:189], v[186:187], 0, s[12:13]
	v_mov_b32_e32 v7, v2
	v_mov_b32_e32 v40, v2
	v_mov_b32_e32 v41, v2
	v_mov_b32_e32 v42, v2
	v_mov_b32_e32 v43, v2
	v_mov_b32_e32 v44, v2
	v_mov_b32_e32 v45, v2
	v_mov_b32_e32 v46, v2
	v_mov_b32_e32 v47, v2
	v_mov_b32_e32 v48, v2
	v_mov_b32_e32 v49, v2
	v_mov_b32_e32 v66, v2
	v_mov_b32_e32 v67, v2
	v_mov_b32_e32 v68, v2
	v_mov_b32_e32 v69, v2
	v_mov_b32_e32 v70, v2
	v_mov_b32_e32 v71, v2
	v_mov_b32_e32 v72, v2
	v_mov_b32_e32 v73, v2
	s_waitcnt vmcnt(15)
	ds_write_b128 v184, v[8:11]
	s_waitcnt vmcnt(14)
	ds_write_b128 v184, v[12:15] offset:4608
	s_waitcnt vmcnt(13)
	ds_write_b128 v184, v[16:19] offset:9216
	s_waitcnt vmcnt(12)
	ds_write_b128 v184, v[20:23] offset:13824
	s_waitcnt vmcnt(11)
	ds_write_b128 v184, v[24:27] offset:18432
	s_waitcnt vmcnt(10)
	ds_write_b128 v184, v[28:31] offset:23040
	s_waitcnt vmcnt(9)
	ds_write_b128 v184, v[32:35] offset:27648
	s_waitcnt vmcnt(8)
	ds_write_b128 v184, v[36:39] offset:32256
	v_mov_b32_e32 v8, v2
	v_mov_b32_e32 v9, v2
	v_mov_b32_e32 v10, v2
	v_mov_b32_e32 v11, v2
	v_mov_b32_e32 v12, v2
	v_mov_b32_e32 v13, v2
	v_mov_b32_e32 v14, v2
	v_mov_b32_e32 v15, v2
	v_mov_b32_e32 v16, v2
	v_mov_b32_e32 v17, v2
	v_mov_b32_e32 v34, v2
	v_mov_b32_e32 v35, v2
	v_mov_b32_e32 v36, v2
	v_mov_b32_e32 v37, v2
	v_mov_b32_e32 v38, v2
	v_mov_b32_e32 v39, v2
	v_mov_b32_e32 v74, v2
	v_mov_b32_e32 v75, v2
	v_mov_b32_e32 v76, v2
	v_mov_b32_e32 v77, v2
	v_mov_b32_e32 v78, v2
	v_mov_b32_e32 v79, v2
	v_mov_b32_e32 v80, v2
	v_mov_b32_e32 v81, v2
	v_mov_b32_e32 v98, v2
	v_mov_b32_e32 v99, v2
	v_mov_b32_e32 v100, v2
	v_mov_b32_e32 v101, v2
	v_mov_b32_e32 v102, v2
	v_mov_b32_e32 v103, v2
	v_mov_b32_e32 v104, v2
	v_mov_b32_e32 v105, v2
	v_mov_b32_e32 v106, v2
	v_mov_b32_e32 v107, v2
	v_mov_b32_e32 v108, v2
	v_mov_b32_e32 v109, v2
	v_mov_b32_e32 v110, v2
	v_mov_b32_e32 v111, v2
	v_mov_b32_e32 v112, v2
	v_mov_b32_e32 v113, v2
	v_mov_b32_e32 v18, v2
	v_mov_b32_e32 v19, v2
	v_mov_b32_e32 v20, v2
	v_mov_b32_e32 v21, v2
	v_mov_b32_e32 v22, v2
	v_mov_b32_e32 v23, v2
	v_mov_b32_e32 v24, v2
	v_mov_b32_e32 v25, v2
	v_mov_b32_e32 v26, v2
	v_mov_b32_e32 v27, v2
	v_mov_b32_e32 v28, v2
	v_mov_b32_e32 v29, v2
	v_mov_b32_e32 v30, v2
	v_mov_b32_e32 v31, v2
	v_mov_b32_e32 v32, v2
	v_mov_b32_e32 v33, v2
	v_mov_b32_e32 v50, v2
	v_mov_b32_e32 v51, v2
	v_mov_b32_e32 v52, v2
	v_mov_b32_e32 v53, v2
	v_mov_b32_e32 v54, v2
	v_mov_b32_e32 v55, v2
	v_mov_b32_e32 v56, v2
	v_mov_b32_e32 v57, v2
	v_mov_b32_e32 v58, v2
	v_mov_b32_e32 v59, v2
	v_mov_b32_e32 v60, v2
	v_mov_b32_e32 v61, v2
	v_mov_b32_e32 v62, v2
	v_mov_b32_e32 v63, v2
	v_mov_b32_e32 v64, v2
	v_mov_b32_e32 v65, v2
	v_mov_b32_e32 v82, v2
	v_mov_b32_e32 v83, v2
	v_mov_b32_e32 v84, v2
	v_mov_b32_e32 v85, v2
	v_mov_b32_e32 v86, v2
	v_mov_b32_e32 v87, v2
	v_mov_b32_e32 v88, v2
	v_mov_b32_e32 v89, v2
	v_mov_b32_e32 v90, v2
	v_mov_b32_e32 v91, v2
	v_mov_b32_e32 v92, v2
	v_mov_b32_e32 v93, v2
	v_mov_b32_e32 v94, v2
	v_mov_b32_e32 v95, v2
	v_mov_b32_e32 v96, v2
	v_mov_b32_e32 v97, v2
	v_mov_b32_e32 v114, v2
	v_mov_b32_e32 v115, v2
	v_mov_b32_e32 v116, v2
	v_mov_b32_e32 v117, v2
	v_mov_b32_e32 v118, v2
	v_mov_b32_e32 v119, v2
	v_mov_b32_e32 v120, v2
	v_mov_b32_e32 v121, v2
	v_mov_b32_e32 v122, v2
	v_mov_b32_e32 v123, v2
	v_mov_b32_e32 v124, v2
	v_mov_b32_e32 v125, v2
	v_mov_b32_e32 v126, v2
	v_mov_b32_e32 v127, v2
	v_mov_b32_e32 v128, v2
	v_mov_b32_e32 v129, v2
	s_waitcnt lgkmcnt(0)
	s_barrier
; #define A256_LOADH(kt_, hf_) { a0 = la.ld1(kt_, (hf_) * 4 + 0, tid); a1 = la.ld1(kt_, (hf_) * 4 + 1, tid); a2 = la.ld1(kt_, (hf_) * 4 + 2, tid); a3 = la.ld1(kt_, (hf_) * 4 + 3, tid); }
; template <bool swap, class LA>
; DI void gemm256_ws(const LA& la, const bf16_t* Wt, const int KS, const int nk, bf16_t* smem, f32x16 (&acc)[8]) {
;     ...
;   for (int kt = 0; kt < nk; kt++) {
;     const int cur = kt & 1; const int kn = (kt + 1 < nk) ? kt + 1 : last;
;     const bf16_t* sp = smem + cur * ATILE_E + aoff;
;     bf16_t* nxt = smem + (cur ^ 1) * ATILE_E;
;     A256_LOADH(kn, 0)
;     MMA256(0, w00, w10) W256_LD(kn, 0, w00, w10)
;     MMA256(1, w01, w11) W256_LD(kn, 1, w01, w11)
;     A256_STH(nxt, 0)
;     A256_LOADH(kn, 1)
;     MMA256(2, w02, w12) W256_LD(kn, 2, w02, w12)
;     MMA256(3, w03, w13) W256_LD(kn, 3, w03, w13)
;     A256_STH(nxt, 1)
;     __syncthreads();
	s_lshl_b32 s37, 1, 14
	s_add_u32 s12, s2, s37
	s_addc_u32 s13, s3, 0
	v_lshl_add_u64 v[206:207], s[12:13], 0, v[176:177]
	s_add_u32 s12, s12, 0x1000
	s_addc_u32 s13, s13, 0
	v_lshl_add_u64 v[210:211], s[12:13], 0, v[176:177]
	s_add_u32 s12, s12, 0x1000
	s_addc_u32 s13, s13, 0
	v_lshl_add_u64 v[216:217], s[12:13], 0, v[176:177]
	s_add_u32 s12, s12, 0x1000
	s_addc_u32 s13, s13, 0
	v_lshl_add_u64 v[220:221], s[12:13], 0, v[176:177]
	global_load_dwordx4 v[206:209], v[206:207], off
	global_load_dwordx4 v[210:213], v[210:211], off
	global_load_dwordx4 v[216:219], v[216:217], off
	global_load_dwordx4 v[220:223], v[220:221], off
	s_add_u32 s12, s10, s37
	s_addc_u32 s13, s11, 0
	v_lshl_add_u64 v[224:225], s[12:13], 0, v[176:177]
	s_add_u32 s12, s12, 0x1000
	s_addc_u32 s13, s13, 0
	v_lshl_add_u64 v[228:229], s[12:13], 0, v[176:177]
	s_add_u32 s12, s12, 0x1000
	s_addc_u32 s13, s13, 0
	v_lshl_add_u64 v[246:247], s[12:13], 0, v[176:177]
	s_add_u32 s12, s12, 0x1000
	s_addc_u32 s13, s13, 0
	v_lshl_add_u64 v[178:179], s[12:13], 0, v[176:177]
	global_load_dwordx4 v[224:227], v[224:225], off
	global_load_dwordx4 v[228:231], v[228:229], off
	global_load_dwordx4 v[246:249], v[246:247], off
	global_load_dwordx4 v[178:181], v[178:179], off
.LBB0_236:
	s_and_b32 s12, s9, 1
	s_mul_i32 s13, s12, 0x9000
	v_add_u32_e32 v0, s13, v169
	ds_read_b128 v[194:197], v0
	ds_read_b128 v[198:201], v0 offset:4608
	ds_read_b128 v[202:205], v0 offset:9216
	s_add_i32 s9, s9, 1
	s_min_u32 s36, s9, 15
	s_xor_b32 s12, s12, 1
	s_mul_i32 s13, s12, 0x9000
	v_add_u32_e32 v185, s13, v184
	s_lshl_b32 s90, s36, 12
	s_add_i32 s36, s9, 1
	s_min_u32 s36, s36, 15
	s_lshl_b32 s37, s36, 14
	s_waitcnt vmcnt(14) lgkmcnt(2)
	v_mfma_f32_32x32x16_bf16 v[98:113], v[154:157], v[194:197], v[98:113]
	v_mfma_f32_32x32x16_bf16 v[114:129], v[158:161], v[194:197], v[114:129]
	ds_read_b128 v[194:197], v0 offset:13824
	s_waitcnt lgkmcnt(2)
	v_mfma_f32_32x32x16_bf16 v[66:81], v[154:157], v[198:201], v[66:81]
	v_mfma_f32_32x32x16_bf16 v[82:97], v[158:161], v[198:201], v[82:97]
	ds_read_b128 v[198:201], v0 offset:32
	s_waitcnt lgkmcnt(2)
	v_mfma_f32_32x32x16_bf16 v[34:49], v[154:157], v[202:205], v[34:49]
	v_mfma_f32_32x32x16_bf16 v[50:65], v[158:161], v[202:205], v[50:65]
	ds_read_b128 v[202:205], v0 offset:4640
	s_waitcnt lgkmcnt(2)
	v_mfma_f32_32x32x16_bf16 v[2:17], v[154:157], v[194:197], v[2:17]
	v_mfma_f32_32x32x16_bf16 v[18:33], v[158:161], v[194:197], v[18:33]
	ds_read_b128 v[194:197], v0 offset:9248
	v_lshl_add_u64 v[154:155], v[188:189], 0, s[90:91]
	global_load_dwordx4 v[154:157], v[154:155], off
	v_lshl_add_u64 v[158:159], v[186:187], 0, s[90:91]
	global_load_dwordx4 v[158:161], v[158:159], off
	s_waitcnt vmcnt(14) lgkmcnt(2)
	v_mfma_f32_32x32x16_bf16 v[98:113], v[146:149], v[198:201], v[98:113]
	v_mfma_f32_32x32x16_bf16 v[114:129], v[150:153], v[198:201], v[114:129]
	ds_read_b128 v[198:201], v0 offset:13856
	s_waitcnt lgkmcnt(2)
	v_mfma_f32_32x32x16_bf16 v[66:81], v[146:149], v[202:205], v[66:81]
	v_mfma_f32_32x32x16_bf16 v[82:97], v[150:153], v[202:205], v[82:97]
	ds_read_b128 v[202:205], v0 offset:64
	s_waitcnt lgkmcnt(2)
	v_mfma_f32_32x32x16_bf16 v[34:49], v[146:149], v[194:197], v[34:49]
	v_mfma_f32_32x32x16_bf16 v[50:65], v[150:153], v[194:197], v[50:65]
	ds_read_b128 v[194:197], v0 offset:4672
	s_waitcnt lgkmcnt(2)
	v_mfma_f32_32x32x16_bf16 v[2:17], v[146:149], v[198:201], v[2:17]
	v_mfma_f32_32x32x16_bf16 v[18:33], v[150:153], v[198:201], v[18:33]
	ds_read_b128 v[198:201], v0 offset:9280
	v_lshl_add_u64 v[146:147], v[188:189], 0, s[90:91]
	global_load_dwordx4 v[146:149], v[146:147], off offset:1024
	v_lshl_add_u64 v[150:151], v[186:187], 0, s[90:91]
	global_load_dwordx4 v[150:153], v[150:151], off offset:1024
	s_waitcnt vmcnt(8)
	ds_write_b128 v185, v[206:209]
	ds_write_b128 v185, v[210:213] offset:4608
	ds_write_b128 v185, v[216:219] offset:9216
	ds_write_b128 v185, v[220:223] offset:13824
	s_add_u32 s12, s2, s37
	s_addc_u32 s13, s3, 0
	v_lshl_add_u64 v[206:207], s[12:13], 0, v[176:177]
	s_add_u32 s12, s12, 0x1000
	s_addc_u32 s13, s13, 0
	v_lshl_add_u64 v[210:211], s[12:13], 0, v[176:177]
	s_add_u32 s12, s12, 0x1000
	s_addc_u32 s13, s13, 0
	v_lshl_add_u64 v[216:217], s[12:13], 0, v[176:177]
	s_add_u32 s12, s12, 0x1000
	s_addc_u32 s13, s13, 0
	v_lshl_add_u64 v[220:221], s[12:13], 0, v[176:177]
	global_load_dwordx4 v[206:209], v[206:207], off
	global_load_dwordx4 v[210:213], v[210:211], off
	global_load_dwordx4 v[216:219], v[216:217], off
	global_load_dwordx4 v[220:223], v[220:221], off
	s_waitcnt lgkmcnt(6)
	v_mfma_f32_32x32x16_bf16 v[98:113], v[142:145], v[202:205], v[98:113]
	v_mfma_f32_32x32x16_bf16 v[114:129], v[138:141], v[202:205], v[114:129]
	ds_read_b128 v[202:205], v0 offset:13888
	s_waitcnt lgkmcnt(6)
	v_mfma_f32_32x32x16_bf16 v[66:81], v[142:145], v[194:197], v[66:81]
	v_mfma_f32_32x32x16_bf16 v[82:97], v[138:141], v[194:197], v[82:97]
	ds_read_b128 v[194:197], v0 offset:96
	s_waitcnt lgkmcnt(6)
	v_mfma_f32_32x32x16_bf16 v[34:49], v[142:145], v[198:201], v[34:49]
	v_mfma_f32_32x32x16_bf16 v[50:65], v[138:141], v[198:201], v[50:65]
	ds_read_b128 v[198:201], v0 offset:4704
	s_waitcnt lgkmcnt(2)
	v_mfma_f32_32x32x16_bf16 v[2:17], v[142:145], v[202:205], v[2:17]
	v_mfma_f32_32x32x16_bf16 v[18:33], v[138:141], v[202:205], v[18:33]
	ds_read_b128 v[202:205], v0 offset:9312
	v_lshl_add_u64 v[142:143], v[188:189], 0, s[90:91]
	global_load_dwordx4 v[142:145], v[142:143], off offset:2048
	v_lshl_add_u64 v[138:139], v[186:187], 0, s[90:91]
	global_load_dwordx4 v[138:141], v[138:139], off offset:2048
	s_waitcnt lgkmcnt(2)
; DI unsigned pk2(float a, float b) { f32v2 v = {a, b}; return __builtin_bit_cast(unsigned, __builtin_convertvector(v, bf16v2)); }
; DI float sigmoidf_(float v) { return 1.f / (1.f + __expf(-v)); }
; #define A256_LOADH(kt_, hf_) { a0 = la.ld1(kt_, (hf_) * 4 + 0, tid); a1 = la.ld1(kt_, (hf_) * 4 + 1, tid); a2 = la.ld1(kt_, (hf_) * 4 + 2, tid); a3 = la.ld1(kt_, (hf_) * 4 + 3, tid); }
; #define SW_FOR_TOK(j) _Pragma("unroll") for (int j = 0; j < 4; j++)
; #define SW_FOR_FEAT(i, rq) _Pragma("unroll") for (int i = 0; i < 2; i++) _Pragma("unroll") for (int rq = 0; rq < 4; rq++)
; template <bool swap, class LA>
; DI void gemm256_ws(const LA& la, const bf16_t* Wt, const int KS, const int nk, bf16_t* smem, f32x16 (&acc)[8]) {
;     ...
;   for (int kt = 0; kt < nk; kt++) {
;     const int cur = kt & 1; const int kn = (kt + 1 < nk) ? kt + 1 : last;
;     const bf16_t* sp = smem + cur * ATILE_E + aoff;
;     bf16_t* nxt = smem + (cur ^ 1) * ATILE_E;
;     A256_LOADH(kn, 0)
;     MMA256(0, w00, w10) W256_LD(kn, 0, w00, w10)
;     MMA256(1, w01, w11) W256_LD(kn, 1, w01, w11)
;     A256_STH(nxt, 0)
;     A256_LOADH(kn, 1)
;     MMA256(2, w02, w12) W256_LD(kn, 2, w02, w12)
;     MMA256(3, w03, w13) W256_LD(kn, 3, w03, w13)
;     A256_STH(nxt, 1)
;     __syncthreads();
; DI void ph_ple(const Params& P, int g, int layer, bf16_t* smem) {
;     ...
;     SW_FOR_TOK(j) { const int tl_ = wn * 128 + j * 32 + l32;
;       SW_FOR_FEAT(i, rq) { const int c_ = wm * 64 + i * 32 + 8 * rq + 4 * h;
;         *(uint2*)(smem + tl_ * EPLD + c_) = make_uint2(pk2(sigmoidf_(SWV(i, j, 4 * rq)), sigmoidf_(SWV(i, j, 4 * rq + 1))), pk2(sigmoidf_(SWV(i, j, 4 * rq + 2)), sigmoidf_(SWV(i, j, 4 * rq + 3)))); } }
	v_mfma_f32_32x32x16_bf16 v[98:113], v[130:133], v[194:197], v[98:113]
	v_mfma_f32_32x32x16_bf16 v[114:129], v[134:137], v[194:197], v[114:129]
	ds_read_b128 v[194:197], v0 offset:13920
	s_waitcnt lgkmcnt(2)
	v_mfma_f32_32x32x16_bf16 v[66:81], v[130:133], v[198:201], v[66:81]
	v_mfma_f32_32x32x16_bf16 v[82:97], v[134:137], v[198:201], v[82:97]
	s_waitcnt lgkmcnt(1)
	v_mfma_f32_32x32x16_bf16 v[34:49], v[130:133], v[202:205], v[34:49]
	v_mfma_f32_32x32x16_bf16 v[50:65], v[134:137], v[202:205], v[50:65]
	s_waitcnt lgkmcnt(0)
	v_mfma_f32_32x32x16_bf16 v[2:17], v[130:133], v[194:197], v[2:17]
	v_mfma_f32_32x32x16_bf16 v[18:33], v[134:137], v[194:197], v[18:33]
	v_lshl_add_u64 v[130:131], v[188:189], 0, s[90:91]
	global_load_dwordx4 v[130:133], v[130:131], off offset:3072
	v_lshl_add_u64 v[134:135], v[186:187], 0, s[90:91]
	global_load_dwordx4 v[134:137], v[134:135], off offset:3072
	s_waitcnt vmcnt(12)
	ds_write_b128 v185, v[224:227] offset:18432
	ds_write_b128 v185, v[228:231] offset:23040
	ds_write_b128 v185, v[246:249] offset:27648
	ds_write_b128 v185, v[178:181] offset:32256
	s_add_u32 s12, s10, s37
	s_addc_u32 s13, s11, 0
	v_lshl_add_u64 v[224:225], s[12:13], 0, v[176:177]
	s_add_u32 s12, s12, 0x1000
	s_addc_u32 s13, s13, 0
	v_lshl_add_u64 v[228:229], s[12:13], 0, v[176:177]
	s_add_u32 s12, s12, 0x1000
	s_addc_u32 s13, s13, 0
	v_lshl_add_u64 v[246:247], s[12:13], 0, v[176:177]
	s_add_u32 s12, s12, 0x1000
	s_addc_u32 s13, s13, 0
	v_lshl_add_u64 v[178:179], s[12:13], 0, v[176:177]
	global_load_dwordx4 v[224:227], v[224:225], off
	global_load_dwordx4 v[228:231], v[228:229], off
	global_load_dwordx4 v[246:249], v[246:247], off
	global_load_dwordx4 v[178:181], v[178:179], off
	s_cmp_lg_u32 s9, 16
	s_waitcnt lgkmcnt(0)
	s_barrier
	s_cbranch_scc1 .LBB0_236
	s_waitcnt vmcnt(0)
	v_mul_f32_e32 v0, 0xbfb8aa3b, v114
	v_exp_f32_e32 v114, v0
	v_mul_f32_e32 v0, 0xbfb8aa3b, v115
	v_exp_f32_e32 v115, v0
	v_readlane_b32 s10, v253, 45
	v_readlane_b32 s11, v253, 46
	s_mov_b32 s9, 0
	v_pk_add_f32 v[114:115], v[114:115], 1.0 op_sel_hi:[1,0]
	s_nop 0
	v_div_scale_f32 v0, s[2:3], v115, v115, 1.0
	s_waitcnt vmcnt(0)
	v_rcp_f32_e32 v130, v0
	s_nop 0
	v_fma_f32 v131, -v0, v130, 1.0
	v_fmac_f32_e32 v130, v131, v130
	v_div_scale_f32 v131, vcc, 1.0, v115, 1.0
	v_mul_f32_e32 v132, v131, v130
	v_fma_f32 v133, -v0, v132, v131
	v_fmac_f32_e32 v132, v133, v130
	v_fma_f32 v0, -v0, v132, v131
	v_div_fmas_f32 v0, v0, v130, v132
	v_div_fixup_f32 v0, v0, v115, 1.0
	v_div_scale_f32 v115, s[2:3], v114, v114, 1.0
	v_rcp_f32_e32 v130, v115
	s_nop 0
	v_fma_f32 v131, -v115, v130, 1.0
	v_fmac_f32_e32 v130, v131, v130
	v_div_scale_f32 v131, vcc, 1.0, v114, 1.0
	v_mul_f32_e32 v132, v131, v130
	v_fma_f32 v133, -v115, v132, v131
	v_fmac_f32_e32 v132, v133, v130
	v_fma_f32 v115, -v115, v132, v131
	v_div_fmas_f32 v115, v115, v130, v132
	v_div_fixup_f32 v114, v115, v114, 1.0
	v_cvt_pk_bf16_f32 v114, v114, v0
	v_mul_f32_e32 v0, 0xbfb8aa3b, v116
	v_exp_f32_e32 v116, v0
	v_mul_f32_e32 v0, 0xbfb8aa3b, v117
	v_exp_f32_e32 v117, v0
	s_nop 0
	v_pk_add_f32 v[116:117], v[116:117], 1.0 op_sel_hi:[1,0]
	s_nop 0
	v_div_scale_f32 v0, s[2:3], v117, v117, 1.0
	v_rcp_f32_e32 v115, v0
	s_nop 0
	v_fma_f32 v130, -v0, v115, 1.0
	v_fmac_f32_e32 v115, v130, v115
	v_div_scale_f32 v130, vcc, 1.0, v117, 1.0
	v_mul_f32_e32 v131, v130, v115
	v_fma_f32 v132, -v0, v131, v130
	v_fmac_f32_e32 v131, v132, v115
	v_fma_f32 v0, -v0, v131, v130
	v_div_fmas_f32 v0, v0, v115, v131
	v_div_scale_f32 v115, s[2:3], v116, v116, 1.0
	v_div_fixup_f32 v0, v0, v117, 1.0
	v_rcp_f32_e32 v117, v115
	s_nop 0
	v_fma_f32 v130, -v115, v117, 1.0
	v_fmac_f32_e32 v117, v130, v117
	v_div_scale_f32 v130, vcc, 1.0, v116, 1.0
	v_mul_f32_e32 v131, v130, v117
	v_fma_f32 v132, -v115, v131, v130
	v_fmac_f32_e32 v131, v132, v117
	v_fma_f32 v115, -v115, v131, v130
	v_div_fmas_f32 v115, v115, v117, v131
	v_div_fixup_f32 v115, v115, v116, 1.0
	v_cvt_pk_bf16_f32 v115, v115, v0
	v_mul_f32_e32 v0, 0xbfb8aa3b, v118
	v_exp_f32_e32 v116, v0
	v_mul_f32_e32 v0, 0xbfb8aa3b, v119
	v_exp_f32_e32 v117, v0
	s_nop 0
	v_pk_add_f32 v[116:117], v[116:117], 1.0 op_sel_hi:[1,0]
	s_nop 0
	v_div_scale_f32 v0, s[2:3], v117, v117, 1.0
	v_rcp_f32_e32 v118, v0
	s_nop 0
	v_fma_f32 v119, -v0, v118, 1.0
	v_fmac_f32_e32 v118, v119, v118
	v_div_scale_f32 v119, vcc, 1.0, v117, 1.0
	v_mul_f32_e32 v130, v119, v118
	v_fma_f32 v131, -v0, v130, v119
	v_fmac_f32_e32 v130, v131, v118
	v_fma_f32 v0, -v0, v130, v119
	v_div_fmas_f32 v0, v0, v118, v130
	v_div_fixup_f32 v0, v0, v117, 1.0
	v_div_scale_f32 v117, s[2:3], v116, v116, 1.0
	v_rcp_f32_e32 v118, v117
	s_nop 0
	v_fma_f32 v119, -v117, v118, 1.0
	v_fmac_f32_e32 v118, v119, v118
	v_div_scale_f32 v119, vcc, 1.0, v116, 1.0
	v_mul_f32_e32 v130, v119, v118
	v_fma_f32 v131, -v117, v130, v119
	v_fmac_f32_e32 v130, v131, v118
	v_fma_f32 v117, -v117, v130, v119
	v_div_fmas_f32 v117, v117, v118, v130
	v_div_fixup_f32 v116, v117, v116, 1.0
	v_cvt_pk_bf16_f32 v116, v116, v0
	v_mul_f32_e32 v0, 0xbfb8aa3b, v120
	v_exp_f32_e32 v118, v0
	v_mul_f32_e32 v0, 0xbfb8aa3b, v121
	v_exp_f32_e32 v119, v0
	s_nop 0
	v_pk_add_f32 v[118:119], v[118:119], 1.0 op_sel_hi:[1,0]
	s_nop 0
	v_div_scale_f32 v0, s[2:3], v119, v119, 1.0
	v_rcp_f32_e32 v117, v0
	s_nop 0
	v_fma_f32 v120, -v0, v117, 1.0
	v_fmac_f32_e32 v117, v120, v117
	v_div_scale_f32 v120, vcc, 1.0, v119, 1.0
	v_mul_f32_e32 v121, v120, v117
	v_fma_f32 v130, -v0, v121, v120
	v_fmac_f32_e32 v121, v130, v117
	v_fma_f32 v0, -v0, v121, v120
	v_div_fmas_f32 v0, v0, v117, v121
	v_div_scale_f32 v117, s[2:3], v118, v118, 1.0
	v_div_fixup_f32 v0, v0, v119, 1.0
	v_rcp_f32_e32 v119, v117
	s_nop 0
	v_fma_f32 v120, -v117, v119, 1.0
; DI unsigned pk2(float a, float b) { f32v2 v = {a, b}; return __builtin_bit_cast(unsigned, __builtin_convertvector(v, bf16v2)); }
; DI float sigmoidf_(float v) { return 1.f / (1.f + __expf(-v)); }
; #define SW_FOR_TOK(j) _Pragma("unroll") for (int j = 0; j < 4; j++)
; #define SW_FOR_FEAT(i, rq) _Pragma("unroll") for (int i = 0; i < 2; i++) _Pragma("unroll") for (int rq = 0; rq < 4; rq++)
; DI void ph_ple(const Params& P, int g, int layer, bf16_t* smem) {
;     ...
;     SW_FOR_TOK(j) { const int tl_ = wn * 128 + j * 32 + l32;
;       SW_FOR_FEAT(i, rq) { const int c_ = wm * 64 + i * 32 + 8 * rq + 4 * h;
;         *(uint2*)(smem + tl_ * EPLD + c_) = make_uint2(pk2(sigmoidf_(SWV(i, j, 4 * rq)), sigmoidf_(SWV(i, j, 4 * rq + 1))), pk2(sigmoidf_(SWV(i, j, 4 * rq + 2)), sigmoidf_(SWV(i, j, 4 * rq + 3)))); } }
	v_fmac_f32_e32 v119, v120, v119
	v_div_scale_f32 v120, vcc, 1.0, v118, 1.0
	v_mul_f32_e32 v121, v120, v119
	v_fma_f32 v130, -v117, v121, v120
	v_fmac_f32_e32 v121, v130, v119
	v_fma_f32 v117, -v117, v121, v120
	v_div_fmas_f32 v117, v117, v119, v121
	v_div_fixup_f32 v117, v117, v118, 1.0
	v_cvt_pk_bf16_f32 v117, v117, v0
	v_mul_f32_e32 v0, 0xbfb8aa3b, v122
	ds_write2_b64 v165, v[114:115], v[116:117] offset1:2
	v_exp_f32_e32 v114, v0
	v_mul_f32_e32 v0, 0xbfb8aa3b, v123
	v_exp_f32_e32 v115, v0
	s_nop 0
	v_pk_add_f32 v[114:115], v[114:115], 1.0 op_sel_hi:[1,0]
	s_nop 0
	v_div_scale_f32 v0, s[2:3], v115, v115, 1.0
	v_rcp_f32_e32 v116, v0
	s_nop 0
	v_fma_f32 v117, -v0, v116, 1.0
	v_fmac_f32_e32 v116, v117, v116
	v_div_scale_f32 v117, vcc, 1.0, v115, 1.0
	v_mul_f32_e32 v118, v117, v116
	v_fma_f32 v119, -v0, v118, v117
	v_fmac_f32_e32 v118, v119, v116
	v_fma_f32 v0, -v0, v118, v117
	v_div_fmas_f32 v0, v0, v116, v118
	v_div_fixup_f32 v0, v0, v115, 1.0
	v_div_scale_f32 v115, s[2:3], v114, v114, 1.0
	v_rcp_f32_e32 v116, v115
	s_nop 0
	v_fma_f32 v117, -v115, v116, 1.0
	v_fmac_f32_e32 v116, v117, v116
	v_div_scale_f32 v117, vcc, 1.0, v114, 1.0
	v_mul_f32_e32 v118, v117, v116
	v_fma_f32 v119, -v115, v118, v117
	v_fmac_f32_e32 v118, v119, v116
	v_fma_f32 v115, -v115, v118, v117
	v_div_fmas_f32 v115, v115, v116, v118
	v_div_fixup_f32 v114, v115, v114, 1.0
	v_cvt_pk_bf16_f32 v114, v114, v0
	v_mul_f32_e32 v0, 0xbfb8aa3b, v124
	v_exp_f32_e32 v116, v0
	v_mul_f32_e32 v0, 0xbfb8aa3b, v125
	v_exp_f32_e32 v117, v0
	s_nop 0
	v_pk_add_f32 v[116:117], v[116:117], 1.0 op_sel_hi:[1,0]
	s_nop 0
	v_div_scale_f32 v0, s[2:3], v117, v117, 1.0
	v_rcp_f32_e32 v115, v0
	s_nop 0
	v_fma_f32 v118, -v0, v115, 1.0
	v_fmac_f32_e32 v115, v118, v115
	v_div_scale_f32 v118, vcc, 1.0, v117, 1.0
	v_mul_f32_e32 v119, v118, v115
	v_fma_f32 v120, -v0, v119, v118
	v_fmac_f32_e32 v119, v120, v115
	v_fma_f32 v0, -v0, v119, v118
	v_div_fmas_f32 v0, v0, v115, v119
	v_div_scale_f32 v115, s[2:3], v116, v116, 1.0
	v_div_fixup_f32 v0, v0, v117, 1.0
	v_rcp_f32_e32 v117, v115
	s_nop 0
	v_fma_f32 v118, -v115, v117, 1.0
	v_fmac_f32_e32 v117, v118, v117
	v_div_scale_f32 v118, vcc, 1.0, v116, 1.0
	v_mul_f32_e32 v119, v118, v117
	v_fma_f32 v120, -v115, v119, v118
	v_fmac_f32_e32 v119, v120, v117
	v_fma_f32 v115, -v115, v119, v118
	v_div_fmas_f32 v115, v115, v117, v119
	v_div_fixup_f32 v115, v115, v116, 1.0
	v_cvt_pk_bf16_f32 v115, v115, v0
	v_mul_f32_e32 v0, 0xbfb8aa3b, v126
	v_exp_f32_e32 v116, v0
	v_mul_f32_e32 v0, 0xbfb8aa3b, v127
	v_exp_f32_e32 v117, v0
	s_nop 0
	v_pk_add_f32 v[116:117], v[116:117], 1.0 op_sel_hi:[1,0]
	s_nop 0
	v_div_scale_f32 v0, s[2:3], v117, v117, 1.0
	v_rcp_f32_e32 v118, v0
	s_nop 0
	v_fma_f32 v119, -v0, v118, 1.0
	v_fmac_f32_e32 v118, v119, v118
	v_div_scale_f32 v119, vcc, 1.0, v117, 1.0
	v_mul_f32_e32 v120, v119, v118
	v_fma_f32 v121, -v0, v120, v119
	v_fmac_f32_e32 v120, v121, v118
	v_fma_f32 v0, -v0, v120, v119
	v_div_fmas_f32 v0, v0, v118, v120
	v_div_fixup_f32 v0, v0, v117, 1.0
	v_div_scale_f32 v117, s[2:3], v116, v116, 1.0
	v_rcp_f32_e32 v118, v117
	s_nop 0
	v_fma_f32 v119, -v117, v118, 1.0
	v_fmac_f32_e32 v118, v119, v118
	v_div_scale_f32 v119, vcc, 1.0, v116, 1.0
	v_mul_f32_e32 v120, v119, v118
	v_fma_f32 v121, -v117, v120, v119
	v_fmac_f32_e32 v120, v121, v118
	v_fma_f32 v117, -v117, v120, v119
	v_div_fmas_f32 v117, v117, v118, v120
	v_div_fixup_f32 v116, v117, v116, 1.0
	v_cvt_pk_bf16_f32 v116, v116, v0
	v_mul_f32_e32 v0, 0xbfb8aa3b, v128
	v_exp_f32_e32 v118, v0
	v_mul_f32_e32 v0, 0xbfb8aa3b, v129
	v_exp_f32_e32 v119, v0
	s_nop 0
	v_pk_add_f32 v[118:119], v[118:119], 1.0 op_sel_hi:[1,0]
	s_nop 0
	v_div_scale_f32 v0, s[2:3], v119, v119, 1.0
	v_rcp_f32_e32 v117, v0
	s_nop 0
	v_fma_f32 v120, -v0, v117, 1.0
	v_fmac_f32_e32 v117, v120, v117
	v_div_scale_f32 v120, vcc, 1.0, v119, 1.0
	v_mul_f32_e32 v121, v120, v117
	v_fma_f32 v122, -v0, v121, v120
	v_fmac_f32_e32 v121, v122, v117
	v_fma_f32 v0, -v0, v121, v120
	v_div_fmas_f32 v0, v0, v117, v121
	v_div_scale_f32 v117, s[2:3], v118, v118, 1.0
	v_div_fixup_f32 v0, v0, v119, 1.0
	v_rcp_f32_e32 v119, v117
	s_nop 0
	v_fma_f32 v120, -v117, v119, 1.0
	v_fmac_f32_e32 v119, v120, v119
	v_div_scale_f32 v120, vcc, 1.0, v118, 1.0
	v_mul_f32_e32 v121, v120, v119
	v_fma_f32 v122, -v117, v121, v120
	v_fmac_f32_e32 v121, v122, v119
	v_fma_f32 v117, -v117, v121, v120
	v_div_fmas_f32 v117, v117, v119, v121
	v_div_fixup_f32 v117, v117, v118, 1.0
	v_cvt_pk_bf16_f32 v117, v117, v0
	v_mul_f32_e32 v0, 0xbfb8aa3b, v98
	v_exp_f32_e32 v98, v0
	v_mul_f32_e32 v0, 0xbfb8aa3b, v99
	v_exp_f32_e32 v99, v0
	ds_write2_b64 v165, v[114:115], v[116:117] offset0:4 offset1:6
	v_pk_add_f32 v[98:99], v[98:99], 1.0 op_sel_hi:[1,0]
	s_nop 0
	v_div_scale_f32 v0, s[2:3], v99, v99, 1.0
	v_rcp_f32_e32 v114, v0
	s_nop 0
	v_fma_f32 v115, -v0, v114, 1.0
	v_fmac_f32_e32 v114, v115, v114
	v_div_scale_f32 v115, vcc, 1.0, v99, 1.0
	v_mul_f32_e32 v116, v115, v114
	v_fma_f32 v117, -v0, v116, v115
	v_fmac_f32_e32 v116, v117, v114
	v_fma_f32 v0, -v0, v116, v115
	v_div_fmas_f32 v0, v0, v114, v116
	v_div_fixup_f32 v0, v0, v99, 1.0
	v_div_scale_f32 v99, s[2:3], v98, v98, 1.0
	v_rcp_f32_e32 v114, v99
	s_nop 0
	v_fma_f32 v115, -v99, v114, 1.0
	v_fmac_f32_e32 v114, v115, v114
	v_div_scale_f32 v115, vcc, 1.0, v98, 1.0
	v_mul_f32_e32 v116, v115, v114
	v_fma_f32 v117, -v99, v116, v115
	v_fmac_f32_e32 v116, v117, v114
	v_fma_f32 v99, -v99, v116, v115
	v_div_fmas_f32 v99, v99, v114, v116
	v_div_fixup_f32 v98, v99, v98, 1.0
	v_cvt_pk_bf16_f32 v98, v98, v0
	v_mul_f32_e32 v0, 0xbfb8aa3b, v100
	v_exp_f32_e32 v100, v0
	v_mul_f32_e32 v0, 0xbfb8aa3b, v101
	v_exp_f32_e32 v101, v0
	s_nop 0
; DI unsigned pk2(float a, float b) { f32v2 v = {a, b}; return __builtin_bit_cast(unsigned, __builtin_convertvector(v, bf16v2)); }
; DI float sigmoidf_(float v) { return 1.f / (1.f + __expf(-v)); }
; #define SW_FOR_TOK(j) _Pragma("unroll") for (int j = 0; j < 4; j++)
; #define SW_FOR_FEAT(i, rq) _Pragma("unroll") for (int i = 0; i < 2; i++) _Pragma("unroll") for (int rq = 0; rq < 4; rq++)
; DI void ph_ple(const Params& P, int g, int layer, bf16_t* smem) {
;     ...
;     SW_FOR_TOK(j) { const int tl_ = wn * 128 + j * 32 + l32;
;       SW_FOR_FEAT(i, rq) { const int c_ = wm * 64 + i * 32 + 8 * rq + 4 * h;
;         *(uint2*)(smem + tl_ * EPLD + c_) = make_uint2(pk2(sigmoidf_(SWV(i, j, 4 * rq)), sigmoidf_(SWV(i, j, 4 * rq + 1))), pk2(sigmoidf_(SWV(i, j, 4 * rq + 2)), sigmoidf_(SWV(i, j, 4 * rq + 3)))); } }
	v_pk_add_f32 v[100:101], v[100:101], 1.0 op_sel_hi:[1,0]
	s_nop 0
	v_div_scale_f32 v0, s[2:3], v101, v101, 1.0
	v_rcp_f32_e32 v99, v0
	s_nop 0
	v_fma_f32 v114, -v0, v99, 1.0
	v_fmac_f32_e32 v99, v114, v99
	v_div_scale_f32 v114, vcc, 1.0, v101, 1.0
	v_mul_f32_e32 v115, v114, v99
	v_fma_f32 v116, -v0, v115, v114
	v_fmac_f32_e32 v115, v116, v99
	v_fma_f32 v0, -v0, v115, v114
	v_div_fmas_f32 v0, v0, v99, v115
	v_div_scale_f32 v99, s[2:3], v100, v100, 1.0
	v_div_fixup_f32 v0, v0, v101, 1.0
	v_rcp_f32_e32 v101, v99
	s_nop 0
	v_fma_f32 v114, -v99, v101, 1.0
	v_fmac_f32_e32 v101, v114, v101
	v_div_scale_f32 v114, vcc, 1.0, v100, 1.0
	v_mul_f32_e32 v115, v114, v101
	v_fma_f32 v116, -v99, v115, v114
	v_fmac_f32_e32 v115, v116, v101
	v_fma_f32 v99, -v99, v115, v114
	v_div_fmas_f32 v99, v99, v101, v115
	v_div_fixup_f32 v99, v99, v100, 1.0
	v_cvt_pk_bf16_f32 v99, v99, v0
	v_mul_f32_e32 v0, 0xbfb8aa3b, v102
	v_exp_f32_e32 v100, v0
	v_mul_f32_e32 v0, 0xbfb8aa3b, v103
	v_exp_f32_e32 v101, v0
	s_nop 0
	v_pk_add_f32 v[100:101], v[100:101], 1.0 op_sel_hi:[1,0]
	s_nop 0
	v_div_scale_f32 v0, s[2:3], v101, v101, 1.0
	v_rcp_f32_e32 v102, v0
	s_nop 0
	v_fma_f32 v103, -v0, v102, 1.0
	v_fmac_f32_e32 v102, v103, v102
	v_div_scale_f32 v103, vcc, 1.0, v101, 1.0
	v_mul_f32_e32 v114, v103, v102
	v_fma_f32 v115, -v0, v114, v103
	v_fmac_f32_e32 v114, v115, v102
	v_fma_f32 v0, -v0, v114, v103
	v_div_fmas_f32 v0, v0, v102, v114
	v_div_fixup_f32 v0, v0, v101, 1.0
	v_div_scale_f32 v101, s[2:3], v100, v100, 1.0
	v_rcp_f32_e32 v102, v101
	s_nop 0
	v_fma_f32 v103, -v101, v102, 1.0
	v_fmac_f32_e32 v102, v103, v102
	v_div_scale_f32 v103, vcc, 1.0, v100, 1.0
	v_mul_f32_e32 v114, v103, v102
	v_fma_f32 v115, -v101, v114, v103
	v_fmac_f32_e32 v114, v115, v102
	v_fma_f32 v101, -v101, v114, v103
	v_div_fmas_f32 v101, v101, v102, v114
	v_div_fixup_f32 v100, v101, v100, 1.0
	v_cvt_pk_bf16_f32 v100, v100, v0
	v_mul_f32_e32 v0, 0xbfb8aa3b, v104
	v_exp_f32_e32 v102, v0
	v_mul_f32_e32 v0, 0xbfb8aa3b, v105
	v_exp_f32_e32 v103, v0
	s_nop 0
	v_pk_add_f32 v[102:103], v[102:103], 1.0 op_sel_hi:[1,0]
	s_nop 0
	v_div_scale_f32 v0, s[2:3], v103, v103, 1.0
	v_rcp_f32_e32 v101, v0
	s_nop 0
	v_fma_f32 v104, -v0, v101, 1.0
	v_fmac_f32_e32 v101, v104, v101
	v_div_scale_f32 v104, vcc, 1.0, v103, 1.0
	v_mul_f32_e32 v105, v104, v101
	v_fma_f32 v114, -v0, v105, v104
	v_fmac_f32_e32 v105, v114, v101
	v_fma_f32 v0, -v0, v105, v104
	v_div_fmas_f32 v0, v0, v101, v105
	v_div_scale_f32 v101, s[2:3], v102, v102, 1.0
	v_div_fixup_f32 v0, v0, v103, 1.0
	v_rcp_f32_e32 v103, v101
	s_nop 0
	v_fma_f32 v104, -v101, v103, 1.0
	v_fmac_f32_e32 v103, v104, v103
	v_div_scale_f32 v104, vcc, 1.0, v102, 1.0
	v_mul_f32_e32 v105, v104, v103
	v_fma_f32 v114, -v101, v105, v104
	v_fmac_f32_e32 v105, v114, v103
	v_fma_f32 v101, -v101, v105, v104
	v_div_fmas_f32 v101, v101, v103, v105
	v_div_fixup_f32 v101, v101, v102, 1.0
	v_cvt_pk_bf16_f32 v101, v101, v0
	v_mul_f32_e32 v0, 0xbfb8aa3b, v106
	ds_write2_b64 v165, v[98:99], v[100:101] offset0:8 offset1:10
	v_exp_f32_e32 v98, v0
	v_mul_f32_e32 v0, 0xbfb8aa3b, v107
	v_exp_f32_e32 v99, v0
	s_nop 0
	v_pk_add_f32 v[98:99], v[98:99], 1.0 op_sel_hi:[1,0]
	s_nop 0
	v_div_scale_f32 v0, s[2:3], v99, v99, 1.0
	v_rcp_f32_e32 v100, v0
	s_nop 0
	v_fma_f32 v101, -v0, v100, 1.0
	v_fmac_f32_e32 v100, v101, v100
	v_div_scale_f32 v101, vcc, 1.0, v99, 1.0
	v_mul_f32_e32 v102, v101, v100
	v_fma_f32 v103, -v0, v102, v101
	v_fmac_f32_e32 v102, v103, v100
	v_fma_f32 v0, -v0, v102, v101
	v_div_fmas_f32 v0, v0, v100, v102
	v_div_fixup_f32 v0, v0, v99, 1.0
	v_div_scale_f32 v99, s[2:3], v98, v98, 1.0
	v_rcp_f32_e32 v100, v99
	s_nop 0
	v_fma_f32 v101, -v99, v100, 1.0
	v_fmac_f32_e32 v100, v101, v100
	v_div_scale_f32 v101, vcc, 1.0, v98, 1.0
	v_mul_f32_e32 v102, v101, v100
	v_fma_f32 v103, -v99, v102, v101
	v_fmac_f32_e32 v102, v103, v100
	v_fma_f32 v99, -v99, v102, v101
	v_div_fmas_f32 v99, v99, v100, v102
	v_div_fixup_f32 v98, v99, v98, 1.0
	v_cvt_pk_bf16_f32 v98, v98, v0
	v_mul_f32_e32 v0, 0xbfb8aa3b, v108
	v_exp_f32_e32 v100, v0
	v_mul_f32_e32 v0, 0xbfb8aa3b, v109
	v_exp_f32_e32 v101, v0
	s_nop 0
	v_pk_add_f32 v[100:101], v[100:101], 1.0 op_sel_hi:[1,0]
	s_nop 0
	v_div_scale_f32 v0, s[2:3], v101, v101, 1.0
	v_rcp_f32_e32 v99, v0
	s_nop 0
	v_fma_f32 v102, -v0, v99, 1.0
	v_fmac_f32_e32 v99, v102, v99
	v_div_scale_f32 v102, vcc, 1.0, v101, 1.0
	v_mul_f32_e32 v103, v102, v99
	v_fma_f32 v104, -v0, v103, v102
	v_fmac_f32_e32 v103, v104, v99
	v_fma_f32 v0, -v0, v103, v102
	v_div_fmas_f32 v0, v0, v99, v103
	v_div_scale_f32 v99, s[2:3], v100, v100, 1.0
	v_div_fixup_f32 v0, v0, v101, 1.0
	v_rcp_f32_e32 v101, v99
	s_nop 0
	v_fma_f32 v102, -v99, v101, 1.0
	v_fmac_f32_e32 v101, v102, v101
	v_div_scale_f32 v102, vcc, 1.0, v100, 1.0
	v_mul_f32_e32 v103, v102, v101
	v_fma_f32 v104, -v99, v103, v102
	v_fmac_f32_e32 v103, v104, v101
	v_fma_f32 v99, -v99, v103, v102
	v_div_fmas_f32 v99, v99, v101, v103
	v_div_fixup_f32 v99, v99, v100, 1.0
	v_cvt_pk_bf16_f32 v99, v99, v0
	v_mul_f32_e32 v0, 0xbfb8aa3b, v110
	v_exp_f32_e32 v100, v0
	v_mul_f32_e32 v0, 0xbfb8aa3b, v111
	v_exp_f32_e32 v101, v0
	s_nop 0
	v_pk_add_f32 v[100:101], v[100:101], 1.0 op_sel_hi:[1,0]
	s_nop 0
	v_div_scale_f32 v0, s[2:3], v101, v101, 1.0
	v_rcp_f32_e32 v102, v0
	s_nop 0
	v_fma_f32 v103, -v0, v102, 1.0
	v_fmac_f32_e32 v102, v103, v102
	v_div_scale_f32 v103, vcc, 1.0, v101, 1.0
	v_mul_f32_e32 v104, v103, v102
	v_fma_f32 v105, -v0, v104, v103
	v_fmac_f32_e32 v104, v105, v102
	v_fma_f32 v0, -v0, v104, v103
	v_div_fmas_f32 v0, v0, v102, v104
	v_div_fixup_f32 v0, v0, v101, 1.0
	v_div_scale_f32 v101, s[2:3], v100, v100, 1.0
	v_rcp_f32_e32 v102, v101
	s_nop 0
; DI unsigned pk2(float a, float b) { f32v2 v = {a, b}; return __builtin_bit_cast(unsigned, __builtin_convertvector(v, bf16v2)); }
; DI float sigmoidf_(float v) { return 1.f / (1.f + __expf(-v)); }
; #define SW_FOR_TOK(j) _Pragma("unroll") for (int j = 0; j < 4; j++)
; #define SW_FOR_FEAT(i, rq) _Pragma("unroll") for (int i = 0; i < 2; i++) _Pragma("unroll") for (int rq = 0; rq < 4; rq++)
; DI void ph_ple(const Params& P, int g, int layer, bf16_t* smem) {
;     ...
;     SW_FOR_TOK(j) { const int tl_ = wn * 128 + j * 32 + l32;
;       SW_FOR_FEAT(i, rq) { const int c_ = wm * 64 + i * 32 + 8 * rq + 4 * h;
;         *(uint2*)(smem + tl_ * EPLD + c_) = make_uint2(pk2(sigmoidf_(SWV(i, j, 4 * rq)), sigmoidf_(SWV(i, j, 4 * rq + 1))), pk2(sigmoidf_(SWV(i, j, 4 * rq + 2)), sigmoidf_(SWV(i, j, 4 * rq + 3)))); } }
	v_fma_f32 v103, -v101, v102, 1.0
	v_fmac_f32_e32 v102, v103, v102
	v_div_scale_f32 v103, vcc, 1.0, v100, 1.0
	v_mul_f32_e32 v104, v103, v102
	v_fma_f32 v105, -v101, v104, v103
	v_fmac_f32_e32 v104, v105, v102
	v_fma_f32 v101, -v101, v104, v103
	v_div_fmas_f32 v101, v101, v102, v104
	v_div_fixup_f32 v100, v101, v100, 1.0
	v_cvt_pk_bf16_f32 v100, v100, v0
	v_mul_f32_e32 v0, 0xbfb8aa3b, v112
	v_exp_f32_e32 v102, v0
	v_mul_f32_e32 v0, 0xbfb8aa3b, v113
	v_exp_f32_e32 v103, v0
	s_nop 0
	v_pk_add_f32 v[102:103], v[102:103], 1.0 op_sel_hi:[1,0]
	s_nop 0
	v_div_scale_f32 v0, s[2:3], v103, v103, 1.0
	v_rcp_f32_e32 v101, v0
	s_nop 0
	v_fma_f32 v104, -v0, v101, 1.0
	v_fmac_f32_e32 v101, v104, v101
	v_div_scale_f32 v104, vcc, 1.0, v103, 1.0
	v_mul_f32_e32 v105, v104, v101
	v_fma_f32 v106, -v0, v105, v104
	v_fmac_f32_e32 v105, v106, v101
	v_fma_f32 v0, -v0, v105, v104
	v_div_fmas_f32 v0, v0, v101, v105
	v_div_scale_f32 v101, s[2:3], v102, v102, 1.0
	v_div_fixup_f32 v0, v0, v103, 1.0
	v_rcp_f32_e32 v103, v101
	s_nop 0
	v_fma_f32 v104, -v101, v103, 1.0
	v_fmac_f32_e32 v103, v104, v103
	v_div_scale_f32 v104, vcc, 1.0, v102, 1.0
	v_mul_f32_e32 v105, v104, v103
	v_fma_f32 v106, -v101, v105, v104
	v_fmac_f32_e32 v105, v106, v103
	v_fma_f32 v101, -v101, v105, v104
	v_div_fmas_f32 v101, v101, v103, v105
	v_div_fixup_f32 v101, v101, v102, 1.0
	v_cvt_pk_bf16_f32 v101, v101, v0
	v_mul_f32_e32 v0, 0xbfb8aa3b, v82
	v_exp_f32_e32 v82, v0
	v_mul_f32_e32 v0, 0xbfb8aa3b, v83
	v_exp_f32_e32 v83, v0
	ds_write2_b64 v165, v[98:99], v[100:101] offset0:12 offset1:14
	v_pk_add_f32 v[82:83], v[82:83], 1.0 op_sel_hi:[1,0]
	s_nop 0
	v_div_scale_f32 v0, s[2:3], v83, v83, 1.0
	v_rcp_f32_e32 v98, v0
	s_nop 0
	v_fma_f32 v99, -v0, v98, 1.0
	v_fmac_f32_e32 v98, v99, v98
	v_div_scale_f32 v99, vcc, 1.0, v83, 1.0
	v_mul_f32_e32 v100, v99, v98
	v_fma_f32 v101, -v0, v100, v99
	v_fmac_f32_e32 v100, v101, v98
	v_fma_f32 v0, -v0, v100, v99
	v_div_fmas_f32 v0, v0, v98, v100
	v_div_fixup_f32 v0, v0, v83, 1.0
	v_div_scale_f32 v83, s[2:3], v82, v82, 1.0
	v_rcp_f32_e32 v98, v83
	s_nop 0
	v_fma_f32 v99, -v83, v98, 1.0
	v_fmac_f32_e32 v98, v99, v98
	v_div_scale_f32 v99, vcc, 1.0, v82, 1.0
	v_mul_f32_e32 v100, v99, v98
	v_fma_f32 v101, -v83, v100, v99
	v_fmac_f32_e32 v100, v101, v98
	v_fma_f32 v83, -v83, v100, v99
	v_div_fmas_f32 v83, v83, v98, v100
	v_div_fixup_f32 v82, v83, v82, 1.0
	v_cvt_pk_bf16_f32 v82, v82, v0
	v_mul_f32_e32 v0, 0xbfb8aa3b, v84
	v_exp_f32_e32 v84, v0
	v_mul_f32_e32 v0, 0xbfb8aa3b, v85
	v_exp_f32_e32 v85, v0
	s_nop 0
	v_pk_add_f32 v[84:85], v[84:85], 1.0 op_sel_hi:[1,0]
	s_nop 0
	v_div_scale_f32 v0, s[2:3], v85, v85, 1.0
	v_rcp_f32_e32 v83, v0
	s_nop 0
	v_fma_f32 v98, -v0, v83, 1.0
	v_fmac_f32_e32 v83, v98, v83
	v_div_scale_f32 v98, vcc, 1.0, v85, 1.0
	v_mul_f32_e32 v99, v98, v83
	v_fma_f32 v100, -v0, v99, v98
	v_fmac_f32_e32 v99, v100, v83
	v_fma_f32 v0, -v0, v99, v98
	v_div_fmas_f32 v0, v0, v83, v99
	v_div_scale_f32 v83, s[2:3], v84, v84, 1.0
	v_div_fixup_f32 v0, v0, v85, 1.0
	v_rcp_f32_e32 v85, v83
	s_nop 0
	v_fma_f32 v98, -v83, v85, 1.0
	v_fmac_f32_e32 v85, v98, v85
	v_div_scale_f32 v98, vcc, 1.0, v84, 1.0
	v_mul_f32_e32 v99, v98, v85
	v_fma_f32 v100, -v83, v99, v98
	v_fmac_f32_e32 v99, v100, v85
	v_fma_f32 v83, -v83, v99, v98
	v_div_fmas_f32 v83, v83, v85, v99
	v_div_fixup_f32 v83, v83, v84, 1.0
	v_cvt_pk_bf16_f32 v83, v83, v0
	v_mul_f32_e32 v0, 0xbfb8aa3b, v86
	v_exp_f32_e32 v84, v0
	v_mul_f32_e32 v0, 0xbfb8aa3b, v87
	v_exp_f32_e32 v85, v0
	s_nop 0
	v_pk_add_f32 v[84:85], v[84:85], 1.0 op_sel_hi:[1,0]
	s_nop 0
	v_div_scale_f32 v0, s[2:3], v85, v85, 1.0
	v_rcp_f32_e32 v86, v0
	s_nop 0
	v_fma_f32 v87, -v0, v86, 1.0
	v_fmac_f32_e32 v86, v87, v86
	v_div_scale_f32 v87, vcc, 1.0, v85, 1.0
	v_mul_f32_e32 v98, v87, v86
	v_fma_f32 v99, -v0, v98, v87
	v_fmac_f32_e32 v98, v99, v86
	v_fma_f32 v0, -v0, v98, v87
	v_div_fmas_f32 v0, v0, v86, v98
	v_div_fixup_f32 v0, v0, v85, 1.0
	v_div_scale_f32 v85, s[2:3], v84, v84, 1.0
	v_rcp_f32_e32 v86, v85
	s_nop 0
	v_fma_f32 v87, -v85, v86, 1.0
	v_fmac_f32_e32 v86, v87, v86
	v_div_scale_f32 v87, vcc, 1.0, v84, 1.0
	v_mul_f32_e32 v98, v87, v86
	v_fma_f32 v99, -v85, v98, v87
	v_fmac_f32_e32 v98, v99, v86
	v_fma_f32 v85, -v85, v98, v87
	v_div_fmas_f32 v85, v85, v86, v98
	v_div_fixup_f32 v84, v85, v84, 1.0
	v_cvt_pk_bf16_f32 v84, v84, v0
	v_mul_f32_e32 v0, 0xbfb8aa3b, v88
	v_exp_f32_e32 v86, v0
	v_mul_f32_e32 v0, 0xbfb8aa3b, v89
	v_exp_f32_e32 v87, v0
	s_nop 0
	v_pk_add_f32 v[86:87], v[86:87], 1.0 op_sel_hi:[1,0]
	s_nop 0
	v_div_scale_f32 v0, s[2:3], v87, v87, 1.0
	v_rcp_f32_e32 v85, v0
	s_nop 0
	v_fma_f32 v88, -v0, v85, 1.0
	v_fmac_f32_e32 v85, v88, v85
	v_div_scale_f32 v88, vcc, 1.0, v87, 1.0
	v_mul_f32_e32 v89, v88, v85
	v_fma_f32 v98, -v0, v89, v88
	v_fmac_f32_e32 v89, v98, v85
	v_fma_f32 v0, -v0, v89, v88
	v_div_fmas_f32 v0, v0, v85, v89
	v_div_scale_f32 v85, s[2:3], v86, v86, 1.0
	v_div_fixup_f32 v0, v0, v87, 1.0
	v_rcp_f32_e32 v87, v85
	s_nop 0
	v_fma_f32 v88, -v85, v87, 1.0
	v_fmac_f32_e32 v87, v88, v87
	v_div_scale_f32 v88, vcc, 1.0, v86, 1.0
	v_mul_f32_e32 v89, v88, v87
	v_fma_f32 v98, -v85, v89, v88
	v_fmac_f32_e32 v89, v98, v87
	v_fma_f32 v85, -v85, v89, v88
	v_div_fmas_f32 v85, v85, v87, v89
	v_div_fixup_f32 v85, v85, v86, 1.0
	v_cvt_pk_bf16_f32 v85, v85, v0
	v_mul_f32_e32 v0, 0xbfb8aa3b, v90
	ds_write2_b64 v193, v[82:83], v[84:85] offset0:64 offset1:66
	v_exp_f32_e32 v82, v0
	v_mul_f32_e32 v0, 0xbfb8aa3b, v91
	v_exp_f32_e32 v83, v0
	s_nop 0
	v_pk_add_f32 v[82:83], v[82:83], 1.0 op_sel_hi:[1,0]
	s_nop 0
	v_div_scale_f32 v0, s[2:3], v83, v83, 1.0
	v_rcp_f32_e32 v84, v0
	s_nop 0
	v_fma_f32 v85, -v0, v84, 1.0
	v_fmac_f32_e32 v84, v85, v84
; DI unsigned pk2(float a, float b) { f32v2 v = {a, b}; return __builtin_bit_cast(unsigned, __builtin_convertvector(v, bf16v2)); }
; DI float sigmoidf_(float v) { return 1.f / (1.f + __expf(-v)); }
; #define SW_FOR_TOK(j) _Pragma("unroll") for (int j = 0; j < 4; j++)
; #define SW_FOR_FEAT(i, rq) _Pragma("unroll") for (int i = 0; i < 2; i++) _Pragma("unroll") for (int rq = 0; rq < 4; rq++)
; DI void ph_ple(const Params& P, int g, int layer, bf16_t* smem) {
;     ...
;     SW_FOR_TOK(j) { const int tl_ = wn * 128 + j * 32 + l32;
;       SW_FOR_FEAT(i, rq) { const int c_ = wm * 64 + i * 32 + 8 * rq + 4 * h;
;         *(uint2*)(smem + tl_ * EPLD + c_) = make_uint2(pk2(sigmoidf_(SWV(i, j, 4 * rq)), sigmoidf_(SWV(i, j, 4 * rq + 1))), pk2(sigmoidf_(SWV(i, j, 4 * rq + 2)), sigmoidf_(SWV(i, j, 4 * rq + 3)))); } }
	v_div_scale_f32 v85, vcc, 1.0, v83, 1.0
	v_mul_f32_e32 v86, v85, v84
	v_fma_f32 v87, -v0, v86, v85
	v_fmac_f32_e32 v86, v87, v84
	v_fma_f32 v0, -v0, v86, v85
	v_div_fmas_f32 v0, v0, v84, v86
	v_div_fixup_f32 v0, v0, v83, 1.0
	v_div_scale_f32 v83, s[2:3], v82, v82, 1.0
	v_rcp_f32_e32 v84, v83
	s_nop 0
	v_fma_f32 v85, -v83, v84, 1.0
	v_fmac_f32_e32 v84, v85, v84
	v_div_scale_f32 v85, vcc, 1.0, v82, 1.0
	v_mul_f32_e32 v86, v85, v84
	v_fma_f32 v87, -v83, v86, v85
	v_fmac_f32_e32 v86, v87, v84
	v_fma_f32 v83, -v83, v86, v85
	v_div_fmas_f32 v83, v83, v84, v86
	v_div_fixup_f32 v82, v83, v82, 1.0
	v_cvt_pk_bf16_f32 v82, v82, v0
	v_mul_f32_e32 v0, 0xbfb8aa3b, v92
	v_exp_f32_e32 v84, v0
	v_mul_f32_e32 v0, 0xbfb8aa3b, v93
	v_exp_f32_e32 v85, v0
	s_nop 0
	v_pk_add_f32 v[84:85], v[84:85], 1.0 op_sel_hi:[1,0]
	s_nop 0
	v_div_scale_f32 v0, s[2:3], v85, v85, 1.0
	v_rcp_f32_e32 v83, v0
	s_nop 0
	v_fma_f32 v86, -v0, v83, 1.0
	v_fmac_f32_e32 v83, v86, v83
	v_div_scale_f32 v86, vcc, 1.0, v85, 1.0
	v_mul_f32_e32 v87, v86, v83
	v_fma_f32 v88, -v0, v87, v86
	v_fmac_f32_e32 v87, v88, v83
	v_fma_f32 v0, -v0, v87, v86
	v_div_fmas_f32 v0, v0, v83, v87
	v_div_scale_f32 v83, s[2:3], v84, v84, 1.0
	v_div_fixup_f32 v0, v0, v85, 1.0
	v_rcp_f32_e32 v85, v83
	s_nop 0
	v_fma_f32 v86, -v83, v85, 1.0
	v_fmac_f32_e32 v85, v86, v85
	v_div_scale_f32 v86, vcc, 1.0, v84, 1.0
	v_mul_f32_e32 v87, v86, v85
	v_fma_f32 v88, -v83, v87, v86
	v_fmac_f32_e32 v87, v88, v85
	v_fma_f32 v83, -v83, v87, v86
	v_div_fmas_f32 v83, v83, v85, v87
	v_div_fixup_f32 v83, v83, v84, 1.0
	v_cvt_pk_bf16_f32 v83, v83, v0
	v_mul_f32_e32 v0, 0xbfb8aa3b, v94
	v_exp_f32_e32 v84, v0
	v_mul_f32_e32 v0, 0xbfb8aa3b, v95
	v_exp_f32_e32 v85, v0
	s_nop 0
	v_pk_add_f32 v[84:85], v[84:85], 1.0 op_sel_hi:[1,0]
	s_nop 0
	v_div_scale_f32 v0, s[2:3], v85, v85, 1.0
	v_rcp_f32_e32 v86, v0
	s_nop 0
	v_fma_f32 v87, -v0, v86, 1.0
	v_fmac_f32_e32 v86, v87, v86
	v_div_scale_f32 v87, vcc, 1.0, v85, 1.0
	v_mul_f32_e32 v88, v87, v86
	v_fma_f32 v89, -v0, v88, v87
	v_fmac_f32_e32 v88, v89, v86
	v_fma_f32 v0, -v0, v88, v87
	v_div_fmas_f32 v0, v0, v86, v88
	v_div_fixup_f32 v0, v0, v85, 1.0
	v_div_scale_f32 v85, s[2:3], v84, v84, 1.0
	v_rcp_f32_e32 v86, v85
	s_nop 0
	v_fma_f32 v87, -v85, v86, 1.0
	v_fmac_f32_e32 v86, v87, v86
	v_div_scale_f32 v87, vcc, 1.0, v84, 1.0
	v_mul_f32_e32 v88, v87, v86
	v_fma_f32 v89, -v85, v88, v87
	v_fmac_f32_e32 v88, v89, v86
	v_fma_f32 v85, -v85, v88, v87
	v_div_fmas_f32 v85, v85, v86, v88
	v_div_fixup_f32 v84, v85, v84, 1.0
	v_cvt_pk_bf16_f32 v84, v84, v0
	v_mul_f32_e32 v0, 0xbfb8aa3b, v96
	v_exp_f32_e32 v86, v0
	v_mul_f32_e32 v0, 0xbfb8aa3b, v97
	v_exp_f32_e32 v87, v0
	s_nop 0
	v_pk_add_f32 v[86:87], v[86:87], 1.0 op_sel_hi:[1,0]
	s_nop 0
	v_div_scale_f32 v0, s[2:3], v87, v87, 1.0
	v_rcp_f32_e32 v85, v0
	s_nop 0
	v_fma_f32 v88, -v0, v85, 1.0
	v_fmac_f32_e32 v85, v88, v85
	v_div_scale_f32 v88, vcc, 1.0, v87, 1.0
	v_mul_f32_e32 v89, v88, v85
	v_fma_f32 v90, -v0, v89, v88
	v_fmac_f32_e32 v89, v90, v85
	v_fma_f32 v0, -v0, v89, v88
	v_div_fmas_f32 v0, v0, v85, v89
	v_div_scale_f32 v85, s[2:3], v86, v86, 1.0
	v_div_fixup_f32 v0, v0, v87, 1.0
	v_rcp_f32_e32 v87, v85
	s_nop 0
	v_fma_f32 v88, -v85, v87, 1.0
	v_fmac_f32_e32 v87, v88, v87
	v_div_scale_f32 v88, vcc, 1.0, v86, 1.0
	v_mul_f32_e32 v89, v88, v87
	v_fma_f32 v90, -v85, v89, v88
	v_fmac_f32_e32 v89, v90, v87
	v_fma_f32 v85, -v85, v89, v88
	v_div_fmas_f32 v85, v85, v87, v89
	v_div_fixup_f32 v85, v85, v86, 1.0
	v_cvt_pk_bf16_f32 v85, v85, v0
	v_mul_f32_e32 v0, 0xbfb8aa3b, v66
	v_exp_f32_e32 v66, v0
	v_mul_f32_e32 v0, 0xbfb8aa3b, v67
	v_exp_f32_e32 v67, v0
	ds_write2_b64 v193, v[82:83], v[84:85] offset0:68 offset1:70
	v_pk_add_f32 v[66:67], v[66:67], 1.0 op_sel_hi:[1,0]
	s_nop 0
	v_div_scale_f32 v0, s[2:3], v67, v67, 1.0
	v_rcp_f32_e32 v82, v0
	s_nop 0
	v_fma_f32 v83, -v0, v82, 1.0
	v_fmac_f32_e32 v82, v83, v82
	v_div_scale_f32 v83, vcc, 1.0, v67, 1.0
	v_mul_f32_e32 v84, v83, v82
	v_fma_f32 v85, -v0, v84, v83
	v_fmac_f32_e32 v84, v85, v82
	v_fma_f32 v0, -v0, v84, v83
	v_div_fmas_f32 v0, v0, v82, v84
	v_div_fixup_f32 v0, v0, v67, 1.0
	v_div_scale_f32 v67, s[2:3], v66, v66, 1.0
	v_rcp_f32_e32 v82, v67
	s_nop 0
	v_fma_f32 v83, -v67, v82, 1.0
	v_fmac_f32_e32 v82, v83, v82
	v_div_scale_f32 v83, vcc, 1.0, v66, 1.0
	v_mul_f32_e32 v84, v83, v82
	v_fma_f32 v85, -v67, v84, v83
	v_fmac_f32_e32 v84, v85, v82
	v_fma_f32 v67, -v67, v84, v83
	v_div_fmas_f32 v67, v67, v82, v84
	v_div_fixup_f32 v66, v67, v66, 1.0
	v_cvt_pk_bf16_f32 v66, v66, v0
	v_mul_f32_e32 v0, 0xbfb8aa3b, v68
	v_exp_f32_e32 v68, v0
	v_mul_f32_e32 v0, 0xbfb8aa3b, v69
	v_exp_f32_e32 v69, v0
	s_nop 0
	v_pk_add_f32 v[68:69], v[68:69], 1.0 op_sel_hi:[1,0]
	s_nop 0
	v_div_scale_f32 v0, s[2:3], v69, v69, 1.0
	v_rcp_f32_e32 v67, v0
	s_nop 0
	v_fma_f32 v82, -v0, v67, 1.0
	v_fmac_f32_e32 v67, v82, v67
	v_div_scale_f32 v82, vcc, 1.0, v69, 1.0
	v_mul_f32_e32 v83, v82, v67
	v_fma_f32 v84, -v0, v83, v82
	v_fmac_f32_e32 v83, v84, v67
	v_fma_f32 v0, -v0, v83, v82
	v_div_fmas_f32 v0, v0, v67, v83
	v_div_scale_f32 v67, s[2:3], v68, v68, 1.0
	v_div_fixup_f32 v0, v0, v69, 1.0
	v_rcp_f32_e32 v69, v67
	s_nop 0
	v_fma_f32 v82, -v67, v69, 1.0
	v_fmac_f32_e32 v69, v82, v69
	v_div_scale_f32 v82, vcc, 1.0, v68, 1.0
	v_mul_f32_e32 v83, v82, v69
	v_fma_f32 v84, -v67, v83, v82
	v_fmac_f32_e32 v83, v84, v69
	v_fma_f32 v67, -v67, v83, v82
	v_div_fmas_f32 v67, v67, v69, v83
	v_div_fixup_f32 v67, v67, v68, 1.0
	v_cvt_pk_bf16_f32 v67, v67, v0
	v_mul_f32_e32 v0, 0xbfb8aa3b, v70
	v_exp_f32_e32 v68, v0
	v_mul_f32_e32 v0, 0xbfb8aa3b, v71
	v_exp_f32_e32 v69, v0
	s_nop 0
	v_pk_add_f32 v[68:69], v[68:69], 1.0 op_sel_hi:[1,0]
	s_nop 0
; DI unsigned pk2(float a, float b) { f32v2 v = {a, b}; return __builtin_bit_cast(unsigned, __builtin_convertvector(v, bf16v2)); }
; DI float sigmoidf_(float v) { return 1.f / (1.f + __expf(-v)); }
; #define SW_FOR_TOK(j) _Pragma("unroll") for (int j = 0; j < 4; j++)
; #define SW_FOR_FEAT(i, rq) _Pragma("unroll") for (int i = 0; i < 2; i++) _Pragma("unroll") for (int rq = 0; rq < 4; rq++)
; DI void ph_ple(const Params& P, int g, int layer, bf16_t* smem) {
;     ...
;     SW_FOR_TOK(j) { const int tl_ = wn * 128 + j * 32 + l32;
;       SW_FOR_FEAT(i, rq) { const int c_ = wm * 64 + i * 32 + 8 * rq + 4 * h;
;         *(uint2*)(smem + tl_ * EPLD + c_) = make_uint2(pk2(sigmoidf_(SWV(i, j, 4 * rq)), sigmoidf_(SWV(i, j, 4 * rq + 1))), pk2(sigmoidf_(SWV(i, j, 4 * rq + 2)), sigmoidf_(SWV(i, j, 4 * rq + 3)))); } }
	v_div_scale_f32 v0, s[2:3], v69, v69, 1.0
	v_rcp_f32_e32 v70, v0
	s_nop 0
	v_fma_f32 v71, -v0, v70, 1.0
	v_fmac_f32_e32 v70, v71, v70
	v_div_scale_f32 v71, vcc, 1.0, v69, 1.0
	v_mul_f32_e32 v82, v71, v70
	v_fma_f32 v83, -v0, v82, v71
	v_fmac_f32_e32 v82, v83, v70
	v_fma_f32 v0, -v0, v82, v71
	v_div_fmas_f32 v0, v0, v70, v82
	v_div_fixup_f32 v0, v0, v69, 1.0
	v_div_scale_f32 v69, s[2:3], v68, v68, 1.0
	v_rcp_f32_e32 v70, v69
	s_nop 0
	v_fma_f32 v71, -v69, v70, 1.0
	v_fmac_f32_e32 v70, v71, v70
	v_div_scale_f32 v71, vcc, 1.0, v68, 1.0
	v_mul_f32_e32 v82, v71, v70
	v_fma_f32 v83, -v69, v82, v71
	v_fmac_f32_e32 v82, v83, v70
	v_fma_f32 v69, -v69, v82, v71
	v_div_fmas_f32 v69, v69, v70, v82
	v_div_fixup_f32 v68, v69, v68, 1.0
	v_cvt_pk_bf16_f32 v68, v68, v0
	v_mul_f32_e32 v0, 0xbfb8aa3b, v72
	v_exp_f32_e32 v70, v0
	v_mul_f32_e32 v0, 0xbfb8aa3b, v73
	v_exp_f32_e32 v71, v0
	s_nop 0
	v_pk_add_f32 v[70:71], v[70:71], 1.0 op_sel_hi:[1,0]
	s_nop 0
	v_div_scale_f32 v0, s[2:3], v71, v71, 1.0
	v_rcp_f32_e32 v69, v0
	s_nop 0
	v_fma_f32 v72, -v0, v69, 1.0
	v_fmac_f32_e32 v69, v72, v69
	v_div_scale_f32 v72, vcc, 1.0, v71, 1.0
	v_mul_f32_e32 v73, v72, v69
	v_fma_f32 v82, -v0, v73, v72
	v_fmac_f32_e32 v73, v82, v69
	v_fma_f32 v0, -v0, v73, v72
	v_div_fmas_f32 v0, v0, v69, v73
	v_div_scale_f32 v69, s[2:3], v70, v70, 1.0
	v_div_fixup_f32 v0, v0, v71, 1.0
	v_rcp_f32_e32 v71, v69
	s_nop 0
	v_fma_f32 v72, -v69, v71, 1.0
	v_fmac_f32_e32 v71, v72, v71
	v_div_scale_f32 v72, vcc, 1.0, v70, 1.0
	v_mul_f32_e32 v73, v72, v71
	v_fma_f32 v82, -v69, v73, v72
	v_fmac_f32_e32 v73, v82, v71
	v_fma_f32 v69, -v69, v73, v72
	v_div_fmas_f32 v69, v69, v71, v73
	v_div_fixup_f32 v69, v69, v70, 1.0
	v_cvt_pk_bf16_f32 v69, v69, v0
	v_mul_f32_e32 v0, 0xbfb8aa3b, v74
	ds_write2_b64 v193, v[66:67], v[68:69] offset0:72 offset1:74
	v_exp_f32_e32 v66, v0
	v_mul_f32_e32 v0, 0xbfb8aa3b, v75
	v_exp_f32_e32 v67, v0
	s_nop 0
	v_pk_add_f32 v[66:67], v[66:67], 1.0 op_sel_hi:[1,0]
	s_nop 0
	v_div_scale_f32 v0, s[2:3], v67, v67, 1.0
	v_rcp_f32_e32 v68, v0
	s_nop 0
	v_fma_f32 v69, -v0, v68, 1.0
	v_fmac_f32_e32 v68, v69, v68
	v_div_scale_f32 v69, vcc, 1.0, v67, 1.0
	v_mul_f32_e32 v70, v69, v68
	v_fma_f32 v71, -v0, v70, v69
	v_fmac_f32_e32 v70, v71, v68
	v_fma_f32 v0, -v0, v70, v69
	v_div_fmas_f32 v0, v0, v68, v70
	v_div_fixup_f32 v0, v0, v67, 1.0
	v_div_scale_f32 v67, s[2:3], v66, v66, 1.0
	v_rcp_f32_e32 v68, v67
	s_nop 0
	v_fma_f32 v69, -v67, v68, 1.0
	v_fmac_f32_e32 v68, v69, v68
	v_div_scale_f32 v69, vcc, 1.0, v66, 1.0
	v_mul_f32_e32 v70, v69, v68
	v_fma_f32 v71, -v67, v70, v69
	v_fmac_f32_e32 v70, v71, v68
	v_fma_f32 v67, -v67, v70, v69
	v_div_fmas_f32 v67, v67, v68, v70
	v_div_fixup_f32 v66, v67, v66, 1.0
	v_cvt_pk_bf16_f32 v66, v66, v0
	v_mul_f32_e32 v0, 0xbfb8aa3b, v76
	v_exp_f32_e32 v68, v0
	v_mul_f32_e32 v0, 0xbfb8aa3b, v77
	v_exp_f32_e32 v69, v0
	s_nop 0
	v_pk_add_f32 v[68:69], v[68:69], 1.0 op_sel_hi:[1,0]
	s_nop 0
	v_div_scale_f32 v0, s[2:3], v69, v69, 1.0
	v_rcp_f32_e32 v67, v0
	s_nop 0
	v_fma_f32 v70, -v0, v67, 1.0
	v_fmac_f32_e32 v67, v70, v67
	v_div_scale_f32 v70, vcc, 1.0, v69, 1.0
	v_mul_f32_e32 v71, v70, v67
	v_fma_f32 v72, -v0, v71, v70
	v_fmac_f32_e32 v71, v72, v67
	v_fma_f32 v0, -v0, v71, v70
	v_div_fmas_f32 v0, v0, v67, v71
	v_div_scale_f32 v67, s[2:3], v68, v68, 1.0
	v_div_fixup_f32 v0, v0, v69, 1.0
	v_rcp_f32_e32 v69, v67
	s_nop 0
	v_fma_f32 v70, -v67, v69, 1.0
	v_fmac_f32_e32 v69, v70, v69
	v_div_scale_f32 v70, vcc, 1.0, v68, 1.0
	v_mul_f32_e32 v71, v70, v69
	v_fma_f32 v72, -v67, v71, v70
	v_fmac_f32_e32 v71, v72, v69
	v_fma_f32 v67, -v67, v71, v70
	v_div_fmas_f32 v67, v67, v69, v71
	v_div_fixup_f32 v67, v67, v68, 1.0
	v_cvt_pk_bf16_f32 v67, v67, v0
	v_mul_f32_e32 v0, 0xbfb8aa3b, v78
	v_exp_f32_e32 v68, v0
	v_mul_f32_e32 v0, 0xbfb8aa3b, v79
	v_exp_f32_e32 v69, v0
	s_nop 0
	v_pk_add_f32 v[68:69], v[68:69], 1.0 op_sel_hi:[1,0]
	s_nop 0
	v_div_scale_f32 v0, s[2:3], v69, v69, 1.0
	v_rcp_f32_e32 v70, v0
	s_nop 0
	v_fma_f32 v71, -v0, v70, 1.0
	v_fmac_f32_e32 v70, v71, v70
	v_div_scale_f32 v71, vcc, 1.0, v69, 1.0
	v_mul_f32_e32 v72, v71, v70
	v_fma_f32 v73, -v0, v72, v71
	v_fmac_f32_e32 v72, v73, v70
	v_fma_f32 v0, -v0, v72, v71
	v_div_fmas_f32 v0, v0, v70, v72
	v_div_fixup_f32 v0, v0, v69, 1.0
	v_div_scale_f32 v69, s[2:3], v68, v68, 1.0
	v_rcp_f32_e32 v70, v69
	s_nop 0
	v_fma_f32 v71, -v69, v70, 1.0
	v_fmac_f32_e32 v70, v71, v70
	v_div_scale_f32 v71, vcc, 1.0, v68, 1.0
	v_mul_f32_e32 v72, v71, v70
	v_fma_f32 v73, -v69, v72, v71
	v_fmac_f32_e32 v72, v73, v70
	v_fma_f32 v69, -v69, v72, v71
	v_div_fmas_f32 v69, v69, v70, v72
	v_div_fixup_f32 v68, v69, v68, 1.0
	v_cvt_pk_bf16_f32 v68, v68, v0
	v_mul_f32_e32 v0, 0xbfb8aa3b, v80
	v_exp_f32_e32 v70, v0
	v_mul_f32_e32 v0, 0xbfb8aa3b, v81
	v_exp_f32_e32 v71, v0
	s_nop 0
	v_pk_add_f32 v[70:71], v[70:71], 1.0 op_sel_hi:[1,0]
	s_nop 0
	v_div_scale_f32 v0, s[2:3], v71, v71, 1.0
	v_rcp_f32_e32 v69, v0
	s_nop 0
	v_fma_f32 v72, -v0, v69, 1.0
	v_fmac_f32_e32 v69, v72, v69
	v_div_scale_f32 v72, vcc, 1.0, v71, 1.0
	v_mul_f32_e32 v73, v72, v69
	v_fma_f32 v74, -v0, v73, v72
	v_fmac_f32_e32 v73, v74, v69
	v_fma_f32 v0, -v0, v73, v72
	v_div_fmas_f32 v0, v0, v69, v73
	v_div_scale_f32 v69, s[2:3], v70, v70, 1.0
	v_div_fixup_f32 v0, v0, v71, 1.0
	v_rcp_f32_e32 v71, v69
	s_nop 0
	v_fma_f32 v72, -v69, v71, 1.0
	v_fmac_f32_e32 v71, v72, v71
	v_div_scale_f32 v72, vcc, 1.0, v70, 1.0
	v_mul_f32_e32 v73, v72, v71
	v_fma_f32 v74, -v69, v73, v72
	v_fmac_f32_e32 v73, v74, v71
	v_fma_f32 v69, -v69, v73, v72
	v_div_fmas_f32 v69, v69, v71, v73
	v_div_fixup_f32 v69, v69, v70, 1.0
	v_cvt_pk_bf16_f32 v69, v69, v0
	v_mul_f32_e32 v0, 0xbfb8aa3b, v50
	v_exp_f32_e32 v50, v0
; DI unsigned pk2(float a, float b) { f32v2 v = {a, b}; return __builtin_bit_cast(unsigned, __builtin_convertvector(v, bf16v2)); }
; #define SW_FOR_TOK(j) _Pragma("unroll") for (int j = 0; j < 4; j++)
; #define SW_FOR_FEAT(i, rq) _Pragma("unroll") for (int i = 0; i < 2; i++) _Pragma("unroll") for (int rq = 0; rq < 4; rq++)
; DI float sigmoidf_(float v) { return 1.f / (1.f + __expf(-v)); }
; DI void ph_ple(const Params& P, int g, int layer, bf16_t* smem) {
;     ...
;     SW_FOR_TOK(j) { const int tl_ = wn * 128 + j * 32 + l32;
;       SW_FOR_FEAT(i, rq) { const int c_ = wm * 64 + i * 32 + 8 * rq + 4 * h;
;         *(uint2*)(smem + tl_ * EPLD + c_) = make_uint2(pk2(sigmoidf_(SWV(i, j, 4 * rq)), sigmoidf_(SWV(i, j, 4 * rq + 1))), pk2(sigmoidf_(SWV(i, j, 4 * rq + 2)), sigmoidf_(SWV(i, j, 4 * rq + 3)))); } }
	v_mul_f32_e32 v0, 0xbfb8aa3b, v51
	v_exp_f32_e32 v51, v0
	ds_write2_b64 v193, v[66:67], v[68:69] offset0:76 offset1:78
	v_pk_add_f32 v[50:51], v[50:51], 1.0 op_sel_hi:[1,0]
	s_nop 0
	v_div_scale_f32 v0, s[2:3], v51, v51, 1.0
	v_rcp_f32_e32 v66, v0
	s_nop 0
	v_fma_f32 v67, -v0, v66, 1.0
	v_fmac_f32_e32 v66, v67, v66
	v_div_scale_f32 v67, vcc, 1.0, v51, 1.0
	v_mul_f32_e32 v68, v67, v66
	v_fma_f32 v69, -v0, v68, v67
	v_fmac_f32_e32 v68, v69, v66
	v_fma_f32 v0, -v0, v68, v67
	v_div_fmas_f32 v0, v0, v66, v68
	v_div_fixup_f32 v0, v0, v51, 1.0
	v_div_scale_f32 v51, s[2:3], v50, v50, 1.0
	v_rcp_f32_e32 v66, v51
	s_nop 0
	v_fma_f32 v67, -v51, v66, 1.0
	v_fmac_f32_e32 v66, v67, v66
	v_div_scale_f32 v67, vcc, 1.0, v50, 1.0
	v_mul_f32_e32 v68, v67, v66
	v_fma_f32 v69, -v51, v68, v67
	v_fmac_f32_e32 v68, v69, v66
	v_fma_f32 v51, -v51, v68, v67
	v_div_fmas_f32 v51, v51, v66, v68
	v_div_fixup_f32 v50, v51, v50, 1.0
	v_cvt_pk_bf16_f32 v50, v50, v0
	v_mul_f32_e32 v0, 0xbfb8aa3b, v52
	v_exp_f32_e32 v52, v0
	v_mul_f32_e32 v0, 0xbfb8aa3b, v53
	v_exp_f32_e32 v53, v0
	s_nop 0
	v_pk_add_f32 v[52:53], v[52:53], 1.0 op_sel_hi:[1,0]
	s_nop 0
	v_div_scale_f32 v0, s[2:3], v53, v53, 1.0
	v_rcp_f32_e32 v51, v0
	s_nop 0
	v_fma_f32 v66, -v0, v51, 1.0
	v_fmac_f32_e32 v51, v66, v51
	v_div_scale_f32 v66, vcc, 1.0, v53, 1.0
	v_mul_f32_e32 v67, v66, v51
	v_fma_f32 v68, -v0, v67, v66
	v_fmac_f32_e32 v67, v68, v51
	v_fma_f32 v0, -v0, v67, v66
	v_div_fmas_f32 v0, v0, v51, v67
	v_div_scale_f32 v51, s[2:3], v52, v52, 1.0
	v_div_fixup_f32 v0, v0, v53, 1.0
	v_rcp_f32_e32 v53, v51
	s_nop 0
	v_fma_f32 v66, -v51, v53, 1.0
	v_fmac_f32_e32 v53, v66, v53
	v_div_scale_f32 v66, vcc, 1.0, v52, 1.0
	v_mul_f32_e32 v67, v66, v53
	v_fma_f32 v68, -v51, v67, v66
	v_fmac_f32_e32 v67, v68, v53
	v_fma_f32 v51, -v51, v67, v66
	v_div_fmas_f32 v51, v51, v53, v67
	v_div_fixup_f32 v51, v51, v52, 1.0
	v_cvt_pk_bf16_f32 v51, v51, v0
	v_mul_f32_e32 v0, 0xbfb8aa3b, v54
	v_exp_f32_e32 v52, v0
	v_mul_f32_e32 v0, 0xbfb8aa3b, v55
	v_exp_f32_e32 v53, v0
	s_nop 0
	v_pk_add_f32 v[52:53], v[52:53], 1.0 op_sel_hi:[1,0]
	s_nop 0
	v_div_scale_f32 v0, s[2:3], v53, v53, 1.0
	v_rcp_f32_e32 v54, v0
	s_nop 0
	v_fma_f32 v55, -v0, v54, 1.0
	v_fmac_f32_e32 v54, v55, v54
	v_div_scale_f32 v55, vcc, 1.0, v53, 1.0
	v_mul_f32_e32 v66, v55, v54
	v_fma_f32 v67, -v0, v66, v55
	v_fmac_f32_e32 v66, v67, v54
	v_fma_f32 v0, -v0, v66, v55
	v_div_fmas_f32 v0, v0, v54, v66
	v_div_fixup_f32 v0, v0, v53, 1.0
	v_div_scale_f32 v53, s[2:3], v52, v52, 1.0
	v_rcp_f32_e32 v54, v53
	s_nop 0
	v_fma_f32 v55, -v53, v54, 1.0
	v_fmac_f32_e32 v54, v55, v54
	v_div_scale_f32 v55, vcc, 1.0, v52, 1.0
	v_mul_f32_e32 v66, v55, v54
	v_fma_f32 v67, -v53, v66, v55
	v_fmac_f32_e32 v66, v67, v54
	v_fma_f32 v53, -v53, v66, v55
	v_div_fmas_f32 v53, v53, v54, v66
	v_div_fixup_f32 v52, v53, v52, 1.0
	v_cvt_pk_bf16_f32 v52, v52, v0
	v_mul_f32_e32 v0, 0xbfb8aa3b, v56
	v_exp_f32_e32 v54, v0
	v_mul_f32_e32 v0, 0xbfb8aa3b, v57
	v_exp_f32_e32 v55, v0
	s_nop 0
	v_pk_add_f32 v[54:55], v[54:55], 1.0 op_sel_hi:[1,0]
	s_nop 0
	v_div_scale_f32 v0, s[2:3], v55, v55, 1.0
	v_rcp_f32_e32 v53, v0
	s_nop 0
	v_fma_f32 v56, -v0, v53, 1.0
	v_fmac_f32_e32 v53, v56, v53
	v_div_scale_f32 v56, vcc, 1.0, v55, 1.0
	v_mul_f32_e32 v57, v56, v53
	v_fma_f32 v66, -v0, v57, v56
	v_fmac_f32_e32 v57, v66, v53
	v_fma_f32 v0, -v0, v57, v56
	v_div_fmas_f32 v0, v0, v53, v57
	v_div_scale_f32 v53, s[2:3], v54, v54, 1.0
	v_div_fixup_f32 v0, v0, v55, 1.0
	v_rcp_f32_e32 v55, v53
	s_nop 0
	v_fma_f32 v56, -v53, v55, 1.0
	v_fmac_f32_e32 v55, v56, v55
	v_div_scale_f32 v56, vcc, 1.0, v54, 1.0
	v_mul_f32_e32 v57, v56, v55
	v_fma_f32 v66, -v53, v57, v56
	v_fmac_f32_e32 v57, v66, v55
	v_fma_f32 v53, -v53, v57, v56
	v_div_fmas_f32 v53, v53, v55, v57
	v_div_fixup_f32 v53, v53, v54, 1.0
	v_cvt_pk_bf16_f32 v53, v53, v0
	v_mul_f32_e32 v0, 0xbfb8aa3b, v58
	ds_write2_b64 v192, v[50:51], v[52:53] offset0:128 offset1:130
	v_exp_f32_e32 v50, v0
	v_mul_f32_e32 v0, 0xbfb8aa3b, v59
	v_exp_f32_e32 v51, v0
	s_nop 0
	v_pk_add_f32 v[50:51], v[50:51], 1.0 op_sel_hi:[1,0]
	s_nop 0
	v_div_scale_f32 v0, s[2:3], v51, v51, 1.0
	v_rcp_f32_e32 v52, v0
	s_nop 0
	v_fma_f32 v53, -v0, v52, 1.0
	v_fmac_f32_e32 v52, v53, v52
	v_div_scale_f32 v53, vcc, 1.0, v51, 1.0
	v_mul_f32_e32 v54, v53, v52
	v_fma_f32 v55, -v0, v54, v53
	v_fmac_f32_e32 v54, v55, v52
	v_fma_f32 v0, -v0, v54, v53
	v_div_fmas_f32 v0, v0, v52, v54
	v_div_fixup_f32 v0, v0, v51, 1.0
	v_div_scale_f32 v51, s[2:3], v50, v50, 1.0
	v_rcp_f32_e32 v52, v51
	s_nop 0
	v_fma_f32 v53, -v51, v52, 1.0
	v_fmac_f32_e32 v52, v53, v52
	v_div_scale_f32 v53, vcc, 1.0, v50, 1.0
	v_mul_f32_e32 v54, v53, v52
	v_fma_f32 v55, -v51, v54, v53
	v_fmac_f32_e32 v54, v55, v52
	v_fma_f32 v51, -v51, v54, v53
	v_div_fmas_f32 v51, v51, v52, v54
	v_div_fixup_f32 v50, v51, v50, 1.0
	v_cvt_pk_bf16_f32 v50, v50, v0
	v_mul_f32_e32 v0, 0xbfb8aa3b, v60
	v_exp_f32_e32 v52, v0
	v_mul_f32_e32 v0, 0xbfb8aa3b, v61
	v_exp_f32_e32 v53, v0
	s_nop 0
	v_pk_add_f32 v[52:53], v[52:53], 1.0 op_sel_hi:[1,0]
	s_nop 0
	v_div_scale_f32 v0, s[2:3], v53, v53, 1.0
	v_rcp_f32_e32 v51, v0
	s_nop 0
	v_fma_f32 v54, -v0, v51, 1.0
	v_fmac_f32_e32 v51, v54, v51
	v_div_scale_f32 v54, vcc, 1.0, v53, 1.0
	v_mul_f32_e32 v55, v54, v51
	v_fma_f32 v56, -v0, v55, v54
	v_fmac_f32_e32 v55, v56, v51
	v_fma_f32 v0, -v0, v55, v54
	v_div_fmas_f32 v0, v0, v51, v55
	v_div_scale_f32 v51, s[2:3], v52, v52, 1.0
	v_div_fixup_f32 v0, v0, v53, 1.0
	v_rcp_f32_e32 v53, v51
	s_nop 0
	v_fma_f32 v54, -v51, v53, 1.0
	v_fmac_f32_e32 v53, v54, v53
	v_div_scale_f32 v54, vcc, 1.0, v52, 1.0
	v_mul_f32_e32 v55, v54, v53
	v_fma_f32 v56, -v51, v55, v54
	v_fmac_f32_e32 v55, v56, v53
; DI unsigned pk2(float a, float b) { f32v2 v = {a, b}; return __builtin_bit_cast(unsigned, __builtin_convertvector(v, bf16v2)); }
; #define SW_FOR_TOK(j) _Pragma("unroll") for (int j = 0; j < 4; j++)
; #define SW_FOR_FEAT(i, rq) _Pragma("unroll") for (int i = 0; i < 2; i++) _Pragma("unroll") for (int rq = 0; rq < 4; rq++)
; DI float sigmoidf_(float v) { return 1.f / (1.f + __expf(-v)); }
; DI void ph_ple(const Params& P, int g, int layer, bf16_t* smem) {
;     ...
;     SW_FOR_TOK(j) { const int tl_ = wn * 128 + j * 32 + l32;
;       SW_FOR_FEAT(i, rq) { const int c_ = wm * 64 + i * 32 + 8 * rq + 4 * h;
;         *(uint2*)(smem + tl_ * EPLD + c_) = make_uint2(pk2(sigmoidf_(SWV(i, j, 4 * rq)), sigmoidf_(SWV(i, j, 4 * rq + 1))), pk2(sigmoidf_(SWV(i, j, 4 * rq + 2)), sigmoidf_(SWV(i, j, 4 * rq + 3)))); } }
	v_fma_f32 v51, -v51, v55, v54
	v_div_fmas_f32 v51, v51, v53, v55
	v_div_fixup_f32 v51, v51, v52, 1.0
	v_cvt_pk_bf16_f32 v51, v51, v0
	v_mul_f32_e32 v0, 0xbfb8aa3b, v62
	v_exp_f32_e32 v52, v0
	v_mul_f32_e32 v0, 0xbfb8aa3b, v63
	v_exp_f32_e32 v53, v0
	s_nop 0
	v_pk_add_f32 v[52:53], v[52:53], 1.0 op_sel_hi:[1,0]
	s_nop 0
	v_div_scale_f32 v0, s[2:3], v53, v53, 1.0
	v_rcp_f32_e32 v54, v0
	s_nop 0
	v_fma_f32 v55, -v0, v54, 1.0
	v_fmac_f32_e32 v54, v55, v54
	v_div_scale_f32 v55, vcc, 1.0, v53, 1.0
	v_mul_f32_e32 v56, v55, v54
	v_fma_f32 v57, -v0, v56, v55
	v_fmac_f32_e32 v56, v57, v54
	v_fma_f32 v0, -v0, v56, v55
	v_div_fmas_f32 v0, v0, v54, v56
	v_div_fixup_f32 v0, v0, v53, 1.0
	v_div_scale_f32 v53, s[2:3], v52, v52, 1.0
	v_rcp_f32_e32 v54, v53
	s_nop 0
	v_fma_f32 v55, -v53, v54, 1.0
	v_fmac_f32_e32 v54, v55, v54
	v_div_scale_f32 v55, vcc, 1.0, v52, 1.0
	v_mul_f32_e32 v56, v55, v54
	v_fma_f32 v57, -v53, v56, v55
	v_fmac_f32_e32 v56, v57, v54
	v_fma_f32 v53, -v53, v56, v55
	v_div_fmas_f32 v53, v53, v54, v56
	v_div_fixup_f32 v52, v53, v52, 1.0
	v_cvt_pk_bf16_f32 v52, v52, v0
	v_mul_f32_e32 v0, 0xbfb8aa3b, v64
	v_exp_f32_e32 v54, v0
	v_mul_f32_e32 v0, 0xbfb8aa3b, v65
	v_exp_f32_e32 v55, v0
	s_nop 0
	v_pk_add_f32 v[54:55], v[54:55], 1.0 op_sel_hi:[1,0]
	s_nop 0
	v_div_scale_f32 v0, s[2:3], v55, v55, 1.0
	v_rcp_f32_e32 v53, v0
	s_nop 0
	v_fma_f32 v56, -v0, v53, 1.0
	v_fmac_f32_e32 v53, v56, v53
	v_div_scale_f32 v56, vcc, 1.0, v55, 1.0
	v_mul_f32_e32 v57, v56, v53
	v_fma_f32 v58, -v0, v57, v56
	v_fmac_f32_e32 v57, v58, v53
	v_fma_f32 v0, -v0, v57, v56
	v_div_fmas_f32 v0, v0, v53, v57
	v_div_scale_f32 v53, s[2:3], v54, v54, 1.0
	v_div_fixup_f32 v0, v0, v55, 1.0
	v_rcp_f32_e32 v55, v53
	s_nop 0
	v_fma_f32 v56, -v53, v55, 1.0
	v_fmac_f32_e32 v55, v56, v55
	v_div_scale_f32 v56, vcc, 1.0, v54, 1.0
	v_mul_f32_e32 v57, v56, v55
	v_fma_f32 v58, -v53, v57, v56
	v_fmac_f32_e32 v57, v58, v55
	v_fma_f32 v53, -v53, v57, v56
	v_div_fmas_f32 v53, v53, v55, v57
	v_div_fixup_f32 v53, v53, v54, 1.0
	v_cvt_pk_bf16_f32 v53, v53, v0
	v_mul_f32_e32 v0, 0xbfb8aa3b, v34
	v_exp_f32_e32 v34, v0
	v_mul_f32_e32 v0, 0xbfb8aa3b, v35
	v_exp_f32_e32 v35, v0
	ds_write2_b64 v192, v[50:51], v[52:53] offset0:132 offset1:134
	v_pk_add_f32 v[34:35], v[34:35], 1.0 op_sel_hi:[1,0]
	s_nop 0
	v_div_scale_f32 v0, s[2:3], v35, v35, 1.0
	v_rcp_f32_e32 v50, v0
	s_nop 0
	v_fma_f32 v51, -v0, v50, 1.0
	v_fmac_f32_e32 v50, v51, v50
	v_div_scale_f32 v51, vcc, 1.0, v35, 1.0
	v_mul_f32_e32 v52, v51, v50
	v_fma_f32 v53, -v0, v52, v51
	v_fmac_f32_e32 v52, v53, v50
	v_fma_f32 v0, -v0, v52, v51
	v_div_fmas_f32 v0, v0, v50, v52
	v_div_fixup_f32 v0, v0, v35, 1.0
	v_div_scale_f32 v35, s[2:3], v34, v34, 1.0
	v_rcp_f32_e32 v50, v35
	s_nop 0
	v_fma_f32 v51, -v35, v50, 1.0
	v_fmac_f32_e32 v50, v51, v50
	v_div_scale_f32 v51, vcc, 1.0, v34, 1.0
	v_mul_f32_e32 v52, v51, v50
	v_fma_f32 v53, -v35, v52, v51
	v_fmac_f32_e32 v52, v53, v50
	v_fma_f32 v35, -v35, v52, v51
	v_div_fmas_f32 v35, v35, v50, v52
	v_div_fixup_f32 v34, v35, v34, 1.0
	v_cvt_pk_bf16_f32 v34, v34, v0
	v_mul_f32_e32 v0, 0xbfb8aa3b, v36
	v_exp_f32_e32 v36, v0
	v_mul_f32_e32 v0, 0xbfb8aa3b, v37
	v_exp_f32_e32 v37, v0
	s_nop 0
	v_pk_add_f32 v[36:37], v[36:37], 1.0 op_sel_hi:[1,0]
	s_nop 0
	v_div_scale_f32 v0, s[2:3], v37, v37, 1.0
	v_rcp_f32_e32 v35, v0
	s_nop 0
	v_fma_f32 v50, -v0, v35, 1.0
	v_fmac_f32_e32 v35, v50, v35
	v_div_scale_f32 v50, vcc, 1.0, v37, 1.0
	v_mul_f32_e32 v51, v50, v35
	v_fma_f32 v52, -v0, v51, v50
	v_fmac_f32_e32 v51, v52, v35
	v_fma_f32 v0, -v0, v51, v50
	v_div_fmas_f32 v0, v0, v35, v51
	v_div_scale_f32 v35, s[2:3], v36, v36, 1.0
	v_div_fixup_f32 v0, v0, v37, 1.0
	v_rcp_f32_e32 v37, v35
	s_nop 0
	v_fma_f32 v50, -v35, v37, 1.0
	v_fmac_f32_e32 v37, v50, v37
	v_div_scale_f32 v50, vcc, 1.0, v36, 1.0
	v_mul_f32_e32 v51, v50, v37
	v_fma_f32 v52, -v35, v51, v50
	v_fmac_f32_e32 v51, v52, v37
	v_fma_f32 v35, -v35, v51, v50
	v_div_fmas_f32 v35, v35, v37, v51
	v_div_fixup_f32 v35, v35, v36, 1.0
	v_cvt_pk_bf16_f32 v35, v35, v0
	v_mul_f32_e32 v0, 0xbfb8aa3b, v38
	v_exp_f32_e32 v36, v0
	v_mul_f32_e32 v0, 0xbfb8aa3b, v39
	v_exp_f32_e32 v37, v0
	s_nop 0
	v_pk_add_f32 v[36:37], v[36:37], 1.0 op_sel_hi:[1,0]
	s_nop 0
	v_div_scale_f32 v0, s[2:3], v37, v37, 1.0
	v_rcp_f32_e32 v38, v0
	s_nop 0
	v_fma_f32 v39, -v0, v38, 1.0
	v_fmac_f32_e32 v38, v39, v38
	v_div_scale_f32 v39, vcc, 1.0, v37, 1.0
	v_mul_f32_e32 v50, v39, v38
	v_fma_f32 v51, -v0, v50, v39
	v_fmac_f32_e32 v50, v51, v38
	v_fma_f32 v0, -v0, v50, v39
	v_div_fmas_f32 v0, v0, v38, v50
	v_div_fixup_f32 v0, v0, v37, 1.0
	v_div_scale_f32 v37, s[2:3], v36, v36, 1.0
	v_rcp_f32_e32 v38, v37
	s_nop 0
	v_fma_f32 v39, -v37, v38, 1.0
	v_fmac_f32_e32 v38, v39, v38
	v_div_scale_f32 v39, vcc, 1.0, v36, 1.0
	v_mul_f32_e32 v50, v39, v38
	v_fma_f32 v51, -v37, v50, v39
	v_fmac_f32_e32 v50, v51, v38
	v_fma_f32 v37, -v37, v50, v39
	v_div_fmas_f32 v37, v37, v38, v50
	v_div_fixup_f32 v36, v37, v36, 1.0
	v_cvt_pk_bf16_f32 v36, v36, v0
	v_mul_f32_e32 v0, 0xbfb8aa3b, v40
	v_exp_f32_e32 v38, v0
	v_mul_f32_e32 v0, 0xbfb8aa3b, v41
	v_exp_f32_e32 v39, v0
	s_nop 0
	v_pk_add_f32 v[38:39], v[38:39], 1.0 op_sel_hi:[1,0]
	s_nop 0
	v_div_scale_f32 v0, s[2:3], v39, v39, 1.0
	v_rcp_f32_e32 v37, v0
	s_nop 0
	v_fma_f32 v40, -v0, v37, 1.0
	v_fmac_f32_e32 v37, v40, v37
	v_div_scale_f32 v40, vcc, 1.0, v39, 1.0
	v_mul_f32_e32 v41, v40, v37
	v_fma_f32 v50, -v0, v41, v40
	v_fmac_f32_e32 v41, v50, v37
	v_fma_f32 v0, -v0, v41, v40
	v_div_fmas_f32 v0, v0, v37, v41
	v_div_scale_f32 v37, s[2:3], v38, v38, 1.0
	v_div_fixup_f32 v0, v0, v39, 1.0
	v_rcp_f32_e32 v39, v37
	s_nop 0
	v_fma_f32 v40, -v37, v39, 1.0
	v_fmac_f32_e32 v39, v40, v39
; DI unsigned pk2(float a, float b) { f32v2 v = {a, b}; return __builtin_bit_cast(unsigned, __builtin_convertvector(v, bf16v2)); }
; #define SW_FOR_TOK(j) _Pragma("unroll") for (int j = 0; j < 4; j++)
; #define SW_FOR_FEAT(i, rq) _Pragma("unroll") for (int i = 0; i < 2; i++) _Pragma("unroll") for (int rq = 0; rq < 4; rq++)
; DI float sigmoidf_(float v) { return 1.f / (1.f + __expf(-v)); }
; DI void ph_ple(const Params& P, int g, int layer, bf16_t* smem) {
;     ...
;     SW_FOR_TOK(j) { const int tl_ = wn * 128 + j * 32 + l32;
;       SW_FOR_FEAT(i, rq) { const int c_ = wm * 64 + i * 32 + 8 * rq + 4 * h;
;         *(uint2*)(smem + tl_ * EPLD + c_) = make_uint2(pk2(sigmoidf_(SWV(i, j, 4 * rq)), sigmoidf_(SWV(i, j, 4 * rq + 1))), pk2(sigmoidf_(SWV(i, j, 4 * rq + 2)), sigmoidf_(SWV(i, j, 4 * rq + 3)))); } }
	v_div_scale_f32 v40, vcc, 1.0, v38, 1.0
	v_mul_f32_e32 v41, v40, v39
	v_fma_f32 v50, -v37, v41, v40
	v_fmac_f32_e32 v41, v50, v39
	v_fma_f32 v37, -v37, v41, v40
	v_div_fmas_f32 v37, v37, v39, v41
	v_div_fixup_f32 v37, v37, v38, 1.0
	v_cvt_pk_bf16_f32 v37, v37, v0
	v_mul_f32_e32 v0, 0xbfb8aa3b, v42
	ds_write2_b64 v192, v[34:35], v[36:37] offset0:136 offset1:138
	v_exp_f32_e32 v34, v0
	v_mul_f32_e32 v0, 0xbfb8aa3b, v43
	v_exp_f32_e32 v35, v0
	s_nop 0
	v_pk_add_f32 v[34:35], v[34:35], 1.0 op_sel_hi:[1,0]
	s_nop 0
	v_div_scale_f32 v0, s[2:3], v35, v35, 1.0
	v_rcp_f32_e32 v36, v0
	s_nop 0
	v_fma_f32 v37, -v0, v36, 1.0
	v_fmac_f32_e32 v36, v37, v36
	v_div_scale_f32 v37, vcc, 1.0, v35, 1.0
	v_mul_f32_e32 v38, v37, v36
	v_fma_f32 v39, -v0, v38, v37
	v_fmac_f32_e32 v38, v39, v36
	v_fma_f32 v0, -v0, v38, v37
	v_div_fmas_f32 v0, v0, v36, v38
	v_div_fixup_f32 v0, v0, v35, 1.0
	v_div_scale_f32 v35, s[2:3], v34, v34, 1.0
	v_rcp_f32_e32 v36, v35
	s_nop 0
	v_fma_f32 v37, -v35, v36, 1.0
	v_fmac_f32_e32 v36, v37, v36
	v_div_scale_f32 v37, vcc, 1.0, v34, 1.0
	v_mul_f32_e32 v38, v37, v36
	v_fma_f32 v39, -v35, v38, v37
	v_fmac_f32_e32 v38, v39, v36
	v_fma_f32 v35, -v35, v38, v37
	v_div_fmas_f32 v35, v35, v36, v38
	v_div_fixup_f32 v34, v35, v34, 1.0
	v_cvt_pk_bf16_f32 v34, v34, v0
	v_mul_f32_e32 v0, 0xbfb8aa3b, v44
	v_exp_f32_e32 v36, v0
	v_mul_f32_e32 v0, 0xbfb8aa3b, v45
	v_exp_f32_e32 v37, v0
	s_nop 0
	v_pk_add_f32 v[36:37], v[36:37], 1.0 op_sel_hi:[1,0]
	s_nop 0
	v_div_scale_f32 v0, s[2:3], v37, v37, 1.0
	v_rcp_f32_e32 v35, v0
	s_nop 0
	v_fma_f32 v38, -v0, v35, 1.0
	v_fmac_f32_e32 v35, v38, v35
	v_div_scale_f32 v38, vcc, 1.0, v37, 1.0
	v_mul_f32_e32 v39, v38, v35
	v_fma_f32 v40, -v0, v39, v38
	v_fmac_f32_e32 v39, v40, v35
	v_fma_f32 v0, -v0, v39, v38
	v_div_fmas_f32 v0, v0, v35, v39
	v_div_scale_f32 v35, s[2:3], v36, v36, 1.0
	v_div_fixup_f32 v0, v0, v37, 1.0
	v_rcp_f32_e32 v37, v35
	s_nop 0
	v_fma_f32 v38, -v35, v37, 1.0
	v_fmac_f32_e32 v37, v38, v37
	v_div_scale_f32 v38, vcc, 1.0, v36, 1.0
	v_mul_f32_e32 v39, v38, v37
	v_fma_f32 v40, -v35, v39, v38
	v_fmac_f32_e32 v39, v40, v37
	v_fma_f32 v35, -v35, v39, v38
	v_div_fmas_f32 v35, v35, v37, v39
	v_div_fixup_f32 v35, v35, v36, 1.0
	v_cvt_pk_bf16_f32 v35, v35, v0
	v_mul_f32_e32 v0, 0xbfb8aa3b, v46
	v_exp_f32_e32 v36, v0
	v_mul_f32_e32 v0, 0xbfb8aa3b, v47
	v_exp_f32_e32 v37, v0
	s_nop 0
	v_pk_add_f32 v[36:37], v[36:37], 1.0 op_sel_hi:[1,0]
	s_nop 0
	v_div_scale_f32 v0, s[2:3], v37, v37, 1.0
	v_rcp_f32_e32 v38, v0
	s_nop 0
	v_fma_f32 v39, -v0, v38, 1.0
	v_fmac_f32_e32 v38, v39, v38
	v_div_scale_f32 v39, vcc, 1.0, v37, 1.0
	v_mul_f32_e32 v40, v39, v38
	v_fma_f32 v41, -v0, v40, v39
	v_fmac_f32_e32 v40, v41, v38
	v_fma_f32 v0, -v0, v40, v39
	v_div_fmas_f32 v0, v0, v38, v40
	v_div_fixup_f32 v0, v0, v37, 1.0
	v_div_scale_f32 v37, s[2:3], v36, v36, 1.0
	v_rcp_f32_e32 v38, v37
	s_nop 0
	v_fma_f32 v39, -v37, v38, 1.0
	v_fmac_f32_e32 v38, v39, v38
	v_div_scale_f32 v39, vcc, 1.0, v36, 1.0
	v_mul_f32_e32 v40, v39, v38
	v_fma_f32 v41, -v37, v40, v39
	v_fmac_f32_e32 v40, v41, v38
	v_fma_f32 v37, -v37, v40, v39
	v_div_fmas_f32 v37, v37, v38, v40
	v_div_fixup_f32 v36, v37, v36, 1.0
	v_cvt_pk_bf16_f32 v36, v36, v0
	v_mul_f32_e32 v0, 0xbfb8aa3b, v48
	v_exp_f32_e32 v38, v0
	v_mul_f32_e32 v0, 0xbfb8aa3b, v49
	v_exp_f32_e32 v39, v0
	s_nop 0
	v_pk_add_f32 v[38:39], v[38:39], 1.0 op_sel_hi:[1,0]
	s_nop 0
	v_div_scale_f32 v0, s[2:3], v39, v39, 1.0
	v_rcp_f32_e32 v37, v0
	s_nop 0
	v_fma_f32 v40, -v0, v37, 1.0
	v_fmac_f32_e32 v37, v40, v37
	v_div_scale_f32 v40, vcc, 1.0, v39, 1.0
	v_mul_f32_e32 v41, v40, v37
	v_fma_f32 v42, -v0, v41, v40
	v_fmac_f32_e32 v41, v42, v37
	v_fma_f32 v0, -v0, v41, v40
	v_div_fmas_f32 v0, v0, v37, v41
	v_div_scale_f32 v37, s[2:3], v38, v38, 1.0
	v_div_fixup_f32 v0, v0, v39, 1.0
	v_rcp_f32_e32 v39, v37
	s_nop 0
	v_fma_f32 v40, -v37, v39, 1.0
	v_fmac_f32_e32 v39, v40, v39
	v_div_scale_f32 v40, vcc, 1.0, v38, 1.0
	v_mul_f32_e32 v41, v40, v39
	v_fma_f32 v42, -v37, v41, v40
	v_fmac_f32_e32 v41, v42, v39
	v_fma_f32 v37, -v37, v41, v40
	v_div_fmas_f32 v37, v37, v39, v41
	v_div_fixup_f32 v37, v37, v38, 1.0
	v_cvt_pk_bf16_f32 v37, v37, v0
	v_mul_f32_e32 v0, 0xbfb8aa3b, v18
	v_exp_f32_e32 v18, v0
	v_mul_f32_e32 v0, 0xbfb8aa3b, v19
	v_exp_f32_e32 v19, v0
	ds_write2_b64 v192, v[34:35], v[36:37] offset0:140 offset1:142
	v_pk_add_f32 v[18:19], v[18:19], 1.0 op_sel_hi:[1,0]
	s_nop 0
	v_div_scale_f32 v0, s[2:3], v19, v19, 1.0
	v_rcp_f32_e32 v34, v0
	s_nop 0
	v_fma_f32 v35, -v0, v34, 1.0
	v_fmac_f32_e32 v34, v35, v34
	v_div_scale_f32 v35, vcc, 1.0, v19, 1.0
	v_mul_f32_e32 v36, v35, v34
	v_fma_f32 v37, -v0, v36, v35
	v_fmac_f32_e32 v36, v37, v34
	v_fma_f32 v0, -v0, v36, v35
	v_div_fmas_f32 v0, v0, v34, v36
	v_div_fixup_f32 v0, v0, v19, 1.0
	v_div_scale_f32 v19, s[2:3], v18, v18, 1.0
	v_rcp_f32_e32 v34, v19
	s_nop 0
	v_fma_f32 v35, -v19, v34, 1.0
	v_fmac_f32_e32 v34, v35, v34
	v_div_scale_f32 v35, vcc, 1.0, v18, 1.0
	v_mul_f32_e32 v36, v35, v34
	v_fma_f32 v37, -v19, v36, v35
	v_fmac_f32_e32 v36, v37, v34
	v_fma_f32 v19, -v19, v36, v35
	v_div_fmas_f32 v19, v19, v34, v36
	v_div_fixup_f32 v18, v19, v18, 1.0
	v_cvt_pk_bf16_f32 v18, v18, v0
	v_mul_f32_e32 v0, 0xbfb8aa3b, v20
	v_exp_f32_e32 v20, v0
	v_mul_f32_e32 v0, 0xbfb8aa3b, v21
	v_exp_f32_e32 v21, v0
	s_nop 0
	v_pk_add_f32 v[20:21], v[20:21], 1.0 op_sel_hi:[1,0]
	s_nop 0
	v_div_scale_f32 v0, s[2:3], v21, v21, 1.0
	v_rcp_f32_e32 v19, v0
	s_nop 0
	v_fma_f32 v34, -v0, v19, 1.0
	v_fmac_f32_e32 v19, v34, v19
	v_div_scale_f32 v34, vcc, 1.0, v21, 1.0
	v_mul_f32_e32 v35, v34, v19
	v_fma_f32 v36, -v0, v35, v34
	v_fmac_f32_e32 v35, v36, v19
	v_fma_f32 v0, -v0, v35, v34
; DI unsigned pk2(float a, float b) { f32v2 v = {a, b}; return __builtin_bit_cast(unsigned, __builtin_convertvector(v, bf16v2)); }
; #define SW_FOR_TOK(j) _Pragma("unroll") for (int j = 0; j < 4; j++)
; #define SW_FOR_FEAT(i, rq) _Pragma("unroll") for (int i = 0; i < 2; i++) _Pragma("unroll") for (int rq = 0; rq < 4; rq++)
; DI float sigmoidf_(float v) { return 1.f / (1.f + __expf(-v)); }
; DI void ph_ple(const Params& P, int g, int layer, bf16_t* smem) {
;     ...
;     SW_FOR_TOK(j) { const int tl_ = wn * 128 + j * 32 + l32;
;       SW_FOR_FEAT(i, rq) { const int c_ = wm * 64 + i * 32 + 8 * rq + 4 * h;
;         *(uint2*)(smem + tl_ * EPLD + c_) = make_uint2(pk2(sigmoidf_(SWV(i, j, 4 * rq)), sigmoidf_(SWV(i, j, 4 * rq + 1))), pk2(sigmoidf_(SWV(i, j, 4 * rq + 2)), sigmoidf_(SWV(i, j, 4 * rq + 3)))); } }
	v_div_fmas_f32 v0, v0, v19, v35
	v_div_scale_f32 v19, s[2:3], v20, v20, 1.0
	v_div_fixup_f32 v0, v0, v21, 1.0
	v_rcp_f32_e32 v21, v19
	s_nop 0
	v_fma_f32 v34, -v19, v21, 1.0
	v_fmac_f32_e32 v21, v34, v21
	v_div_scale_f32 v34, vcc, 1.0, v20, 1.0
	v_mul_f32_e32 v35, v34, v21
	v_fma_f32 v36, -v19, v35, v34
	v_fmac_f32_e32 v35, v36, v21
	v_fma_f32 v19, -v19, v35, v34
	v_div_fmas_f32 v19, v19, v21, v35
	v_div_fixup_f32 v19, v19, v20, 1.0
	v_cvt_pk_bf16_f32 v19, v19, v0
	v_mul_f32_e32 v0, 0xbfb8aa3b, v22
	v_exp_f32_e32 v20, v0
	v_mul_f32_e32 v0, 0xbfb8aa3b, v23
	v_exp_f32_e32 v21, v0
	s_nop 0
	v_pk_add_f32 v[20:21], v[20:21], 1.0 op_sel_hi:[1,0]
	s_nop 0
	v_div_scale_f32 v0, s[2:3], v21, v21, 1.0
	v_rcp_f32_e32 v22, v0
	s_nop 0
	v_fma_f32 v23, -v0, v22, 1.0
	v_fmac_f32_e32 v22, v23, v22
	v_div_scale_f32 v23, vcc, 1.0, v21, 1.0
	v_mul_f32_e32 v34, v23, v22
	v_fma_f32 v35, -v0, v34, v23
	v_fmac_f32_e32 v34, v35, v22
	v_fma_f32 v0, -v0, v34, v23
	v_div_fmas_f32 v0, v0, v22, v34
	v_div_fixup_f32 v0, v0, v21, 1.0
	v_div_scale_f32 v21, s[2:3], v20, v20, 1.0
	v_rcp_f32_e32 v22, v21
	s_nop 0
	v_fma_f32 v23, -v21, v22, 1.0
	v_fmac_f32_e32 v22, v23, v22
	v_div_scale_f32 v23, vcc, 1.0, v20, 1.0
	v_mul_f32_e32 v34, v23, v22
	v_fma_f32 v35, -v21, v34, v23
	v_fmac_f32_e32 v34, v35, v22
	v_fma_f32 v21, -v21, v34, v23
	v_div_fmas_f32 v21, v21, v22, v34
	v_div_fixup_f32 v20, v21, v20, 1.0
	v_cvt_pk_bf16_f32 v20, v20, v0
	v_mul_f32_e32 v0, 0xbfb8aa3b, v24
	v_exp_f32_e32 v22, v0
	v_mul_f32_e32 v0, 0xbfb8aa3b, v25
	v_exp_f32_e32 v23, v0
	s_nop 0
	v_pk_add_f32 v[22:23], v[22:23], 1.0 op_sel_hi:[1,0]
	s_nop 0
	v_div_scale_f32 v0, s[2:3], v23, v23, 1.0
	v_rcp_f32_e32 v21, v0
	s_nop 0
	v_fma_f32 v24, -v0, v21, 1.0
	v_fmac_f32_e32 v21, v24, v21
	v_div_scale_f32 v24, vcc, 1.0, v23, 1.0
	v_mul_f32_e32 v25, v24, v21
	v_fma_f32 v34, -v0, v25, v24
	v_fmac_f32_e32 v25, v34, v21
	v_fma_f32 v0, -v0, v25, v24
	v_div_fmas_f32 v0, v0, v21, v25
	v_div_scale_f32 v21, s[2:3], v22, v22, 1.0
	v_div_fixup_f32 v0, v0, v23, 1.0
	v_rcp_f32_e32 v23, v21
	s_nop 0
	v_fma_f32 v24, -v21, v23, 1.0
	v_fmac_f32_e32 v23, v24, v23
	v_div_scale_f32 v24, vcc, 1.0, v22, 1.0
	v_mul_f32_e32 v25, v24, v23
	v_fma_f32 v34, -v21, v25, v24
	v_fmac_f32_e32 v25, v34, v23
	v_fma_f32 v21, -v21, v25, v24
	v_div_fmas_f32 v21, v21, v23, v25
	v_div_fixup_f32 v21, v21, v22, 1.0
	v_cvt_pk_bf16_f32 v21, v21, v0
	v_mul_f32_e32 v0, 0xbfb8aa3b, v26
	ds_write2_b64 v191, v[18:19], v[20:21] offset0:192 offset1:194
	v_exp_f32_e32 v18, v0
	v_mul_f32_e32 v0, 0xbfb8aa3b, v27
	v_exp_f32_e32 v19, v0
	s_nop 0
	v_pk_add_f32 v[18:19], v[18:19], 1.0 op_sel_hi:[1,0]
	s_nop 0
	v_div_scale_f32 v0, s[2:3], v19, v19, 1.0
	v_rcp_f32_e32 v20, v0
	s_nop 0
	v_fma_f32 v21, -v0, v20, 1.0
	v_fmac_f32_e32 v20, v21, v20
	v_div_scale_f32 v21, vcc, 1.0, v19, 1.0
	v_mul_f32_e32 v22, v21, v20
	v_fma_f32 v23, -v0, v22, v21
	v_fmac_f32_e32 v22, v23, v20
	v_fma_f32 v0, -v0, v22, v21
	v_div_fmas_f32 v0, v0, v20, v22
	v_div_fixup_f32 v0, v0, v19, 1.0
	v_div_scale_f32 v19, s[2:3], v18, v18, 1.0
	v_rcp_f32_e32 v20, v19
	s_nop 0
	v_fma_f32 v21, -v19, v20, 1.0
	v_fmac_f32_e32 v20, v21, v20
	v_div_scale_f32 v21, vcc, 1.0, v18, 1.0
	v_mul_f32_e32 v22, v21, v20
	v_fma_f32 v23, -v19, v22, v21
	v_fmac_f32_e32 v22, v23, v20
	v_fma_f32 v19, -v19, v22, v21
	v_div_fmas_f32 v19, v19, v20, v22
	v_div_fixup_f32 v18, v19, v18, 1.0
	v_cvt_pk_bf16_f32 v18, v18, v0
	v_mul_f32_e32 v0, 0xbfb8aa3b, v28
	v_exp_f32_e32 v20, v0
	v_mul_f32_e32 v0, 0xbfb8aa3b, v29
	v_exp_f32_e32 v21, v0
	s_nop 0
	v_pk_add_f32 v[20:21], v[20:21], 1.0 op_sel_hi:[1,0]
	s_nop 0
	v_div_scale_f32 v0, s[2:3], v21, v21, 1.0
	v_rcp_f32_e32 v19, v0
	s_nop 0
	v_fma_f32 v22, -v0, v19, 1.0
	v_fmac_f32_e32 v19, v22, v19
	v_div_scale_f32 v22, vcc, 1.0, v21, 1.0
	v_mul_f32_e32 v23, v22, v19
	v_fma_f32 v24, -v0, v23, v22
	v_fmac_f32_e32 v23, v24, v19
	v_fma_f32 v0, -v0, v23, v22
	v_div_fmas_f32 v0, v0, v19, v23
	v_div_scale_f32 v19, s[2:3], v20, v20, 1.0
	v_div_fixup_f32 v0, v0, v21, 1.0
	v_rcp_f32_e32 v21, v19
	s_nop 0
	v_fma_f32 v22, -v19, v21, 1.0
	v_fmac_f32_e32 v21, v22, v21
	v_div_scale_f32 v22, vcc, 1.0, v20, 1.0
	v_mul_f32_e32 v23, v22, v21
	v_fma_f32 v24, -v19, v23, v22
	v_fmac_f32_e32 v23, v24, v21
	v_fma_f32 v19, -v19, v23, v22
	v_div_fmas_f32 v19, v19, v21, v23
	v_div_fixup_f32 v19, v19, v20, 1.0
	v_cvt_pk_bf16_f32 v19, v19, v0
	v_mul_f32_e32 v0, 0xbfb8aa3b, v30
	v_exp_f32_e32 v20, v0
	v_mul_f32_e32 v0, 0xbfb8aa3b, v31
	v_exp_f32_e32 v21, v0
	s_nop 0
	v_pk_add_f32 v[20:21], v[20:21], 1.0 op_sel_hi:[1,0]
	s_nop 0
	v_div_scale_f32 v0, s[2:3], v21, v21, 1.0
	v_rcp_f32_e32 v22, v0
	s_nop 0
	v_fma_f32 v23, -v0, v22, 1.0
	v_fmac_f32_e32 v22, v23, v22
	v_div_scale_f32 v23, vcc, 1.0, v21, 1.0
	v_mul_f32_e32 v24, v23, v22
	v_fma_f32 v25, -v0, v24, v23
	v_fmac_f32_e32 v24, v25, v22
	v_fma_f32 v0, -v0, v24, v23
	v_div_fmas_f32 v0, v0, v22, v24
	v_div_fixup_f32 v0, v0, v21, 1.0
	v_div_scale_f32 v21, s[2:3], v20, v20, 1.0
	v_rcp_f32_e32 v22, v21
	s_nop 0
	v_fma_f32 v23, -v21, v22, 1.0
	v_fmac_f32_e32 v22, v23, v22
	v_div_scale_f32 v23, vcc, 1.0, v20, 1.0
	v_mul_f32_e32 v24, v23, v22
	v_fma_f32 v25, -v21, v24, v23
	v_fmac_f32_e32 v24, v25, v22
	v_fma_f32 v21, -v21, v24, v23
	v_div_fmas_f32 v21, v21, v22, v24
	v_div_fixup_f32 v20, v21, v20, 1.0
	v_cvt_pk_bf16_f32 v20, v20, v0
	v_mul_f32_e32 v0, 0xbfb8aa3b, v32
	v_exp_f32_e32 v22, v0
	v_mul_f32_e32 v0, 0xbfb8aa3b, v33
	v_exp_f32_e32 v23, v0
	s_nop 0
	v_pk_add_f32 v[22:23], v[22:23], 1.0 op_sel_hi:[1,0]
	s_nop 0
	v_div_scale_f32 v0, s[2:3], v23, v23, 1.0
	v_rcp_f32_e32 v21, v0
	s_nop 0
	v_fma_f32 v24, -v0, v21, 1.0
	v_fmac_f32_e32 v21, v24, v21
	v_div_scale_f32 v24, vcc, 1.0, v23, 1.0
; DI unsigned pk2(float a, float b) { f32v2 v = {a, b}; return __builtin_bit_cast(unsigned, __builtin_convertvector(v, bf16v2)); }
; #define SW_FOR_TOK(j) _Pragma("unroll") for (int j = 0; j < 4; j++)
; #define SW_FOR_FEAT(i, rq) _Pragma("unroll") for (int i = 0; i < 2; i++) _Pragma("unroll") for (int rq = 0; rq < 4; rq++)
; DI float sigmoidf_(float v) { return 1.f / (1.f + __expf(-v)); }
; DI void ph_ple(const Params& P, int g, int layer, bf16_t* smem) {
;     ...
;     SW_FOR_TOK(j) { const int tl_ = wn * 128 + j * 32 + l32;
;       SW_FOR_FEAT(i, rq) { const int c_ = wm * 64 + i * 32 + 8 * rq + 4 * h;
;         *(uint2*)(smem + tl_ * EPLD + c_) = make_uint2(pk2(sigmoidf_(SWV(i, j, 4 * rq)), sigmoidf_(SWV(i, j, 4 * rq + 1))), pk2(sigmoidf_(SWV(i, j, 4 * rq + 2)), sigmoidf_(SWV(i, j, 4 * rq + 3)))); } }
	v_mul_f32_e32 v25, v24, v21
	v_fma_f32 v26, -v0, v25, v24
	v_fmac_f32_e32 v25, v26, v21
	v_fma_f32 v0, -v0, v25, v24
	v_div_fmas_f32 v0, v0, v21, v25
	v_div_scale_f32 v21, s[2:3], v22, v22, 1.0
	v_div_fixup_f32 v0, v0, v23, 1.0
	v_rcp_f32_e32 v23, v21
	s_nop 0
	v_fma_f32 v24, -v21, v23, 1.0
	v_fmac_f32_e32 v23, v24, v23
	v_div_scale_f32 v24, vcc, 1.0, v22, 1.0
	v_mul_f32_e32 v25, v24, v23
	v_fma_f32 v26, -v21, v25, v24
	v_fmac_f32_e32 v25, v26, v23
	v_fma_f32 v21, -v21, v25, v24
	v_div_fmas_f32 v21, v21, v23, v25
	v_div_fixup_f32 v21, v21, v22, 1.0
	v_cvt_pk_bf16_f32 v21, v21, v0
	v_mul_f32_e32 v0, 0xbfb8aa3b, v2
	v_exp_f32_e32 v2, v0
	v_mul_f32_e32 v0, 0xbfb8aa3b, v3
	v_exp_f32_e32 v3, v0
	ds_write2_b64 v191, v[18:19], v[20:21] offset0:196 offset1:198
	v_pk_add_f32 v[2:3], v[2:3], 1.0 op_sel_hi:[1,0]
	s_nop 0
	v_div_scale_f32 v0, s[2:3], v3, v3, 1.0
	v_rcp_f32_e32 v18, v0
	s_nop 0
	v_fma_f32 v19, -v0, v18, 1.0
	v_fmac_f32_e32 v18, v19, v18
	v_div_scale_f32 v19, vcc, 1.0, v3, 1.0
	v_mul_f32_e32 v20, v19, v18
	v_fma_f32 v21, -v0, v20, v19
	v_fmac_f32_e32 v20, v21, v18
	v_fma_f32 v0, -v0, v20, v19
	v_div_fmas_f32 v0, v0, v18, v20
	v_div_fixup_f32 v0, v0, v3, 1.0
	v_div_scale_f32 v3, s[2:3], v2, v2, 1.0
	v_rcp_f32_e32 v18, v3
	s_nop 0
	v_fma_f32 v19, -v3, v18, 1.0
	v_fmac_f32_e32 v18, v19, v18
	v_div_scale_f32 v19, vcc, 1.0, v2, 1.0
	v_mul_f32_e32 v20, v19, v18
	v_fma_f32 v21, -v3, v20, v19
	v_fmac_f32_e32 v20, v21, v18
	v_fma_f32 v3, -v3, v20, v19
	v_div_fmas_f32 v3, v3, v18, v20
	v_div_fixup_f32 v2, v3, v2, 1.0
	v_cvt_pk_bf16_f32 v2, v2, v0
	v_mul_f32_e32 v0, 0xbfb8aa3b, v4
	v_exp_f32_e32 v4, v0
	v_mul_f32_e32 v0, 0xbfb8aa3b, v5
	v_exp_f32_e32 v5, v0
	s_nop 0
	v_pk_add_f32 v[4:5], v[4:5], 1.0 op_sel_hi:[1,0]
	s_nop 0
	v_div_scale_f32 v0, s[2:3], v5, v5, 1.0
	v_rcp_f32_e32 v3, v0
	s_nop 0
	v_fma_f32 v18, -v0, v3, 1.0
	v_fmac_f32_e32 v3, v18, v3
	v_div_scale_f32 v18, vcc, 1.0, v5, 1.0
	v_mul_f32_e32 v19, v18, v3
	v_fma_f32 v20, -v0, v19, v18
	v_fmac_f32_e32 v19, v20, v3
	v_fma_f32 v0, -v0, v19, v18
	v_div_fmas_f32 v0, v0, v3, v19
	v_div_scale_f32 v3, s[2:3], v4, v4, 1.0
	v_div_fixup_f32 v0, v0, v5, 1.0
	v_rcp_f32_e32 v5, v3
	s_nop 0
	v_fma_f32 v18, -v3, v5, 1.0
	v_fmac_f32_e32 v5, v18, v5
	v_div_scale_f32 v18, vcc, 1.0, v4, 1.0
	v_mul_f32_e32 v19, v18, v5
	v_fma_f32 v20, -v3, v19, v18
	v_fmac_f32_e32 v19, v20, v5
	v_fma_f32 v3, -v3, v19, v18
	v_div_fmas_f32 v3, v3, v5, v19
	v_div_fixup_f32 v3, v3, v4, 1.0
	v_cvt_pk_bf16_f32 v3, v3, v0
	v_mul_f32_e32 v0, 0xbfb8aa3b, v6
	v_exp_f32_e32 v4, v0
	v_mul_f32_e32 v0, 0xbfb8aa3b, v7
	v_exp_f32_e32 v5, v0
	s_nop 0
	v_pk_add_f32 v[4:5], v[4:5], 1.0 op_sel_hi:[1,0]
	s_nop 0
	v_div_scale_f32 v0, s[2:3], v5, v5, 1.0
	v_rcp_f32_e32 v6, v0
	s_nop 0
	v_fma_f32 v7, -v0, v6, 1.0
	v_fmac_f32_e32 v6, v7, v6
	v_div_scale_f32 v7, vcc, 1.0, v5, 1.0
	v_mul_f32_e32 v18, v7, v6
	v_fma_f32 v19, -v0, v18, v7
	v_fmac_f32_e32 v18, v19, v6
	v_fma_f32 v0, -v0, v18, v7
	v_div_fmas_f32 v0, v0, v6, v18
	v_div_fixup_f32 v0, v0, v5, 1.0
	v_div_scale_f32 v5, s[2:3], v4, v4, 1.0
	v_rcp_f32_e32 v6, v5
	s_nop 0
	v_fma_f32 v7, -v5, v6, 1.0
	v_fmac_f32_e32 v6, v7, v6
	v_div_scale_f32 v7, vcc, 1.0, v4, 1.0
	v_mul_f32_e32 v18, v7, v6
	v_fma_f32 v19, -v5, v18, v7
	v_fmac_f32_e32 v18, v19, v6
	v_fma_f32 v5, -v5, v18, v7
	v_div_fmas_f32 v5, v5, v6, v18
	v_div_fixup_f32 v4, v5, v4, 1.0
	v_cvt_pk_bf16_f32 v4, v4, v0
	v_mul_f32_e32 v0, 0xbfb8aa3b, v8
	v_exp_f32_e32 v6, v0
	v_mul_f32_e32 v0, 0xbfb8aa3b, v9
	v_exp_f32_e32 v7, v0
	s_nop 0
	v_pk_add_f32 v[6:7], v[6:7], 1.0 op_sel_hi:[1,0]
	s_nop 0
	v_div_scale_f32 v0, s[2:3], v7, v7, 1.0
	v_rcp_f32_e32 v5, v0
	s_nop 0
	v_fma_f32 v8, -v0, v5, 1.0
	v_fmac_f32_e32 v5, v8, v5
	v_div_scale_f32 v8, vcc, 1.0, v7, 1.0
	v_mul_f32_e32 v9, v8, v5
	v_fma_f32 v18, -v0, v9, v8
	v_fmac_f32_e32 v9, v18, v5
	v_fma_f32 v0, -v0, v9, v8
	v_div_fmas_f32 v0, v0, v5, v9
	v_div_scale_f32 v5, s[2:3], v6, v6, 1.0
	v_div_fixup_f32 v0, v0, v7, 1.0
	v_rcp_f32_e32 v7, v5
	s_nop 0
	v_fma_f32 v8, -v5, v7, 1.0
	v_fmac_f32_e32 v7, v8, v7
	v_div_scale_f32 v8, vcc, 1.0, v6, 1.0
	v_mul_f32_e32 v9, v8, v7
	v_fma_f32 v18, -v5, v9, v8
	v_fmac_f32_e32 v9, v18, v7
	v_fma_f32 v5, -v5, v9, v8
	v_div_fmas_f32 v5, v5, v7, v9
	v_div_fixup_f32 v5, v5, v6, 1.0
	v_cvt_pk_bf16_f32 v5, v5, v0
; DI unsigned pk2(float a, float b) { f32v2 v = {a, b}; return __builtin_bit_cast(unsigned, __builtin_convertvector(v, bf16v2)); }
; DI float sigmoidf_(float v) { return 1.f / (1.f + __expf(-v)); }
; DI size_t tix(size_t t, int f, int KT) { return ((t >> 7) * KT + (f >> 6)) * 8192 + (t & 127) * 64 + (f & 63); }
; #define SW_FOR_TOK(j) _Pragma("unroll") for (int j = 0; j < 4; j++)
; #define SW_FOR_FEAT(i, rq) _Pragma("unroll") for (int i = 0; i < 2; i++) _Pragma("unroll") for (int rq = 0; rq < 4; rq++)
; DI void ph_ple(const Params& P, int g, int layer, bf16_t* smem) {
;     ...
;     SW_FOR_TOK(j) { const int tl_ = wn * 128 + j * 32 + l32;
;       SW_FOR_FEAT(i, rq) { const int c_ = wm * 64 + i * 32 + 8 * rq + 4 * h;
;         *(uint2*)(smem + tl_ * EPLD + c_) = make_uint2(pk2(sigmoidf_(SWV(i, j, 4 * rq)), sigmoidf_(SWV(i, j, 4 * rq + 1))), pk2(sigmoidf_(SWV(i, j, 4 * rq + 2)), sigmoidf_(SWV(i, j, 4 * rq + 3)))); } }
;     __syncthreads();
; #pragma unroll 8
;     for (int k = 0; k < 16; k++) {
;       const int c = tid + 256 * k; const int ch8 = c & 7, row = (c >> 3) & 255, fh = c >> 11;
;       const int f = fh * 64 + ch8 * 8; const size_t tg = (size_t)m0 + row;
;       const uint4 sg = *(const uint4*)(smem + row * EPLD + f);
;       bf16_t* ep = x2b + tix(tg, n0 + f, 16);
;       const uint4 eu = *(const uint4*)ep;
;       float* yp = y + tg * 1024 + n0 + f;
;       const uint4 xu = *(const uint4*)(x1b + tix(tg, n0 + f, 16));
	v_mul_f32_e32 v0, 0xbfb8aa3b, v10
	ds_write2_b64 v191, v[2:3], v[4:5] offset0:200 offset1:202
	v_exp_f32_e32 v2, v0
	v_mul_f32_e32 v0, 0xbfb8aa3b, v11
	v_exp_f32_e32 v3, v0
	s_nop 0
	v_pk_add_f32 v[2:3], v[2:3], 1.0 op_sel_hi:[1,0]
	s_nop 0
	v_div_scale_f32 v0, s[2:3], v3, v3, 1.0
	v_rcp_f32_e32 v4, v0
	s_nop 0
	v_fma_f32 v5, -v0, v4, 1.0
	v_fmac_f32_e32 v4, v5, v4
	v_div_scale_f32 v5, vcc, 1.0, v3, 1.0
	v_mul_f32_e32 v6, v5, v4
	v_fma_f32 v7, -v0, v6, v5
	v_fmac_f32_e32 v6, v7, v4
	v_fma_f32 v0, -v0, v6, v5
	v_div_fmas_f32 v0, v0, v4, v6
	v_div_fixup_f32 v0, v0, v3, 1.0
	v_div_scale_f32 v3, s[2:3], v2, v2, 1.0
	v_rcp_f32_e32 v4, v3
	s_nop 0
	v_fma_f32 v5, -v3, v4, 1.0
	v_fmac_f32_e32 v4, v5, v4
	v_div_scale_f32 v5, vcc, 1.0, v2, 1.0
	v_mul_f32_e32 v6, v5, v4
	v_fma_f32 v7, -v3, v6, v5
	v_fmac_f32_e32 v6, v7, v4
	v_fma_f32 v3, -v3, v6, v5
	v_div_fmas_f32 v3, v3, v4, v6
	v_div_fixup_f32 v2, v3, v2, 1.0
	v_cvt_pk_bf16_f32 v2, v2, v0
	v_mul_f32_e32 v0, 0xbfb8aa3b, v12
	v_exp_f32_e32 v4, v0
	v_mul_f32_e32 v0, 0xbfb8aa3b, v13
	v_exp_f32_e32 v5, v0
	s_nop 0
	v_pk_add_f32 v[4:5], v[4:5], 1.0 op_sel_hi:[1,0]
	s_nop 0
	v_div_scale_f32 v0, s[2:3], v5, v5, 1.0
	v_rcp_f32_e32 v3, v0
	s_nop 0
	v_fma_f32 v6, -v0, v3, 1.0
	v_fmac_f32_e32 v3, v6, v3
	v_div_scale_f32 v6, vcc, 1.0, v5, 1.0
	v_mul_f32_e32 v7, v6, v3
	v_fma_f32 v8, -v0, v7, v6
	v_fmac_f32_e32 v7, v8, v3
	v_fma_f32 v0, -v0, v7, v6
	v_div_fmas_f32 v0, v0, v3, v7
	v_div_scale_f32 v3, s[2:3], v4, v4, 1.0
	v_div_fixup_f32 v0, v0, v5, 1.0
	v_rcp_f32_e32 v5, v3
	s_nop 0
	v_fma_f32 v6, -v3, v5, 1.0
	v_fmac_f32_e32 v5, v6, v5
	v_div_scale_f32 v6, vcc, 1.0, v4, 1.0
	v_mul_f32_e32 v7, v6, v5
	v_fma_f32 v8, -v3, v7, v6
	v_fmac_f32_e32 v7, v8, v5
	v_fma_f32 v3, -v3, v7, v6
	v_div_fmas_f32 v3, v3, v5, v7
	v_div_fixup_f32 v3, v3, v4, 1.0
	v_cvt_pk_bf16_f32 v3, v3, v0
	v_mul_f32_e32 v0, 0xbfb8aa3b, v14
	v_exp_f32_e32 v4, v0
	v_mul_f32_e32 v0, 0xbfb8aa3b, v15
	v_exp_f32_e32 v5, v0
	s_nop 0
	v_pk_add_f32 v[4:5], v[4:5], 1.0 op_sel_hi:[1,0]
	s_nop 0
	v_div_scale_f32 v0, s[2:3], v5, v5, 1.0
	v_rcp_f32_e32 v6, v0
	s_nop 0
	v_fma_f32 v7, -v0, v6, 1.0
	v_fmac_f32_e32 v6, v7, v6
	v_div_scale_f32 v7, vcc, 1.0, v5, 1.0
	v_mul_f32_e32 v8, v7, v6
	v_fma_f32 v9, -v0, v8, v7
	v_fmac_f32_e32 v8, v9, v6
	v_fma_f32 v0, -v0, v8, v7
	v_div_fmas_f32 v0, v0, v6, v8
	v_div_fixup_f32 v0, v0, v5, 1.0
	v_div_scale_f32 v5, s[2:3], v4, v4, 1.0
	v_rcp_f32_e32 v6, v5
	s_nop 0
	v_fma_f32 v7, -v5, v6, 1.0
	v_fmac_f32_e32 v6, v7, v6
	v_div_scale_f32 v7, vcc, 1.0, v4, 1.0
	v_mul_f32_e32 v8, v7, v6
	v_fma_f32 v9, -v5, v8, v7
	v_fmac_f32_e32 v8, v9, v6
	v_fma_f32 v5, -v5, v8, v7
	v_div_fmas_f32 v5, v5, v6, v8
	v_div_fixup_f32 v4, v5, v4, 1.0
	v_cvt_pk_bf16_f32 v4, v4, v0
	v_mul_f32_e32 v0, 0xbfb8aa3b, v16
	v_exp_f32_e32 v6, v0
	v_mul_f32_e32 v0, 0xbfb8aa3b, v17
	v_exp_f32_e32 v7, v0
	s_nop 0
	v_pk_add_f32 v[6:7], v[6:7], 1.0 op_sel_hi:[1,0]
	s_nop 0
	v_div_scale_f32 v0, s[2:3], v7, v7, 1.0
	v_rcp_f32_e32 v5, v0
	s_nop 0
	v_fma_f32 v8, -v0, v5, 1.0
	v_fmac_f32_e32 v5, v8, v5
	v_div_scale_f32 v8, vcc, 1.0, v7, 1.0
	v_mul_f32_e32 v9, v8, v5
	v_fma_f32 v10, -v0, v9, v8
	v_fmac_f32_e32 v9, v10, v5
	v_fma_f32 v0, -v0, v9, v8
	v_div_fmas_f32 v0, v0, v5, v9
	v_div_scale_f32 v5, s[2:3], v6, v6, 1.0
	v_div_fixup_f32 v0, v0, v7, 1.0
	v_rcp_f32_e32 v7, v5
	s_lshl_b32 s2, s29, 1
	s_ashr_i32 s3, s2, 31
	s_lshl_b64 s[2:3], s[2:3], 2
	v_fma_f32 v8, -v5, v7, 1.0
	v_fmac_f32_e32 v7, v8, v7
	v_div_scale_f32 v8, vcc, 1.0, v6, 1.0
	v_mul_f32_e32 v9, v8, v7
	v_fma_f32 v10, -v5, v9, v8
	v_fmac_f32_e32 v9, v10, v7
	v_fma_f32 v5, -v5, v9, v8
	v_div_fmas_f32 v5, v5, v7, v9
	v_div_fixup_f32 v5, v5, v6, 1.0
	v_cmp_lt_i32_e32 vcc, v241, v237
	v_cvt_pk_bf16_f32 v5, v5, v0
	s_add_u32 s2, s10, s2
	v_cndmask_b32_e32 v0, v238, v241, vcc
	v_cmp_lt_i32_e32 vcc, v240, v237
	v_lshlrev_b32_e32 v10, 2, v0
	s_addc_u32 s3, s11, s3
	v_cndmask_b32_e32 v0, v238, v240, vcc
	v_cmp_lt_i32_e32 vcc, v252, v237
	v_lshlrev_b32_e32 v11, 2, v0
	ds_write2_b64 v191, v[2:3], v[4:5] offset0:204 offset1:206
	v_cndmask_b32_e32 v0, v238, v252, vcc
	v_lshlrev_b32_e32 v12, 2, v0
	v_and_b32_e32 v3, 0x7ffff, v171
	v_and_b32_e32 v2, -16, v170
	v_or_b32_e32 v0, v174, v162
	v_lshl_add_u64 v[4:5], s[2:3], 0, v[172:173]
	s_waitcnt lgkmcnt(0)
	s_barrier
	s_branch .LBB0_239

; DI size_t tix(size_t t, int f, int KT) { return ((t >> 7) * KT + (f >> 6)) * 8192 + (t & 127) * 64 + (f & 63); }
; DI void rows_out_tiled(const bf16_t* smem, bf16_t* buf, size_t t0, int f0, int KT, int tid) {
; #pragma unroll 8
;   for (int k = 0; k < 16; k++) { const int c = tid + 256 * k; const int ch = c & 7, row = (c >> 3) & 255, fh = c >> 11;
;     *(uint4*)(buf + tix(t0 + row, f0 + fh * 64 + ch * 8, KT)) = *(const uint4*)(smem + row * EPLD + fh * 64 + ch * 8); }
; }
.LBB0_468:
	v_add_u32_e32 v16, s10, v163
	v_ashrrev_i32_e32 v0, 5, v16
	v_lshlrev_b32_e32 v6, 1, v0
	v_and_b32_e32 v6, 0xffffff80, v6
	v_add_u32_e32 v0, s8, v0
	v_add_u32_e32 v8, v188, v6
	v_ashrrev_i32_e32 v6, 6, v0
	v_ashrrev_i32_e32 v7, 31, v6
	v_lshl_add_u64 v[6:7], v[2:3], 0, v[6:7]
	v_lshlrev_b64 v[6:7], 14, v[6:7]
	v_lshl_add_u64 v[10:11], v[4:5], 0, v[6:7]
	ds_read_b128 v[6:9], v8
	v_add_u32_e32 v0, 0x100, v16
	v_mov_b32_e32 v13, s19
	s_addk_i32 s10, 0x800
	s_cmpk_lg_i32 s10, 0x1000
	s_waitcnt lgkmcnt(0)
	global_store_dwordx4 v[10:11], v[6:9], off
	v_lshlrev_b32_e32 v10, 1, v162
	v_mov_b32_e32 v11, v1
	v_bfe_u32 v6, v0, 3, 8
	v_ashrrev_i32_e32 v0, 5, v0
	v_lshlrev_b32_e32 v8, 1, v0
	v_mul_u32_u24_e32 v7, 0x110, v6
	v_and_b32_e32 v8, 0xffffff80, v8
	v_or_b32_e32 v12, s18, v6
	v_add_u32_e32 v0, s8, v0
	v_add3_u32 v17, v7, v8, v10
	v_lshrrev_b64 v[6:7], 3, v[12:13]
	v_ashrrev_i32_e32 v8, 6, v0
	v_and_b32_e32 v7, 0x3ffff, v7
	v_and_b32_e32 v6, -16, v6
	v_ashrrev_i32_e32 v9, 31, v8
	v_lshl_add_u64 v[6:7], v[6:7], 0, v[8:9]
	v_lshlrev_b64 v[6:7], 14, v[6:7]
	v_lshlrev_b32_e32 v0, 7, v12
	v_lshl_add_u64 v[6:7], s[82:83], 0, v[6:7]
	v_and_b32_e32 v0, 0x3f80, v0
	v_lshl_add_u64 v[6:7], v[6:7], 0, v[0:1]
	v_lshl_add_u64 v[14:15], v[6:7], 0, v[10:11]
	ds_read_b128 v[6:9], v17
	v_add_u32_e32 v0, 0x200, v16
	s_waitcnt lgkmcnt(0)
	global_store_dwordx4 v[14:15], v[6:9], off
	s_nop 1
	v_bfe_u32 v6, v0, 3, 8
	v_ashrrev_i32_e32 v0, 5, v0
	v_lshlrev_b32_e32 v8, 1, v0
	v_mul_u32_u24_e32 v7, 0x110, v6
	v_and_b32_e32 v8, 0xffffff80, v8
	v_or_b32_e32 v12, s18, v6
	v_add_u32_e32 v0, s8, v0
	v_add3_u32 v17, v7, v8, v10
	v_lshrrev_b64 v[6:7], 3, v[12:13]
	v_ashrrev_i32_e32 v8, 6, v0
	v_and_b32_e32 v7, 0x3ffff, v7
	v_and_b32_e32 v6, -16, v6
	v_ashrrev_i32_e32 v9, 31, v8
	v_lshl_add_u64 v[6:7], v[6:7], 0, v[8:9]
	v_lshlrev_b64 v[6:7], 14, v[6:7]
	v_lshlrev_b32_e32 v0, 7, v12
	v_lshl_add_u64 v[6:7], s[82:83], 0, v[6:7]
	v_and_b32_e32 v0, 0x3f80, v0
	v_lshl_add_u64 v[6:7], v[6:7], 0, v[0:1]
	v_lshl_add_u64 v[14:15], v[6:7], 0, v[10:11]
	ds_read_b128 v[6:9], v17
	v_add_u32_e32 v0, 0x300, v16
	s_waitcnt lgkmcnt(0)
	global_store_dwordx4 v[14:15], v[6:9], off
	s_nop 1
	v_bfe_u32 v6, v0, 3, 8
	v_ashrrev_i32_e32 v0, 5, v0
	v_lshlrev_b32_e32 v8, 1, v0
	v_mul_u32_u24_e32 v7, 0x110, v6
	v_and_b32_e32 v8, 0xffffff80, v8
	v_or_b32_e32 v12, s18, v6
	v_add_u32_e32 v0, s8, v0
	v_add3_u32 v17, v7, v8, v10
	v_lshrrev_b64 v[6:7], 3, v[12:13]
	v_ashrrev_i32_e32 v8, 6, v0
	v_and_b32_e32 v7, 0x3ffff, v7
	v_and_b32_e32 v6, -16, v6
	v_ashrrev_i32_e32 v9, 31, v8
	v_lshl_add_u64 v[6:7], v[6:7], 0, v[8:9]
	v_lshlrev_b64 v[6:7], 14, v[6:7]
	v_lshlrev_b32_e32 v0, 7, v12
	v_lshl_add_u64 v[6:7], s[82:83], 0, v[6:7]
	v_and_b32_e32 v0, 0x3f80, v0
	v_lshl_add_u64 v[6:7], v[6:7], 0, v[0:1]
	v_lshl_add_u64 v[14:15], v[6:7], 0, v[10:11]
	ds_read_b128 v[6:9], v17
	v_add_u32_e32 v0, 0x400, v16
	s_waitcnt lgkmcnt(0)
	global_store_dwordx4 v[14:15], v[6:9], off
	s_nop 1
	v_bfe_u32 v6, v0, 3, 8
	v_ashrrev_i32_e32 v0, 5, v0
	v_lshlrev_b32_e32 v8, 1, v0
	v_mul_u32_u24_e32 v7, 0x110, v6
	v_and_b32_e32 v8, 0xffffff80, v8
	v_or_b32_e32 v12, s18, v6
	v_add_u32_e32 v0, s8, v0
	v_add3_u32 v17, v7, v8, v10
	v_lshrrev_b64 v[6:7], 3, v[12:13]
	v_ashrrev_i32_e32 v8, 6, v0
	v_and_b32_e32 v7, 0x3ffff, v7
	v_and_b32_e32 v6, -16, v6
	v_ashrrev_i32_e32 v9, 31, v8
	v_lshl_add_u64 v[6:7], v[6:7], 0, v[8:9]
	v_lshlrev_b64 v[6:7], 14, v[6:7]
	v_lshlrev_b32_e32 v0, 7, v12
	v_lshl_add_u64 v[6:7], s[82:83], 0, v[6:7]
	v_and_b32_e32 v0, 0x3f80, v0
	v_lshl_add_u64 v[6:7], v[6:7], 0, v[0:1]
	v_lshl_add_u64 v[14:15], v[6:7], 0, v[10:11]
	ds_read_b128 v[6:9], v17
	v_add_u32_e32 v0, 0x500, v16
	s_waitcnt lgkmcnt(0)
	global_store_dwordx4 v[14:15], v[6:9], off
	s_nop 1
	v_bfe_u32 v6, v0, 3, 8
	v_ashrrev_i32_e32 v0, 5, v0
	v_lshlrev_b32_e32 v8, 1, v0
	v_mul_u32_u24_e32 v7, 0x110, v6
	v_and_b32_e32 v8, 0xffffff80, v8
	v_or_b32_e32 v12, s18, v6
	v_add_u32_e32 v0, s8, v0
	v_add3_u32 v17, v7, v8, v10
	v_lshrrev_b64 v[6:7], 3, v[12:13]
	v_ashrrev_i32_e32 v8, 6, v0
	v_and_b32_e32 v7, 0x3ffff, v7
	v_and_b32_e32 v6, -16, v6
	v_ashrrev_i32_e32 v9, 31, v8
	v_lshl_add_u64 v[6:7], v[6:7], 0, v[8:9]
	v_lshlrev_b64 v[6:7], 14, v[6:7]
	v_lshlrev_b32_e32 v0, 7, v12
	v_lshl_add_u64 v[6:7], s[82:83], 0, v[6:7]
	v_and_b32_e32 v0, 0x3f80, v0
	v_lshl_add_u64 v[6:7], v[6:7], 0, v[0:1]
	v_lshl_add_u64 v[14:15], v[6:7], 0, v[10:11]
	ds_read_b128 v[6:9], v17
	v_add_u32_e32 v0, 0x600, v16
	s_waitcnt lgkmcnt(0)
	global_store_dwordx4 v[14:15], v[6:9], off
	s_nop 1
	v_bfe_u32 v6, v0, 3, 8
	v_ashrrev_i32_e32 v0, 5, v0
	v_lshlrev_b32_e32 v8, 1, v0
	v_mul_u32_u24_e32 v7, 0x110, v6
	v_and_b32_e32 v8, 0xffffff80, v8
	v_or_b32_e32 v12, s18, v6
	v_add_u32_e32 v0, s8, v0
	v_add3_u32 v17, v7, v8, v10
	v_lshrrev_b64 v[6:7], 3, v[12:13]
	v_ashrrev_i32_e32 v8, 6, v0
	v_and_b32_e32 v7, 0x3ffff, v7
	v_and_b32_e32 v6, -16, v6
	v_ashrrev_i32_e32 v9, 31, v8
	v_lshl_add_u64 v[6:7], v[6:7], 0, v[8:9]
	v_lshlrev_b64 v[6:7], 14, v[6:7]
	v_lshlrev_b32_e32 v0, 7, v12
	v_lshl_add_u64 v[6:7], s[82:83], 0, v[6:7]
	v_and_b32_e32 v0, 0x3f80, v0
	v_lshl_add_u64 v[6:7], v[6:7], 0, v[0:1]
	v_lshl_add_u64 v[14:15], v[6:7], 0, v[10:11]
	ds_read_b128 v[6:9], v17
	v_add_u32_e32 v0, 0x700, v16
	s_waitcnt lgkmcnt(0)
	global_store_dwordx4 v[14:15], v[6:9], off
	s_nop 1
	v_bfe_u32 v6, v0, 3, 8
	v_ashrrev_i32_e32 v0, 5, v0
	v_lshlrev_b32_e32 v8, 1, v0
	v_mul_u32_u24_e32 v7, 0x110, v6
	v_and_b32_e32 v8, 0xffffff80, v8
	v_or_b32_e32 v12, s18, v6
	v_add_u32_e32 v0, s8, v0
	v_add3_u32 v14, v7, v8, v10
	v_lshrrev_b64 v[6:7], 3, v[12:13]
	v_ashrrev_i32_e32 v8, 6, v0
	v_and_b32_e32 v7, 0x3ffff, v7
	v_and_b32_e32 v6, -16, v6
	v_ashrrev_i32_e32 v9, 31, v8
	v_lshl_add_u64 v[6:7], v[6:7], 0, v[8:9]
	v_lshlrev_b64 v[6:7], 14, v[6:7]
	v_lshlrev_b32_e32 v0, 7, v12
	v_lshl_add_u64 v[6:7], s[82:83], 0, v[6:7]
	v_and_b32_e32 v0, 0x3f80, v0
	v_lshl_add_u64 v[6:7], v[6:7], 0, v[0:1]
	v_lshl_add_u64 v[10:11], v[6:7], 0, v[10:11]
	ds_read_b128 v[6:9], v14
	s_waitcnt lgkmcnt(0)
	global_store_dwordx4 v[10:11], v[6:9], off
	s_cbranch_scc1 .LBB0_468
; #define A256_LOADH(kt_, hf_) { a0 = la.ld1(kt_, (hf_) * 4 + 0, tid); a1 = la.ld1(kt_, (hf_) * 4 + 1, tid); a2 = la.ld1(kt_, (hf_) * 4 + 2, tid); a3 = la.ld1(kt_, (hf_) * 4 + 3, tid); }
; #define ZERO_ACC8(a) { _Pragma("unroll") for (int i_ = 0; i_ < 8; i_++) _Pragma("unroll") for (int r_ = 0; r_ < 16; r_++) a[i_][r_] = 0.f; }
; template <bool swap, class LA>
; DI void gemm256_ws(const LA& la, const bf16_t* Wt, const int KS, const int nk, bf16_t* smem, f32x16 (&acc)[8]) {
;     ...
;   A256_LOADH(0, 0) A256_STH(smem, 0)
;   A256_LOADH(0, 1) A256_STH(smem, 1)
;   W256_LD(0, 0, w00, w10) W256_LD(0, 1, w01, w11) W256_LD(0, 2, w02, w12) W256_LD(0, 3, w03, w13)
;   __syncthreads();
;   const int aoff = (tbk * 128 + l32) * LDT + h * 8;
; DI void ph_ple(const Params& P, int g, int layer, bf16_t* smem) {
;     ...
;     rows_out_tiled(smem, x2b, (size_t)m0, n0, 16, tid);
;     __syncthreads();
;     ZERO_ACC8(acc)
;     { LoadTile256 la{x1b + (size_t)(2 * mt) * 16 * 8192, 16 * 8192}; gemm256_ws<true>(la, Wg + (size_t)n0 * 1024, 64, 16, smem, acc); }
	s_lshl_b64 s[2:3], s[2:3], 18
	v_mov_b32_e32 v0, v234
	s_barrier
	s_add_u32 s2, s80, s2
	s_addc_u32 s3, s81, s3
	v_lshlrev_b32_e32 v2, 3, v0
	s_lshl_b64 s[10:11], s[8:9], 11
	v_readlane_b32 s12, v254, 7
	v_ashrrev_i32_e32 v3, 31, v2
	v_readlane_b32 s13, v254, 8
	s_add_u32 s12, s12, s10
	v_lshlrev_b64 v[174:175], 1, v[2:3]
	v_add_u32_e32 v6, 0x800, v2
	v_add_u32_e32 v8, 0x1000, v2
	v_add_u32_e32 v2, 0x1800, v2
	s_addc_u32 s13, s13, s11
	v_ashrrev_i32_e32 v7, 31, v6
	v_ashrrev_i32_e32 v9, 31, v8
	v_ashrrev_i32_e32 v3, 31, v2
	v_lshlrev_b64 v[176:177], 1, v[6:7]
	v_lshlrev_b64 v[178:179], 1, v[8:9]
	v_lshlrev_b64 v[180:181], 1, v[2:3]
	s_add_u32 s10, s2, 0x40000
	v_lshl_add_u64 v[4:5], s[2:3], 0, v[174:175]
	v_lshl_add_u64 v[6:7], s[2:3], 0, v[176:177]
	v_lshl_add_u64 v[16:17], s[2:3], 0, v[178:179]
	v_lshl_add_u64 v[2:3], s[2:3], 0, v[180:181]
	s_addc_u32 s11, s3, 0
	v_ashrrev_i32_e32 v40, 6, v0
	global_load_dwordx4 v[8:11], v[4:5], off
	global_load_dwordx4 v[12:15], v[6:7], off
	s_nop 0
	global_load_dwordx4 v[16:19], v[16:17], off
	s_nop 0
	global_load_dwordx4 v[20:23], v[2:3], off
	v_lshl_add_u64 v[2:3], s[10:11], 0, v[174:175]
	v_lshl_add_u64 v[6:7], s[10:11], 0, v[178:179]
	v_lshl_add_u64 v[36:37], s[10:11], 0, v[180:181]
	v_lshlrev_b32_e32 v41, 4, v0
	v_and_b32_e32 v40, -2, v40
	v_lshl_add_u64 v[4:5], s[10:11], 0, v[176:177]
	global_load_dwordx4 v[24:27], v[2:3], off
	global_load_dwordx4 v[28:31], v[4:5], off
	global_load_dwordx4 v[32:35], v[6:7], off
	s_nop 0
	global_load_dwordx4 v[36:39], v[36:37], off
	v_and_b32_e32 v7, 31, v0
	v_lshrrev_b32_e32 v43, 3, v0
	v_lshlrev_b32_e32 v44, 1, v0
	v_lshrrev_b32_e32 v45, 1, v0
	v_and_b32_e32 v0, 0x3f0, v41
	v_and_b32_e32 v42, 0x70, v41
	v_ashrrev_i32_e32 v41, 31, v40
	v_lshlrev_b64 v[40:41], 16, v[40:41]
	v_lshl_add_u64 v[40:41], s[12:13], 0, v[40:41]
	v_lshl_add_u64 v[184:185], v[40:41], 0, v[0:1]
	v_add_co_u32_e32 v40, vcc, s94, v184
	s_movk_i32 s36, 0x80
	s_nop 0
	v_addc_co_u32_e32 v41, vcc, 0, v185, vcc
	global_load_dwordx4 v[154:157], v[40:41], off
	global_load_dwordx4 v[158:161], v[184:185], off
	global_load_dwordx4 v[146:149], v[40:41], off offset:1024
	global_load_dwordx4 v[150:153], v[184:185], off offset:1024
	global_load_dwordx4 v[142:145], v[40:41], off offset:2048
	global_load_dwordx4 v[138:141], v[184:185], off offset:2048
	global_load_dwordx4 v[130:133], v[40:41], off offset:3072
	global_load_dwordx4 v[134:137], v[184:185], off offset:3072
	v_mov_b32_e32 v2, 0
	v_and_or_b32 v7, v44, s36, v7
	v_and_b32_e32 v44, 16, v45
	v_mad_u64_u32 v[182:183], s[36:37], v43, s0, v[42:43]
	s_mov_b64 s[12:13], 0x10000
	s_mov_b32 s29, 0
	v_mov_b32_e32 v3, v2
	v_mov_b32_e32 v4, v2
	v_mov_b32_e32 v5, v2
	v_mov_b32_e32 v6, v2
	v_mad_u32_u24 v183, v7, s0, v44
	v_lshl_add_u64 v[186:187], v[184:185], 0, s[12:13]
	v_mov_b32_e32 v7, v2
	v_mov_b32_e32 v40, v2
	v_mov_b32_e32 v41, v2
	v_mov_b32_e32 v42, v2
	v_mov_b32_e32 v43, v2
	v_mov_b32_e32 v44, v2
	v_mov_b32_e32 v45, v2
	v_mov_b32_e32 v46, v2
	v_mov_b32_e32 v47, v2
	v_mov_b32_e32 v48, v2
	v_mov_b32_e32 v49, v2
	v_mov_b32_e32 v66, v2
	v_mov_b32_e32 v67, v2
	v_mov_b32_e32 v68, v2
	v_mov_b32_e32 v69, v2
	v_mov_b32_e32 v70, v2
	v_mov_b32_e32 v71, v2
	v_mov_b32_e32 v72, v2
	v_mov_b32_e32 v73, v2
	s_waitcnt vmcnt(15)
	ds_write_b128 v182, v[8:11]
	s_waitcnt vmcnt(14)
	ds_write_b128 v182, v[12:15] offset:4608
	s_waitcnt vmcnt(13)
	ds_write_b128 v182, v[16:19] offset:9216
	s_waitcnt vmcnt(12)
	ds_write_b128 v182, v[20:23] offset:13824
	s_waitcnt vmcnt(11)
	ds_write_b128 v182, v[24:27] offset:18432
	s_waitcnt vmcnt(10)
	ds_write_b128 v182, v[28:31] offset:23040
	s_waitcnt vmcnt(9)
	ds_write_b128 v182, v[32:35] offset:27648
	s_waitcnt vmcnt(8)
	ds_write_b128 v182, v[36:39] offset:32256
	v_mov_b32_e32 v8, v2
	v_mov_b32_e32 v9, v2
	v_mov_b32_e32 v10, v2
	v_mov_b32_e32 v11, v2
	v_mov_b32_e32 v12, v2
	v_mov_b32_e32 v13, v2
	v_mov_b32_e32 v14, v2
	v_mov_b32_e32 v15, v2
	v_mov_b32_e32 v16, v2
	v_mov_b32_e32 v17, v2
	v_mov_b32_e32 v34, v2
	v_mov_b32_e32 v35, v2
	v_mov_b32_e32 v36, v2
	v_mov_b32_e32 v37, v2
	v_mov_b32_e32 v38, v2
	v_mov_b32_e32 v39, v2
	v_mov_b32_e32 v74, v2
	v_mov_b32_e32 v75, v2
	v_mov_b32_e32 v76, v2
	v_mov_b32_e32 v77, v2
	v_mov_b32_e32 v78, v2
	v_mov_b32_e32 v79, v2
	v_mov_b32_e32 v80, v2
	v_mov_b32_e32 v81, v2
	v_mov_b32_e32 v98, v2
	v_mov_b32_e32 v99, v2
	v_mov_b32_e32 v100, v2
	v_mov_b32_e32 v101, v2
	v_mov_b32_e32 v102, v2
	v_mov_b32_e32 v103, v2
	v_mov_b32_e32 v104, v2
	v_mov_b32_e32 v105, v2
	v_mov_b32_e32 v106, v2
	v_mov_b32_e32 v107, v2
	v_mov_b32_e32 v108, v2
	v_mov_b32_e32 v109, v2
	v_mov_b32_e32 v110, v2
	v_mov_b32_e32 v111, v2
	v_mov_b32_e32 v112, v2
	v_mov_b32_e32 v113, v2
	v_mov_b32_e32 v18, v2
	v_mov_b32_e32 v19, v2
	v_mov_b32_e32 v20, v2
	v_mov_b32_e32 v21, v2
	v_mov_b32_e32 v22, v2
	v_mov_b32_e32 v23, v2
	v_mov_b32_e32 v24, v2
	v_mov_b32_e32 v25, v2
	v_mov_b32_e32 v26, v2
	v_mov_b32_e32 v27, v2
	v_mov_b32_e32 v28, v2
	v_mov_b32_e32 v29, v2
	v_mov_b32_e32 v30, v2
	v_mov_b32_e32 v31, v2
	v_mov_b32_e32 v32, v2
	v_mov_b32_e32 v33, v2
	v_mov_b32_e32 v50, v2
	v_mov_b32_e32 v51, v2
	v_mov_b32_e32 v52, v2
	v_mov_b32_e32 v53, v2
	v_mov_b32_e32 v54, v2
	v_mov_b32_e32 v55, v2
	v_mov_b32_e32 v56, v2
	v_mov_b32_e32 v57, v2
	v_mov_b32_e32 v58, v2
	v_mov_b32_e32 v59, v2
	v_mov_b32_e32 v60, v2
	v_mov_b32_e32 v61, v2
	v_mov_b32_e32 v62, v2
	v_mov_b32_e32 v63, v2
	v_mov_b32_e32 v64, v2
	v_mov_b32_e32 v65, v2
	v_mov_b32_e32 v82, v2
	v_mov_b32_e32 v83, v2
	v_mov_b32_e32 v84, v2
	v_mov_b32_e32 v85, v2
	v_mov_b32_e32 v86, v2
	v_mov_b32_e32 v87, v2
	v_mov_b32_e32 v88, v2
	v_mov_b32_e32 v89, v2
	v_mov_b32_e32 v90, v2
	v_mov_b32_e32 v91, v2
	v_mov_b32_e32 v92, v2
	v_mov_b32_e32 v93, v2
	v_mov_b32_e32 v94, v2
	v_mov_b32_e32 v95, v2
	v_mov_b32_e32 v96, v2
	v_mov_b32_e32 v97, v2
	v_mov_b32_e32 v114, v2
	v_mov_b32_e32 v115, v2
	v_mov_b32_e32 v116, v2
	v_mov_b32_e32 v117, v2
	v_mov_b32_e32 v118, v2
	v_mov_b32_e32 v119, v2
	v_mov_b32_e32 v120, v2
	v_mov_b32_e32 v121, v2
	v_mov_b32_e32 v122, v2
	v_mov_b32_e32 v123, v2
	v_mov_b32_e32 v124, v2
	v_mov_b32_e32 v125, v2
	v_mov_b32_e32 v126, v2
	v_mov_b32_e32 v127, v2
	v_mov_b32_e32 v128, v2
	v_mov_b32_e32 v129, v2
	s_waitcnt lgkmcnt(0)
	s_barrier
; #define A256_LOADH(kt_, hf_) { a0 = la.ld1(kt_, (hf_) * 4 + 0, tid); a1 = la.ld1(kt_, (hf_) * 4 + 1, tid); a2 = la.ld1(kt_, (hf_) * 4 + 2, tid); a3 = la.ld1(kt_, (hf_) * 4 + 3, tid); }
; template <bool swap, class LA>
; DI void gemm256_ws(const LA& la, const bf16_t* Wt, const int KS, const int nk, bf16_t* smem, f32x16 (&acc)[8]) {
;     ...
;   for (int kt = 0; kt < nk; kt++) {
;     const int cur = kt & 1; const int kn = (kt + 1 < nk) ? kt + 1 : last;
;     const bf16_t* sp = smem + cur * ATILE_E + aoff;
;     bf16_t* nxt = smem + (cur ^ 1) * ATILE_E;
;     A256_LOADH(kn, 0)
;     MMA256(0, w00, w10) W256_LD(kn, 0, w00, w10)
;     MMA256(1, w01, w11) W256_LD(kn, 1, w01, w11)
;     A256_STH(nxt, 0)
;     A256_LOADH(kn, 1)
;     MMA256(2, w02, w12) W256_LD(kn, 2, w02, w12)
;     MMA256(3, w03, w13) W256_LD(kn, 3, w03, w13)
;     A256_STH(nxt, 1)
;     __syncthreads();
;   }
	s_lshl_b32 s37, 1, 14
	s_add_u32 s12, s2, s37
	s_addc_u32 s13, s3, 0
	v_lshl_add_u64 v[204:205], s[12:13], 0, v[174:175]
	s_add_u32 s12, s12, 0x1000
	s_addc_u32 s13, s13, 0
	v_lshl_add_u64 v[208:209], s[12:13], 0, v[174:175]
	s_add_u32 s12, s12, 0x1000
	s_addc_u32 s13, s13, 0
	v_lshl_add_u64 v[216:217], s[12:13], 0, v[174:175]
	s_add_u32 s12, s12, 0x1000
	s_addc_u32 s13, s13, 0
	v_lshl_add_u64 v[220:221], s[12:13], 0, v[174:175]
	global_load_dwordx4 v[204:207], v[204:205], off
	global_load_dwordx4 v[208:211], v[208:209], off
	global_load_dwordx4 v[216:219], v[216:217], off
	global_load_dwordx4 v[220:223], v[220:221], off
	s_add_u32 s12, s10, s37
	s_addc_u32 s13, s11, 0
	v_lshl_add_u64 v[224:225], s[12:13], 0, v[174:175]
	s_add_u32 s12, s12, 0x1000
	s_addc_u32 s13, s13, 0
	v_lshl_add_u64 v[228:229], s[12:13], 0, v[174:175]
	s_add_u32 s12, s12, 0x1000
	s_addc_u32 s13, s13, 0
	v_lshl_add_u64 v[246:247], s[12:13], 0, v[174:175]
	s_add_u32 s12, s12, 0x1000
	s_addc_u32 s13, s13, 0
	v_lshl_add_u64 v[176:177], s[12:13], 0, v[174:175]
	global_load_dwordx4 v[224:227], v[224:225], off
	global_load_dwordx4 v[228:231], v[228:229], off
	global_load_dwordx4 v[246:249], v[246:247], off
	global_load_dwordx4 v[176:179], v[176:177], off
.LBB0_470:
	s_and_b32 s12, s29, 1
	s_mul_i32 s13, s12, 0x9000
	v_add_u32_e32 v0, s13, v183
	ds_read_b128 v[192:195], v0
	ds_read_b128 v[196:199], v0 offset:4608
	ds_read_b128 v[200:203], v0 offset:9216
	s_add_i32 s29, s29, 1
	s_min_u32 s36, s29, 15
	s_xor_b32 s12, s12, 1
	s_mul_i32 s13, s12, 0x9000
	v_add_u32_e32 v214, s13, v182
	s_lshl_b32 s90, s36, 12
	s_add_i32 s36, s29, 1
	s_min_u32 s36, s36, 15
	s_lshl_b32 s37, s36, 14
	s_waitcnt vmcnt(14) lgkmcnt(2)
	v_mfma_f32_32x32x16_bf16 v[98:113], v[154:157], v[192:195], v[98:113]
	v_mfma_f32_32x32x16_bf16 v[114:129], v[158:161], v[192:195], v[114:129]
	ds_read_b128 v[192:195], v0 offset:13824
	s_waitcnt lgkmcnt(2)
	v_mfma_f32_32x32x16_bf16 v[66:81], v[154:157], v[196:199], v[66:81]
	v_mfma_f32_32x32x16_bf16 v[82:97], v[158:161], v[196:199], v[82:97]
	ds_read_b128 v[196:199], v0 offset:32
	s_waitcnt lgkmcnt(2)
	v_mfma_f32_32x32x16_bf16 v[34:49], v[154:157], v[200:203], v[34:49]
	v_mfma_f32_32x32x16_bf16 v[50:65], v[158:161], v[200:203], v[50:65]
	ds_read_b128 v[200:203], v0 offset:4640
	s_waitcnt lgkmcnt(2)
	v_mfma_f32_32x32x16_bf16 v[2:17], v[154:157], v[192:195], v[2:17]
	v_mfma_f32_32x32x16_bf16 v[18:33], v[158:161], v[192:195], v[18:33]
	ds_read_b128 v[192:195], v0 offset:9248
	v_lshl_add_u64 v[154:155], v[186:187], 0, s[90:91]
	global_load_dwordx4 v[154:157], v[154:155], off
	v_lshl_add_u64 v[158:159], v[184:185], 0, s[90:91]
	global_load_dwordx4 v[158:161], v[158:159], off
	s_waitcnt vmcnt(14) lgkmcnt(2)
	v_mfma_f32_32x32x16_bf16 v[98:113], v[146:149], v[196:199], v[98:113]
	v_mfma_f32_32x32x16_bf16 v[114:129], v[150:153], v[196:199], v[114:129]
	ds_read_b128 v[196:199], v0 offset:13856
	s_waitcnt lgkmcnt(2)
	v_mfma_f32_32x32x16_bf16 v[66:81], v[146:149], v[200:203], v[66:81]
	v_mfma_f32_32x32x16_bf16 v[82:97], v[150:153], v[200:203], v[82:97]
	ds_read_b128 v[200:203], v0 offset:64
	s_waitcnt lgkmcnt(2)
	v_mfma_f32_32x32x16_bf16 v[34:49], v[146:149], v[192:195], v[34:49]
	v_mfma_f32_32x32x16_bf16 v[50:65], v[150:153], v[192:195], v[50:65]
	ds_read_b128 v[192:195], v0 offset:4672
	s_waitcnt lgkmcnt(2)
	v_mfma_f32_32x32x16_bf16 v[2:17], v[146:149], v[196:199], v[2:17]
	v_mfma_f32_32x32x16_bf16 v[18:33], v[150:153], v[196:199], v[18:33]
	ds_read_b128 v[196:199], v0 offset:9280
	v_lshl_add_u64 v[146:147], v[186:187], 0, s[90:91]
	global_load_dwordx4 v[146:149], v[146:147], off offset:1024
	v_lshl_add_u64 v[150:151], v[184:185], 0, s[90:91]
	global_load_dwordx4 v[150:153], v[150:151], off offset:1024
	s_waitcnt vmcnt(8)
	ds_write_b128 v214, v[204:207]
	ds_write_b128 v214, v[208:211] offset:4608
	ds_write_b128 v214, v[216:219] offset:9216
	ds_write_b128 v214, v[220:223] offset:13824
	s_add_u32 s12, s2, s37
	s_addc_u32 s13, s3, 0
	v_lshl_add_u64 v[204:205], s[12:13], 0, v[174:175]
	s_add_u32 s12, s12, 0x1000
	s_addc_u32 s13, s13, 0
	v_lshl_add_u64 v[208:209], s[12:13], 0, v[174:175]
	s_add_u32 s12, s12, 0x1000
	s_addc_u32 s13, s13, 0
	v_lshl_add_u64 v[216:217], s[12:13], 0, v[174:175]
	s_add_u32 s12, s12, 0x1000
	s_addc_u32 s13, s13, 0
	v_lshl_add_u64 v[220:221], s[12:13], 0, v[174:175]
	global_load_dwordx4 v[204:207], v[204:205], off
	global_load_dwordx4 v[208:211], v[208:209], off
	global_load_dwordx4 v[216:219], v[216:217], off
	global_load_dwordx4 v[220:223], v[220:221], off
	s_waitcnt lgkmcnt(6)
	v_mfma_f32_32x32x16_bf16 v[98:113], v[142:145], v[200:203], v[98:113]
	v_mfma_f32_32x32x16_bf16 v[114:129], v[138:141], v[200:203], v[114:129]
	ds_read_b128 v[200:203], v0 offset:13888
	s_waitcnt lgkmcnt(6)
	v_mfma_f32_32x32x16_bf16 v[66:81], v[142:145], v[192:195], v[66:81]
	v_mfma_f32_32x32x16_bf16 v[82:97], v[138:141], v[192:195], v[82:97]
	ds_read_b128 v[192:195], v0 offset:96
	s_waitcnt lgkmcnt(6)
	v_mfma_f32_32x32x16_bf16 v[34:49], v[142:145], v[196:199], v[34:49]
	v_mfma_f32_32x32x16_bf16 v[50:65], v[138:141], v[196:199], v[50:65]
	ds_read_b128 v[196:199], v0 offset:4704
	s_waitcnt lgkmcnt(2)
	v_mfma_f32_32x32x16_bf16 v[2:17], v[142:145], v[200:203], v[2:17]
	v_mfma_f32_32x32x16_bf16 v[18:33], v[138:141], v[200:203], v[18:33]
	ds_read_b128 v[200:203], v0 offset:9312
	v_lshl_add_u64 v[142:143], v[186:187], 0, s[90:91]
	global_load_dwordx4 v[142:145], v[142:143], off offset:2048
	v_lshl_add_u64 v[138:139], v[184:185], 0, s[90:91]
	global_load_dwordx4 v[138:141], v[138:139], off offset:2048
	s_waitcnt lgkmcnt(2)
; DI unsigned pk2(float a, float b) { f32v2 v = {a, b}; return __builtin_bit_cast(unsigned, __builtin_convertvector(v, bf16v2)); }
; DI float sigmoidf_(float v) { return 1.f / (1.f + __expf(-v)); }
; #define A256_LOADH(kt_, hf_) { a0 = la.ld1(kt_, (hf_) * 4 + 0, tid); a1 = la.ld1(kt_, (hf_) * 4 + 1, tid); a2 = la.ld1(kt_, (hf_) * 4 + 2, tid); a3 = la.ld1(kt_, (hf_) * 4 + 3, tid); }
; #define SW_FOR_TOK(j) _Pragma("unroll") for (int j = 0; j < 4; j++)
; #define SW_FOR_FEAT(i, rq) _Pragma("unroll") for (int i = 0; i < 2; i++) _Pragma("unroll") for (int rq = 0; rq < 4; rq++)
; template <bool swap, class LA>
; DI void gemm256_ws(const LA& la, const bf16_t* Wt, const int KS, const int nk, bf16_t* smem, f32x16 (&acc)[8]) {
;     ...
;   for (int kt = 0; kt < nk; kt++) {
;     const int cur = kt & 1; const int kn = (kt + 1 < nk) ? kt + 1 : last;
;     const bf16_t* sp = smem + cur * ATILE_E + aoff;
;     bf16_t* nxt = smem + (cur ^ 1) * ATILE_E;
;     A256_LOADH(kn, 0)
;     MMA256(0, w00, w10) W256_LD(kn, 0, w00, w10)
;     MMA256(1, w01, w11) W256_LD(kn, 1, w01, w11)
;     A256_STH(nxt, 0)
;     A256_LOADH(kn, 1)
;     MMA256(2, w02, w12) W256_LD(kn, 2, w02, w12)
;     MMA256(3, w03, w13) W256_LD(kn, 3, w03, w13)
;     A256_STH(nxt, 1)
;     __syncthreads();
;   }
; DI void ph_ple(const Params& P, int g, int layer, bf16_t* smem) {
;     ...
;     SW_FOR_TOK(j) { const int tl_ = wn * 128 + j * 32 + l32;
;       SW_FOR_FEAT(i, rq) { const int c_ = wm * 64 + i * 32 + 8 * rq + 4 * h;
;         *(uint2*)(smem + tl_ * EPLD + c_) = make_uint2(pk2(sigmoidf_(SWV(i, j, 4 * rq)), sigmoidf_(SWV(i, j, 4 * rq + 1))), pk2(sigmoidf_(SWV(i, j, 4 * rq + 2)), sigmoidf_(SWV(i, j, 4 * rq + 3)))); } }
	v_mfma_f32_32x32x16_bf16 v[98:113], v[130:133], v[192:195], v[98:113]
	v_mfma_f32_32x32x16_bf16 v[114:129], v[134:137], v[192:195], v[114:129]
	ds_read_b128 v[192:195], v0 offset:13920
	s_waitcnt lgkmcnt(2)
	v_mfma_f32_32x32x16_bf16 v[66:81], v[130:133], v[196:199], v[66:81]
	v_mfma_f32_32x32x16_bf16 v[82:97], v[134:137], v[196:199], v[82:97]
	s_waitcnt lgkmcnt(1)
	v_mfma_f32_32x32x16_bf16 v[34:49], v[130:133], v[200:203], v[34:49]
	v_mfma_f32_32x32x16_bf16 v[50:65], v[134:137], v[200:203], v[50:65]
	s_waitcnt lgkmcnt(0)
	v_mfma_f32_32x32x16_bf16 v[2:17], v[130:133], v[192:195], v[2:17]
	v_mfma_f32_32x32x16_bf16 v[18:33], v[134:137], v[192:195], v[18:33]
	v_lshl_add_u64 v[130:131], v[186:187], 0, s[90:91]
	global_load_dwordx4 v[130:133], v[130:131], off offset:3072
	v_lshl_add_u64 v[134:135], v[184:185], 0, s[90:91]
	global_load_dwordx4 v[134:137], v[134:135], off offset:3072
	s_waitcnt vmcnt(12)
	ds_write_b128 v214, v[224:227] offset:18432
	ds_write_b128 v214, v[228:231] offset:23040
	ds_write_b128 v214, v[246:249] offset:27648
	ds_write_b128 v214, v[176:179] offset:32256
	s_add_u32 s12, s10, s37
	s_addc_u32 s13, s11, 0
	v_lshl_add_u64 v[224:225], s[12:13], 0, v[174:175]
	s_add_u32 s12, s12, 0x1000
	s_addc_u32 s13, s13, 0
	v_lshl_add_u64 v[228:229], s[12:13], 0, v[174:175]
	s_add_u32 s12, s12, 0x1000
	s_addc_u32 s13, s13, 0
	v_lshl_add_u64 v[246:247], s[12:13], 0, v[174:175]
	s_add_u32 s12, s12, 0x1000
	s_addc_u32 s13, s13, 0
	v_lshl_add_u64 v[176:177], s[12:13], 0, v[174:175]
	global_load_dwordx4 v[224:227], v[224:225], off
	global_load_dwordx4 v[228:231], v[228:229], off
	global_load_dwordx4 v[246:249], v[246:247], off
	global_load_dwordx4 v[176:179], v[176:177], off
	s_cmp_lg_u32 s29, 16
	s_waitcnt lgkmcnt(0)
	s_barrier
	s_cbranch_scc1 .LBB0_470
	s_waitcnt vmcnt(0)
	v_mul_f32_e32 v0, 0xbfb8aa3b, v114
	v_exp_f32_e32 v114, v0
	v_mul_f32_e32 v0, 0xbfb8aa3b, v115
	v_exp_f32_e32 v115, v0
	s_nop 0
	v_pk_add_f32 v[114:115], v[114:115], 1.0 op_sel_hi:[1,0]
	s_nop 0
	v_div_scale_f32 v0, s[2:3], v115, v115, 1.0
	s_waitcnt vmcnt(0)
	v_rcp_f32_e32 v130, v0
	s_nop 0
	v_fma_f32 v131, -v0, v130, 1.0
	v_fmac_f32_e32 v130, v131, v130
	v_div_scale_f32 v131, vcc, 1.0, v115, 1.0
	v_mul_f32_e32 v132, v131, v130
	v_fma_f32 v133, -v0, v132, v131
	v_fmac_f32_e32 v132, v133, v130
	v_fma_f32 v0, -v0, v132, v131
	v_div_fmas_f32 v0, v0, v130, v132
	v_div_fixup_f32 v0, v0, v115, 1.0
	v_div_scale_f32 v115, s[2:3], v114, v114, 1.0
	v_rcp_f32_e32 v130, v115
	s_nop 0
	v_fma_f32 v131, -v115, v130, 1.0
	v_fmac_f32_e32 v130, v131, v130
	v_div_scale_f32 v131, vcc, 1.0, v114, 1.0
	v_mul_f32_e32 v132, v131, v130
	v_fma_f32 v133, -v115, v132, v131
	v_fmac_f32_e32 v132, v133, v130
	v_fma_f32 v115, -v115, v132, v131
	v_div_fmas_f32 v115, v115, v130, v132
	v_div_fixup_f32 v114, v115, v114, 1.0
	v_cvt_pk_bf16_f32 v114, v114, v0
	v_mul_f32_e32 v0, 0xbfb8aa3b, v116
	v_exp_f32_e32 v116, v0
	v_mul_f32_e32 v0, 0xbfb8aa3b, v117
	v_exp_f32_e32 v117, v0
	s_nop 0
	v_pk_add_f32 v[116:117], v[116:117], 1.0 op_sel_hi:[1,0]
	s_nop 0
	v_div_scale_f32 v0, s[2:3], v117, v117, 1.0
	v_rcp_f32_e32 v115, v0
	s_nop 0
	v_fma_f32 v130, -v0, v115, 1.0
	v_fmac_f32_e32 v115, v130, v115
	v_div_scale_f32 v130, vcc, 1.0, v117, 1.0
	v_mul_f32_e32 v131, v130, v115
	v_fma_f32 v132, -v0, v131, v130
	v_fmac_f32_e32 v131, v132, v115
	v_fma_f32 v0, -v0, v131, v130
	v_div_fmas_f32 v0, v0, v115, v131
	v_div_scale_f32 v115, s[2:3], v116, v116, 1.0
	v_div_fixup_f32 v0, v0, v117, 1.0
	v_rcp_f32_e32 v117, v115
	s_nop 0
	v_fma_f32 v130, -v115, v117, 1.0
	v_fmac_f32_e32 v117, v130, v117
	v_div_scale_f32 v130, vcc, 1.0, v116, 1.0
	v_mul_f32_e32 v131, v130, v117
	v_fma_f32 v132, -v115, v131, v130
	v_fmac_f32_e32 v131, v132, v117
	v_fma_f32 v115, -v115, v131, v130
	v_div_fmas_f32 v115, v115, v117, v131
	v_div_fixup_f32 v115, v115, v116, 1.0
	v_cvt_pk_bf16_f32 v115, v115, v0
	v_mul_f32_e32 v0, 0xbfb8aa3b, v118
	v_exp_f32_e32 v116, v0
	v_mul_f32_e32 v0, 0xbfb8aa3b, v119
	v_exp_f32_e32 v117, v0
	s_nop 0
	v_pk_add_f32 v[116:117], v[116:117], 1.0 op_sel_hi:[1,0]
	s_nop 0
	v_div_scale_f32 v0, s[2:3], v117, v117, 1.0
	v_rcp_f32_e32 v118, v0
	s_nop 0
	v_fma_f32 v119, -v0, v118, 1.0
	v_fmac_f32_e32 v118, v119, v118
	v_div_scale_f32 v119, vcc, 1.0, v117, 1.0
	v_mul_f32_e32 v130, v119, v118
	v_fma_f32 v131, -v0, v130, v119
	v_fmac_f32_e32 v130, v131, v118
	v_fma_f32 v0, -v0, v130, v119
	v_div_fmas_f32 v0, v0, v118, v130
	v_div_fixup_f32 v0, v0, v117, 1.0
	v_div_scale_f32 v117, s[2:3], v116, v116, 1.0
	v_rcp_f32_e32 v118, v117
	s_nop 0
	v_fma_f32 v119, -v117, v118, 1.0
	v_fmac_f32_e32 v118, v119, v118
	v_div_scale_f32 v119, vcc, 1.0, v116, 1.0
	v_mul_f32_e32 v130, v119, v118
	v_fma_f32 v131, -v117, v130, v119
	v_fmac_f32_e32 v130, v131, v118
	v_fma_f32 v117, -v117, v130, v119
	v_div_fmas_f32 v117, v117, v118, v130
	v_div_fixup_f32 v116, v117, v116, 1.0
	v_cvt_pk_bf16_f32 v116, v116, v0
	v_mul_f32_e32 v0, 0xbfb8aa3b, v120
	v_exp_f32_e32 v118, v0
	v_mul_f32_e32 v0, 0xbfb8aa3b, v121
	v_exp_f32_e32 v119, v0
	s_nop 0
	v_pk_add_f32 v[118:119], v[118:119], 1.0 op_sel_hi:[1,0]
	s_nop 0
	v_div_scale_f32 v0, s[2:3], v119, v119, 1.0
	v_rcp_f32_e32 v117, v0
	s_nop 0
	v_fma_f32 v120, -v0, v117, 1.0
	v_fmac_f32_e32 v117, v120, v117
	v_div_scale_f32 v120, vcc, 1.0, v119, 1.0
	v_mul_f32_e32 v121, v120, v117
	v_fma_f32 v130, -v0, v121, v120
	v_fmac_f32_e32 v121, v130, v117
	v_fma_f32 v0, -v0, v121, v120
	v_div_fmas_f32 v0, v0, v117, v121
	v_div_scale_f32 v117, s[2:3], v118, v118, 1.0
	v_div_fixup_f32 v0, v0, v119, 1.0
	v_rcp_f32_e32 v119, v117
	s_nop 0
	v_fma_f32 v120, -v117, v119, 1.0
	v_fmac_f32_e32 v119, v120, v119
	v_div_scale_f32 v120, vcc, 1.0, v118, 1.0
; DI unsigned pk2(float a, float b) { f32v2 v = {a, b}; return __builtin_bit_cast(unsigned, __builtin_convertvector(v, bf16v2)); }
; #define SW_FOR_TOK(j) _Pragma("unroll") for (int j = 0; j < 4; j++)
; #define SW_FOR_FEAT(i, rq) _Pragma("unroll") for (int i = 0; i < 2; i++) _Pragma("unroll") for (int rq = 0; rq < 4; rq++)
; DI float sigmoidf_(float v) { return 1.f / (1.f + __expf(-v)); }
; DI void ph_ple(const Params& P, int g, int layer, bf16_t* smem) {
;     ...
;     SW_FOR_TOK(j) { const int tl_ = wn * 128 + j * 32 + l32;
;       SW_FOR_FEAT(i, rq) { const int c_ = wm * 64 + i * 32 + 8 * rq + 4 * h;
;         *(uint2*)(smem + tl_ * EPLD + c_) = make_uint2(pk2(sigmoidf_(SWV(i, j, 4 * rq)), sigmoidf_(SWV(i, j, 4 * rq + 1))), pk2(sigmoidf_(SWV(i, j, 4 * rq + 2)), sigmoidf_(SWV(i, j, 4 * rq + 3)))); } }
	v_mul_f32_e32 v121, v120, v119
	v_fma_f32 v130, -v117, v121, v120
	v_fmac_f32_e32 v121, v130, v119
	v_fma_f32 v117, -v117, v121, v120
	v_div_fmas_f32 v117, v117, v119, v121
	v_div_fixup_f32 v117, v117, v118, 1.0
	v_cvt_pk_bf16_f32 v117, v117, v0
	v_mul_f32_e32 v0, 0xbfb8aa3b, v122
	ds_write2_b64 v165, v[114:115], v[116:117] offset1:2
	v_exp_f32_e32 v114, v0
	v_mul_f32_e32 v0, 0xbfb8aa3b, v123
	v_exp_f32_e32 v115, v0
	s_nop 0
	v_pk_add_f32 v[114:115], v[114:115], 1.0 op_sel_hi:[1,0]
	s_nop 0
	v_div_scale_f32 v0, s[2:3], v115, v115, 1.0
	v_rcp_f32_e32 v116, v0
	s_nop 0
	v_fma_f32 v117, -v0, v116, 1.0
	v_fmac_f32_e32 v116, v117, v116
	v_div_scale_f32 v117, vcc, 1.0, v115, 1.0
	v_mul_f32_e32 v118, v117, v116
	v_fma_f32 v119, -v0, v118, v117
	v_fmac_f32_e32 v118, v119, v116
	v_fma_f32 v0, -v0, v118, v117
	v_div_fmas_f32 v0, v0, v116, v118
	v_div_fixup_f32 v0, v0, v115, 1.0
	v_div_scale_f32 v115, s[2:3], v114, v114, 1.0
	v_rcp_f32_e32 v116, v115
	s_nop 0
	v_fma_f32 v117, -v115, v116, 1.0
	v_fmac_f32_e32 v116, v117, v116
	v_div_scale_f32 v117, vcc, 1.0, v114, 1.0
	v_mul_f32_e32 v118, v117, v116
	v_fma_f32 v119, -v115, v118, v117
	v_fmac_f32_e32 v118, v119, v116
	v_fma_f32 v115, -v115, v118, v117
	v_div_fmas_f32 v115, v115, v116, v118
	v_div_fixup_f32 v114, v115, v114, 1.0
	v_cvt_pk_bf16_f32 v114, v114, v0
	v_mul_f32_e32 v0, 0xbfb8aa3b, v124
	v_exp_f32_e32 v116, v0
	v_mul_f32_e32 v0, 0xbfb8aa3b, v125
	v_exp_f32_e32 v117, v0
	s_nop 0
	v_pk_add_f32 v[116:117], v[116:117], 1.0 op_sel_hi:[1,0]
	s_nop 0
	v_div_scale_f32 v0, s[2:3], v117, v117, 1.0
	v_rcp_f32_e32 v115, v0
	s_nop 0
	v_fma_f32 v118, -v0, v115, 1.0
	v_fmac_f32_e32 v115, v118, v115
	v_div_scale_f32 v118, vcc, 1.0, v117, 1.0
	v_mul_f32_e32 v119, v118, v115
	v_fma_f32 v120, -v0, v119, v118
	v_fmac_f32_e32 v119, v120, v115
	v_fma_f32 v0, -v0, v119, v118
	v_div_fmas_f32 v0, v0, v115, v119
	v_div_scale_f32 v115, s[2:3], v116, v116, 1.0
	v_div_fixup_f32 v0, v0, v117, 1.0
	v_rcp_f32_e32 v117, v115
	s_nop 0
	v_fma_f32 v118, -v115, v117, 1.0
	v_fmac_f32_e32 v117, v118, v117
	v_div_scale_f32 v118, vcc, 1.0, v116, 1.0
	v_mul_f32_e32 v119, v118, v117
	v_fma_f32 v120, -v115, v119, v118
	v_fmac_f32_e32 v119, v120, v117
	v_fma_f32 v115, -v115, v119, v118
	v_div_fmas_f32 v115, v115, v117, v119
	v_div_fixup_f32 v115, v115, v116, 1.0
	v_cvt_pk_bf16_f32 v115, v115, v0
	v_mul_f32_e32 v0, 0xbfb8aa3b, v126
	v_exp_f32_e32 v116, v0
	v_mul_f32_e32 v0, 0xbfb8aa3b, v127
	v_exp_f32_e32 v117, v0
	s_nop 0
	v_pk_add_f32 v[116:117], v[116:117], 1.0 op_sel_hi:[1,0]
	s_nop 0
	v_div_scale_f32 v0, s[2:3], v117, v117, 1.0
	v_rcp_f32_e32 v118, v0
	s_nop 0
	v_fma_f32 v119, -v0, v118, 1.0
	v_fmac_f32_e32 v118, v119, v118
	v_div_scale_f32 v119, vcc, 1.0, v117, 1.0
	v_mul_f32_e32 v120, v119, v118
	v_fma_f32 v121, -v0, v120, v119
	v_fmac_f32_e32 v120, v121, v118
	v_fma_f32 v0, -v0, v120, v119
	v_div_fmas_f32 v0, v0, v118, v120
	v_div_fixup_f32 v0, v0, v117, 1.0
	v_div_scale_f32 v117, s[2:3], v116, v116, 1.0
	v_rcp_f32_e32 v118, v117
	s_nop 0
	v_fma_f32 v119, -v117, v118, 1.0
	v_fmac_f32_e32 v118, v119, v118
	v_div_scale_f32 v119, vcc, 1.0, v116, 1.0
	v_mul_f32_e32 v120, v119, v118
	v_fma_f32 v121, -v117, v120, v119
	v_fmac_f32_e32 v120, v121, v118
	v_fma_f32 v117, -v117, v120, v119
	v_div_fmas_f32 v117, v117, v118, v120
	v_div_fixup_f32 v116, v117, v116, 1.0
	v_cvt_pk_bf16_f32 v116, v116, v0
	v_mul_f32_e32 v0, 0xbfb8aa3b, v128
	v_exp_f32_e32 v118, v0
	v_mul_f32_e32 v0, 0xbfb8aa3b, v129
	v_exp_f32_e32 v119, v0
	s_nop 0
	v_pk_add_f32 v[118:119], v[118:119], 1.0 op_sel_hi:[1,0]
	s_nop 0
	v_div_scale_f32 v0, s[2:3], v119, v119, 1.0
	v_rcp_f32_e32 v117, v0
	s_nop 0
	v_fma_f32 v120, -v0, v117, 1.0
	v_fmac_f32_e32 v117, v120, v117
	v_div_scale_f32 v120, vcc, 1.0, v119, 1.0
	v_mul_f32_e32 v121, v120, v117
	v_fma_f32 v122, -v0, v121, v120
	v_fmac_f32_e32 v121, v122, v117
	v_fma_f32 v0, -v0, v121, v120
	v_div_fmas_f32 v0, v0, v117, v121
	v_div_scale_f32 v117, s[2:3], v118, v118, 1.0
	v_div_fixup_f32 v0, v0, v119, 1.0
	v_rcp_f32_e32 v119, v117
	s_nop 0
	v_fma_f32 v120, -v117, v119, 1.0
	v_fmac_f32_e32 v119, v120, v119
	v_div_scale_f32 v120, vcc, 1.0, v118, 1.0
	v_mul_f32_e32 v121, v120, v119
	v_fma_f32 v122, -v117, v121, v120
	v_fmac_f32_e32 v121, v122, v119
	v_fma_f32 v117, -v117, v121, v120
	v_div_fmas_f32 v117, v117, v119, v121
	v_div_fixup_f32 v117, v117, v118, 1.0
	v_cvt_pk_bf16_f32 v117, v117, v0
	v_mul_f32_e32 v0, 0xbfb8aa3b, v98
	v_exp_f32_e32 v98, v0
	v_mul_f32_e32 v0, 0xbfb8aa3b, v99
	v_exp_f32_e32 v99, v0
	ds_write2_b64 v165, v[114:115], v[116:117] offset0:4 offset1:6
	v_pk_add_f32 v[98:99], v[98:99], 1.0 op_sel_hi:[1,0]
	s_nop 0
	v_div_scale_f32 v0, s[2:3], v99, v99, 1.0
	v_rcp_f32_e32 v114, v0
	s_nop 0
	v_fma_f32 v115, -v0, v114, 1.0
	v_fmac_f32_e32 v114, v115, v114
	v_div_scale_f32 v115, vcc, 1.0, v99, 1.0
	v_mul_f32_e32 v116, v115, v114
	v_fma_f32 v117, -v0, v116, v115
	v_fmac_f32_e32 v116, v117, v114
	v_fma_f32 v0, -v0, v116, v115
	v_div_fmas_f32 v0, v0, v114, v116
	v_div_fixup_f32 v0, v0, v99, 1.0
	v_div_scale_f32 v99, s[2:3], v98, v98, 1.0
	v_rcp_f32_e32 v114, v99
	s_nop 0
	v_fma_f32 v115, -v99, v114, 1.0
	v_fmac_f32_e32 v114, v115, v114
	v_div_scale_f32 v115, vcc, 1.0, v98, 1.0
	v_mul_f32_e32 v116, v115, v114
	v_fma_f32 v117, -v99, v116, v115
	v_fmac_f32_e32 v116, v117, v114
	v_fma_f32 v99, -v99, v116, v115
	v_div_fmas_f32 v99, v99, v114, v116
	v_div_fixup_f32 v98, v99, v98, 1.0
	v_cvt_pk_bf16_f32 v98, v98, v0
	v_mul_f32_e32 v0, 0xbfb8aa3b, v100
	v_exp_f32_e32 v100, v0
	v_mul_f32_e32 v0, 0xbfb8aa3b, v101
	v_exp_f32_e32 v101, v0
	s_nop 0
	v_pk_add_f32 v[100:101], v[100:101], 1.0 op_sel_hi:[1,0]
	s_nop 0
; DI unsigned pk2(float a, float b) { f32v2 v = {a, b}; return __builtin_bit_cast(unsigned, __builtin_convertvector(v, bf16v2)); }
; #define SW_FOR_TOK(j) _Pragma("unroll") for (int j = 0; j < 4; j++)
; #define SW_FOR_FEAT(i, rq) _Pragma("unroll") for (int i = 0; i < 2; i++) _Pragma("unroll") for (int rq = 0; rq < 4; rq++)
; DI float sigmoidf_(float v) { return 1.f / (1.f + __expf(-v)); }
; DI void ph_ple(const Params& P, int g, int layer, bf16_t* smem) {
;     ...
;     SW_FOR_TOK(j) { const int tl_ = wn * 128 + j * 32 + l32;
;       SW_FOR_FEAT(i, rq) { const int c_ = wm * 64 + i * 32 + 8 * rq + 4 * h;
;         *(uint2*)(smem + tl_ * EPLD + c_) = make_uint2(pk2(sigmoidf_(SWV(i, j, 4 * rq)), sigmoidf_(SWV(i, j, 4 * rq + 1))), pk2(sigmoidf_(SWV(i, j, 4 * rq + 2)), sigmoidf_(SWV(i, j, 4 * rq + 3)))); } }
	v_div_scale_f32 v0, s[2:3], v101, v101, 1.0
	v_rcp_f32_e32 v99, v0
	s_nop 0
	v_fma_f32 v114, -v0, v99, 1.0
	v_fmac_f32_e32 v99, v114, v99
	v_div_scale_f32 v114, vcc, 1.0, v101, 1.0
	v_mul_f32_e32 v115, v114, v99
	v_fma_f32 v116, -v0, v115, v114
	v_fmac_f32_e32 v115, v116, v99
	v_fma_f32 v0, -v0, v115, v114
	v_div_fmas_f32 v0, v0, v99, v115
	v_div_scale_f32 v99, s[2:3], v100, v100, 1.0
	v_div_fixup_f32 v0, v0, v101, 1.0
	v_rcp_f32_e32 v101, v99
	s_nop 0
	v_fma_f32 v114, -v99, v101, 1.0
	v_fmac_f32_e32 v101, v114, v101
	v_div_scale_f32 v114, vcc, 1.0, v100, 1.0
	v_mul_f32_e32 v115, v114, v101
	v_fma_f32 v116, -v99, v115, v114
	v_fmac_f32_e32 v115, v116, v101
	v_fma_f32 v99, -v99, v115, v114
	v_div_fmas_f32 v99, v99, v101, v115
	v_div_fixup_f32 v99, v99, v100, 1.0
	v_cvt_pk_bf16_f32 v99, v99, v0
	v_mul_f32_e32 v0, 0xbfb8aa3b, v102
	v_exp_f32_e32 v100, v0
	v_mul_f32_e32 v0, 0xbfb8aa3b, v103
	v_exp_f32_e32 v101, v0
	s_nop 0
	v_pk_add_f32 v[100:101], v[100:101], 1.0 op_sel_hi:[1,0]
	s_nop 0
	v_div_scale_f32 v0, s[2:3], v101, v101, 1.0
	v_rcp_f32_e32 v102, v0
	s_nop 0
	v_fma_f32 v103, -v0, v102, 1.0
	v_fmac_f32_e32 v102, v103, v102
	v_div_scale_f32 v103, vcc, 1.0, v101, 1.0
	v_mul_f32_e32 v114, v103, v102
	v_fma_f32 v115, -v0, v114, v103
	v_fmac_f32_e32 v114, v115, v102
	v_fma_f32 v0, -v0, v114, v103
	v_div_fmas_f32 v0, v0, v102, v114
	v_div_fixup_f32 v0, v0, v101, 1.0
	v_div_scale_f32 v101, s[2:3], v100, v100, 1.0
	v_rcp_f32_e32 v102, v101
	s_nop 0
	v_fma_f32 v103, -v101, v102, 1.0
	v_fmac_f32_e32 v102, v103, v102
	v_div_scale_f32 v103, vcc, 1.0, v100, 1.0
	v_mul_f32_e32 v114, v103, v102
	v_fma_f32 v115, -v101, v114, v103
	v_fmac_f32_e32 v114, v115, v102
	v_fma_f32 v101, -v101, v114, v103
	v_div_fmas_f32 v101, v101, v102, v114
	v_div_fixup_f32 v100, v101, v100, 1.0
	v_cvt_pk_bf16_f32 v100, v100, v0
	v_mul_f32_e32 v0, 0xbfb8aa3b, v104
	v_exp_f32_e32 v102, v0
	v_mul_f32_e32 v0, 0xbfb8aa3b, v105
	v_exp_f32_e32 v103, v0
	s_nop 0
	v_pk_add_f32 v[102:103], v[102:103], 1.0 op_sel_hi:[1,0]
	s_nop 0
	v_div_scale_f32 v0, s[2:3], v103, v103, 1.0
	v_rcp_f32_e32 v101, v0
	s_nop 0
	v_fma_f32 v104, -v0, v101, 1.0
	v_fmac_f32_e32 v101, v104, v101
	v_div_scale_f32 v104, vcc, 1.0, v103, 1.0
	v_mul_f32_e32 v105, v104, v101
	v_fma_f32 v114, -v0, v105, v104
	v_fmac_f32_e32 v105, v114, v101
	v_fma_f32 v0, -v0, v105, v104
	v_div_fmas_f32 v0, v0, v101, v105
	v_div_scale_f32 v101, s[2:3], v102, v102, 1.0
	v_div_fixup_f32 v0, v0, v103, 1.0
	v_rcp_f32_e32 v103, v101
	s_nop 0
	v_fma_f32 v104, -v101, v103, 1.0
	v_fmac_f32_e32 v103, v104, v103
	v_div_scale_f32 v104, vcc, 1.0, v102, 1.0
	v_mul_f32_e32 v105, v104, v103
	v_fma_f32 v114, -v101, v105, v104
	v_fmac_f32_e32 v105, v114, v103
	v_fma_f32 v101, -v101, v105, v104
	v_div_fmas_f32 v101, v101, v103, v105
	v_div_fixup_f32 v101, v101, v102, 1.0
	v_cvt_pk_bf16_f32 v101, v101, v0
	v_mul_f32_e32 v0, 0xbfb8aa3b, v106
	ds_write2_b64 v165, v[98:99], v[100:101] offset0:8 offset1:10
	v_exp_f32_e32 v98, v0
	v_mul_f32_e32 v0, 0xbfb8aa3b, v107
	v_exp_f32_e32 v99, v0
	s_nop 0
	v_pk_add_f32 v[98:99], v[98:99], 1.0 op_sel_hi:[1,0]
	s_nop 0
	v_div_scale_f32 v0, s[2:3], v99, v99, 1.0
	v_rcp_f32_e32 v100, v0
	s_nop 0
	v_fma_f32 v101, -v0, v100, 1.0
	v_fmac_f32_e32 v100, v101, v100
	v_div_scale_f32 v101, vcc, 1.0, v99, 1.0
	v_mul_f32_e32 v102, v101, v100
	v_fma_f32 v103, -v0, v102, v101
	v_fmac_f32_e32 v102, v103, v100
	v_fma_f32 v0, -v0, v102, v101
	v_div_fmas_f32 v0, v0, v100, v102
	v_div_fixup_f32 v0, v0, v99, 1.0
	v_div_scale_f32 v99, s[2:3], v98, v98, 1.0
	v_rcp_f32_e32 v100, v99
	s_nop 0
	v_fma_f32 v101, -v99, v100, 1.0
	v_fmac_f32_e32 v100, v101, v100
	v_div_scale_f32 v101, vcc, 1.0, v98, 1.0
	v_mul_f32_e32 v102, v101, v100
	v_fma_f32 v103, -v99, v102, v101
	v_fmac_f32_e32 v102, v103, v100
	v_fma_f32 v99, -v99, v102, v101
	v_div_fmas_f32 v99, v99, v100, v102
	v_div_fixup_f32 v98, v99, v98, 1.0
	v_cvt_pk_bf16_f32 v98, v98, v0
	v_mul_f32_e32 v0, 0xbfb8aa3b, v108
	v_exp_f32_e32 v100, v0
	v_mul_f32_e32 v0, 0xbfb8aa3b, v109
	v_exp_f32_e32 v101, v0
	s_nop 0
	v_pk_add_f32 v[100:101], v[100:101], 1.0 op_sel_hi:[1,0]
	s_nop 0
	v_div_scale_f32 v0, s[2:3], v101, v101, 1.0
	v_rcp_f32_e32 v99, v0
	s_nop 0
	v_fma_f32 v102, -v0, v99, 1.0
	v_fmac_f32_e32 v99, v102, v99
	v_div_scale_f32 v102, vcc, 1.0, v101, 1.0
	v_mul_f32_e32 v103, v102, v99
	v_fma_f32 v104, -v0, v103, v102
	v_fmac_f32_e32 v103, v104, v99
	v_fma_f32 v0, -v0, v103, v102
	v_div_fmas_f32 v0, v0, v99, v103
	v_div_scale_f32 v99, s[2:3], v100, v100, 1.0
	v_div_fixup_f32 v0, v0, v101, 1.0
	v_rcp_f32_e32 v101, v99
	s_nop 0
	v_fma_f32 v102, -v99, v101, 1.0
	v_fmac_f32_e32 v101, v102, v101
	v_div_scale_f32 v102, vcc, 1.0, v100, 1.0
	v_mul_f32_e32 v103, v102, v101
	v_fma_f32 v104, -v99, v103, v102
	v_fmac_f32_e32 v103, v104, v101
	v_fma_f32 v99, -v99, v103, v102
	v_div_fmas_f32 v99, v99, v101, v103
	v_div_fixup_f32 v99, v99, v100, 1.0
	v_cvt_pk_bf16_f32 v99, v99, v0
	v_mul_f32_e32 v0, 0xbfb8aa3b, v110
	v_exp_f32_e32 v100, v0
	v_mul_f32_e32 v0, 0xbfb8aa3b, v111
	v_exp_f32_e32 v101, v0
	s_nop 0
	v_pk_add_f32 v[100:101], v[100:101], 1.0 op_sel_hi:[1,0]
	s_nop 0
	v_div_scale_f32 v0, s[2:3], v101, v101, 1.0
	v_rcp_f32_e32 v102, v0
	s_nop 0
	v_fma_f32 v103, -v0, v102, 1.0
	v_fmac_f32_e32 v102, v103, v102
	v_div_scale_f32 v103, vcc, 1.0, v101, 1.0
	v_mul_f32_e32 v104, v103, v102
	v_fma_f32 v105, -v0, v104, v103
	v_fmac_f32_e32 v104, v105, v102
	v_fma_f32 v0, -v0, v104, v103
	v_div_fmas_f32 v0, v0, v102, v104
	v_div_fixup_f32 v0, v0, v101, 1.0
	v_div_scale_f32 v101, s[2:3], v100, v100, 1.0
	v_rcp_f32_e32 v102, v101
	s_nop 0
	v_fma_f32 v103, -v101, v102, 1.0
	v_fmac_f32_e32 v102, v103, v102
; DI unsigned pk2(float a, float b) { f32v2 v = {a, b}; return __builtin_bit_cast(unsigned, __builtin_convertvector(v, bf16v2)); }
; #define SW_FOR_TOK(j) _Pragma("unroll") for (int j = 0; j < 4; j++)
; #define SW_FOR_FEAT(i, rq) _Pragma("unroll") for (int i = 0; i < 2; i++) _Pragma("unroll") for (int rq = 0; rq < 4; rq++)
; DI float sigmoidf_(float v) { return 1.f / (1.f + __expf(-v)); }
; DI void ph_ple(const Params& P, int g, int layer, bf16_t* smem) {
;     ...
;     SW_FOR_TOK(j) { const int tl_ = wn * 128 + j * 32 + l32;
;       SW_FOR_FEAT(i, rq) { const int c_ = wm * 64 + i * 32 + 8 * rq + 4 * h;
;         *(uint2*)(smem + tl_ * EPLD + c_) = make_uint2(pk2(sigmoidf_(SWV(i, j, 4 * rq)), sigmoidf_(SWV(i, j, 4 * rq + 1))), pk2(sigmoidf_(SWV(i, j, 4 * rq + 2)), sigmoidf_(SWV(i, j, 4 * rq + 3)))); } }
	v_div_scale_f32 v103, vcc, 1.0, v100, 1.0
	v_mul_f32_e32 v104, v103, v102
	v_fma_f32 v105, -v101, v104, v103
	v_fmac_f32_e32 v104, v105, v102
	v_fma_f32 v101, -v101, v104, v103
	v_div_fmas_f32 v101, v101, v102, v104
	v_div_fixup_f32 v100, v101, v100, 1.0
	v_cvt_pk_bf16_f32 v100, v100, v0
	v_mul_f32_e32 v0, 0xbfb8aa3b, v112
	v_exp_f32_e32 v102, v0
	v_mul_f32_e32 v0, 0xbfb8aa3b, v113
	v_exp_f32_e32 v103, v0
	s_nop 0
	v_pk_add_f32 v[102:103], v[102:103], 1.0 op_sel_hi:[1,0]
	s_nop 0
	v_div_scale_f32 v0, s[2:3], v103, v103, 1.0
	v_rcp_f32_e32 v101, v0
	s_nop 0
	v_fma_f32 v104, -v0, v101, 1.0
	v_fmac_f32_e32 v101, v104, v101
	v_div_scale_f32 v104, vcc, 1.0, v103, 1.0
	v_mul_f32_e32 v105, v104, v101
	v_fma_f32 v106, -v0, v105, v104
	v_fmac_f32_e32 v105, v106, v101
	v_fma_f32 v0, -v0, v105, v104
	v_div_fmas_f32 v0, v0, v101, v105
	v_div_scale_f32 v101, s[2:3], v102, v102, 1.0
	v_div_fixup_f32 v0, v0, v103, 1.0
	v_rcp_f32_e32 v103, v101
	s_nop 0
	v_fma_f32 v104, -v101, v103, 1.0
	v_fmac_f32_e32 v103, v104, v103
	v_div_scale_f32 v104, vcc, 1.0, v102, 1.0
	v_mul_f32_e32 v105, v104, v103
	v_fma_f32 v106, -v101, v105, v104
	v_fmac_f32_e32 v105, v106, v103
	v_fma_f32 v101, -v101, v105, v104
	v_div_fmas_f32 v101, v101, v103, v105
	v_div_fixup_f32 v101, v101, v102, 1.0
	v_cvt_pk_bf16_f32 v101, v101, v0
	v_mul_f32_e32 v0, 0xbfb8aa3b, v82
	v_exp_f32_e32 v82, v0
	v_mul_f32_e32 v0, 0xbfb8aa3b, v83
	v_exp_f32_e32 v83, v0
	ds_write2_b64 v165, v[98:99], v[100:101] offset0:12 offset1:14
	v_pk_add_f32 v[82:83], v[82:83], 1.0 op_sel_hi:[1,0]
	s_nop 0
	v_div_scale_f32 v0, s[2:3], v83, v83, 1.0
	v_rcp_f32_e32 v98, v0
	s_nop 0
	v_fma_f32 v99, -v0, v98, 1.0
	v_fmac_f32_e32 v98, v99, v98
	v_div_scale_f32 v99, vcc, 1.0, v83, 1.0
	v_mul_f32_e32 v100, v99, v98
	v_fma_f32 v101, -v0, v100, v99
	v_fmac_f32_e32 v100, v101, v98
	v_fma_f32 v0, -v0, v100, v99
	v_div_fmas_f32 v0, v0, v98, v100
	v_div_fixup_f32 v0, v0, v83, 1.0
	v_div_scale_f32 v83, s[2:3], v82, v82, 1.0
	v_rcp_f32_e32 v98, v83
	s_nop 0
	v_fma_f32 v99, -v83, v98, 1.0
	v_fmac_f32_e32 v98, v99, v98
	v_div_scale_f32 v99, vcc, 1.0, v82, 1.0
	v_mul_f32_e32 v100, v99, v98
	v_fma_f32 v101, -v83, v100, v99
	v_fmac_f32_e32 v100, v101, v98
	v_fma_f32 v83, -v83, v100, v99
	v_div_fmas_f32 v83, v83, v98, v100
	v_div_fixup_f32 v82, v83, v82, 1.0
	v_cvt_pk_bf16_f32 v82, v82, v0
	v_mul_f32_e32 v0, 0xbfb8aa3b, v84
	v_exp_f32_e32 v84, v0
	v_mul_f32_e32 v0, 0xbfb8aa3b, v85
	v_exp_f32_e32 v85, v0
	s_nop 0
	v_pk_add_f32 v[84:85], v[84:85], 1.0 op_sel_hi:[1,0]
	s_nop 0
	v_div_scale_f32 v0, s[2:3], v85, v85, 1.0
	v_rcp_f32_e32 v83, v0
	s_nop 0
	v_fma_f32 v98, -v0, v83, 1.0
	v_fmac_f32_e32 v83, v98, v83
	v_div_scale_f32 v98, vcc, 1.0, v85, 1.0
	v_mul_f32_e32 v99, v98, v83
	v_fma_f32 v100, -v0, v99, v98
	v_fmac_f32_e32 v99, v100, v83
	v_fma_f32 v0, -v0, v99, v98
	v_div_fmas_f32 v0, v0, v83, v99
	v_div_scale_f32 v83, s[2:3], v84, v84, 1.0
	v_div_fixup_f32 v0, v0, v85, 1.0
	v_rcp_f32_e32 v85, v83
	s_nop 0
	v_fma_f32 v98, -v83, v85, 1.0
	v_fmac_f32_e32 v85, v98, v85
	v_div_scale_f32 v98, vcc, 1.0, v84, 1.0
	v_mul_f32_e32 v99, v98, v85
	v_fma_f32 v100, -v83, v99, v98
	v_fmac_f32_e32 v99, v100, v85
	v_fma_f32 v83, -v83, v99, v98
	v_div_fmas_f32 v83, v83, v85, v99
	v_div_fixup_f32 v83, v83, v84, 1.0
	v_cvt_pk_bf16_f32 v83, v83, v0
	v_mul_f32_e32 v0, 0xbfb8aa3b, v86
	v_exp_f32_e32 v84, v0
	v_mul_f32_e32 v0, 0xbfb8aa3b, v87
	v_exp_f32_e32 v85, v0
	s_nop 0
	v_pk_add_f32 v[84:85], v[84:85], 1.0 op_sel_hi:[1,0]
	s_nop 0
	v_div_scale_f32 v0, s[2:3], v85, v85, 1.0
	v_rcp_f32_e32 v86, v0
	s_nop 0
	v_fma_f32 v87, -v0, v86, 1.0
	v_fmac_f32_e32 v86, v87, v86
	v_div_scale_f32 v87, vcc, 1.0, v85, 1.0
	v_mul_f32_e32 v98, v87, v86
	v_fma_f32 v99, -v0, v98, v87
	v_fmac_f32_e32 v98, v99, v86
	v_fma_f32 v0, -v0, v98, v87
	v_div_fmas_f32 v0, v0, v86, v98
	v_div_fixup_f32 v0, v0, v85, 1.0
	v_div_scale_f32 v85, s[2:3], v84, v84, 1.0
	v_rcp_f32_e32 v86, v85
	s_nop 0
	v_fma_f32 v87, -v85, v86, 1.0
	v_fmac_f32_e32 v86, v87, v86
	v_div_scale_f32 v87, vcc, 1.0, v84, 1.0
	v_mul_f32_e32 v98, v87, v86
	v_fma_f32 v99, -v85, v98, v87
	v_fmac_f32_e32 v98, v99, v86
	v_fma_f32 v85, -v85, v98, v87
	v_div_fmas_f32 v85, v85, v86, v98
	v_div_fixup_f32 v84, v85, v84, 1.0
	v_cvt_pk_bf16_f32 v84, v84, v0
	v_mul_f32_e32 v0, 0xbfb8aa3b, v88
	v_exp_f32_e32 v86, v0
	v_mul_f32_e32 v0, 0xbfb8aa3b, v89
	v_exp_f32_e32 v87, v0
	s_nop 0
	v_pk_add_f32 v[86:87], v[86:87], 1.0 op_sel_hi:[1,0]
	s_nop 0
	v_div_scale_f32 v0, s[2:3], v87, v87, 1.0
	v_rcp_f32_e32 v85, v0
	s_nop 0
	v_fma_f32 v88, -v0, v85, 1.0
	v_fmac_f32_e32 v85, v88, v85
	v_div_scale_f32 v88, vcc, 1.0, v87, 1.0
	v_mul_f32_e32 v89, v88, v85
	v_fma_f32 v98, -v0, v89, v88
	v_fmac_f32_e32 v89, v98, v85
	v_fma_f32 v0, -v0, v89, v88
	v_div_fmas_f32 v0, v0, v85, v89
	v_div_scale_f32 v85, s[2:3], v86, v86, 1.0
	v_div_fixup_f32 v0, v0, v87, 1.0
	v_rcp_f32_e32 v87, v85
	s_nop 0
	v_fma_f32 v88, -v85, v87, 1.0
	v_fmac_f32_e32 v87, v88, v87
	v_div_scale_f32 v88, vcc, 1.0, v86, 1.0
	v_mul_f32_e32 v89, v88, v87
	v_fma_f32 v98, -v85, v89, v88
	v_fmac_f32_e32 v89, v98, v87
	v_fma_f32 v85, -v85, v89, v88
	v_div_fmas_f32 v85, v85, v87, v89
	v_div_fixup_f32 v85, v85, v86, 1.0
	v_cvt_pk_bf16_f32 v85, v85, v0
	v_mul_f32_e32 v0, 0xbfb8aa3b, v90
	ds_write2_b64 v191, v[82:83], v[84:85] offset0:64 offset1:66
	v_exp_f32_e32 v82, v0
	v_mul_f32_e32 v0, 0xbfb8aa3b, v91
	v_exp_f32_e32 v83, v0
	s_nop 0
	v_pk_add_f32 v[82:83], v[82:83], 1.0 op_sel_hi:[1,0]
	s_nop 0
	v_div_scale_f32 v0, s[2:3], v83, v83, 1.0
	v_rcp_f32_e32 v84, v0
	s_nop 0
	v_fma_f32 v85, -v0, v84, 1.0
	v_fmac_f32_e32 v84, v85, v84
	v_div_scale_f32 v85, vcc, 1.0, v83, 1.0
	v_mul_f32_e32 v86, v85, v84
; DI unsigned pk2(float a, float b) { f32v2 v = {a, b}; return __builtin_bit_cast(unsigned, __builtin_convertvector(v, bf16v2)); }
; #define SW_FOR_TOK(j) _Pragma("unroll") for (int j = 0; j < 4; j++)
; #define SW_FOR_FEAT(i, rq) _Pragma("unroll") for (int i = 0; i < 2; i++) _Pragma("unroll") for (int rq = 0; rq < 4; rq++)
; DI float sigmoidf_(float v) { return 1.f / (1.f + __expf(-v)); }
; DI void ph_ple(const Params& P, int g, int layer, bf16_t* smem) {
;     ...
;     SW_FOR_TOK(j) { const int tl_ = wn * 128 + j * 32 + l32;
;       SW_FOR_FEAT(i, rq) { const int c_ = wm * 64 + i * 32 + 8 * rq + 4 * h;
;         *(uint2*)(smem + tl_ * EPLD + c_) = make_uint2(pk2(sigmoidf_(SWV(i, j, 4 * rq)), sigmoidf_(SWV(i, j, 4 * rq + 1))), pk2(sigmoidf_(SWV(i, j, 4 * rq + 2)), sigmoidf_(SWV(i, j, 4 * rq + 3)))); } }
	v_fma_f32 v87, -v0, v86, v85
	v_fmac_f32_e32 v86, v87, v84
	v_fma_f32 v0, -v0, v86, v85
	v_div_fmas_f32 v0, v0, v84, v86
	v_div_fixup_f32 v0, v0, v83, 1.0
	v_div_scale_f32 v83, s[2:3], v82, v82, 1.0
	v_rcp_f32_e32 v84, v83
	s_nop 0
	v_fma_f32 v85, -v83, v84, 1.0
	v_fmac_f32_e32 v84, v85, v84
	v_div_scale_f32 v85, vcc, 1.0, v82, 1.0
	v_mul_f32_e32 v86, v85, v84
	v_fma_f32 v87, -v83, v86, v85
	v_fmac_f32_e32 v86, v87, v84
	v_fma_f32 v83, -v83, v86, v85
	v_div_fmas_f32 v83, v83, v84, v86
	v_div_fixup_f32 v82, v83, v82, 1.0
	v_cvt_pk_bf16_f32 v82, v82, v0
	v_mul_f32_e32 v0, 0xbfb8aa3b, v92
	v_exp_f32_e32 v84, v0
	v_mul_f32_e32 v0, 0xbfb8aa3b, v93
	v_exp_f32_e32 v85, v0
	s_nop 0
	v_pk_add_f32 v[84:85], v[84:85], 1.0 op_sel_hi:[1,0]
	s_nop 0
	v_div_scale_f32 v0, s[2:3], v85, v85, 1.0
	v_rcp_f32_e32 v83, v0
	s_nop 0
	v_fma_f32 v86, -v0, v83, 1.0
	v_fmac_f32_e32 v83, v86, v83
	v_div_scale_f32 v86, vcc, 1.0, v85, 1.0
	v_mul_f32_e32 v87, v86, v83
	v_fma_f32 v88, -v0, v87, v86
	v_fmac_f32_e32 v87, v88, v83
	v_fma_f32 v0, -v0, v87, v86
	v_div_fmas_f32 v0, v0, v83, v87
	v_div_scale_f32 v83, s[2:3], v84, v84, 1.0
	v_div_fixup_f32 v0, v0, v85, 1.0
	v_rcp_f32_e32 v85, v83
	s_nop 0
	v_fma_f32 v86, -v83, v85, 1.0
	v_fmac_f32_e32 v85, v86, v85
	v_div_scale_f32 v86, vcc, 1.0, v84, 1.0
	v_mul_f32_e32 v87, v86, v85
	v_fma_f32 v88, -v83, v87, v86
	v_fmac_f32_e32 v87, v88, v85
	v_fma_f32 v83, -v83, v87, v86
	v_div_fmas_f32 v83, v83, v85, v87
	v_div_fixup_f32 v83, v83, v84, 1.0
	v_cvt_pk_bf16_f32 v83, v83, v0
	v_mul_f32_e32 v0, 0xbfb8aa3b, v94
	v_exp_f32_e32 v84, v0
	v_mul_f32_e32 v0, 0xbfb8aa3b, v95
	v_exp_f32_e32 v85, v0
	s_nop 0
	v_pk_add_f32 v[84:85], v[84:85], 1.0 op_sel_hi:[1,0]
	s_nop 0
	v_div_scale_f32 v0, s[2:3], v85, v85, 1.0
	v_rcp_f32_e32 v86, v0
	s_nop 0
	v_fma_f32 v87, -v0, v86, 1.0
	v_fmac_f32_e32 v86, v87, v86
	v_div_scale_f32 v87, vcc, 1.0, v85, 1.0
	v_mul_f32_e32 v88, v87, v86
	v_fma_f32 v89, -v0, v88, v87
	v_fmac_f32_e32 v88, v89, v86
	v_fma_f32 v0, -v0, v88, v87
	v_div_fmas_f32 v0, v0, v86, v88
	v_div_fixup_f32 v0, v0, v85, 1.0
	v_div_scale_f32 v85, s[2:3], v84, v84, 1.0
	v_rcp_f32_e32 v86, v85
	s_nop 0
	v_fma_f32 v87, -v85, v86, 1.0
	v_fmac_f32_e32 v86, v87, v86
	v_div_scale_f32 v87, vcc, 1.0, v84, 1.0
	v_mul_f32_e32 v88, v87, v86
	v_fma_f32 v89, -v85, v88, v87
	v_fmac_f32_e32 v88, v89, v86
	v_fma_f32 v85, -v85, v88, v87
	v_div_fmas_f32 v85, v85, v86, v88
	v_div_fixup_f32 v84, v85, v84, 1.0
	v_cvt_pk_bf16_f32 v84, v84, v0
	v_mul_f32_e32 v0, 0xbfb8aa3b, v96
	v_exp_f32_e32 v86, v0
	v_mul_f32_e32 v0, 0xbfb8aa3b, v97
	v_exp_f32_e32 v87, v0
	s_nop 0
	v_pk_add_f32 v[86:87], v[86:87], 1.0 op_sel_hi:[1,0]
	s_nop 0
	v_div_scale_f32 v0, s[2:3], v87, v87, 1.0
	v_rcp_f32_e32 v85, v0
	s_nop 0
	v_fma_f32 v88, -v0, v85, 1.0
	v_fmac_f32_e32 v85, v88, v85
	v_div_scale_f32 v88, vcc, 1.0, v87, 1.0
	v_mul_f32_e32 v89, v88, v85
	v_fma_f32 v90, -v0, v89, v88
	v_fmac_f32_e32 v89, v90, v85
	v_fma_f32 v0, -v0, v89, v88
	v_div_fmas_f32 v0, v0, v85, v89
	v_div_scale_f32 v85, s[2:3], v86, v86, 1.0
	v_div_fixup_f32 v0, v0, v87, 1.0
	v_rcp_f32_e32 v87, v85
	s_nop 0
	v_fma_f32 v88, -v85, v87, 1.0
	v_fmac_f32_e32 v87, v88, v87
	v_div_scale_f32 v88, vcc, 1.0, v86, 1.0
	v_mul_f32_e32 v89, v88, v87
	v_fma_f32 v90, -v85, v89, v88
	v_fmac_f32_e32 v89, v90, v87
	v_fma_f32 v85, -v85, v89, v88
	v_div_fmas_f32 v85, v85, v87, v89
	v_div_fixup_f32 v85, v85, v86, 1.0
	v_cvt_pk_bf16_f32 v85, v85, v0
	v_mul_f32_e32 v0, 0xbfb8aa3b, v66
	v_exp_f32_e32 v66, v0
	v_mul_f32_e32 v0, 0xbfb8aa3b, v67
	v_exp_f32_e32 v67, v0
	ds_write2_b64 v191, v[82:83], v[84:85] offset0:68 offset1:70
	v_pk_add_f32 v[66:67], v[66:67], 1.0 op_sel_hi:[1,0]
	s_nop 0
	v_div_scale_f32 v0, s[2:3], v67, v67, 1.0
	v_rcp_f32_e32 v82, v0
	s_nop 0
	v_fma_f32 v83, -v0, v82, 1.0
	v_fmac_f32_e32 v82, v83, v82
	v_div_scale_f32 v83, vcc, 1.0, v67, 1.0
	v_mul_f32_e32 v84, v83, v82
	v_fma_f32 v85, -v0, v84, v83
	v_fmac_f32_e32 v84, v85, v82
	v_fma_f32 v0, -v0, v84, v83
	v_div_fmas_f32 v0, v0, v82, v84
	v_div_fixup_f32 v0, v0, v67, 1.0
	v_div_scale_f32 v67, s[2:3], v66, v66, 1.0
	v_rcp_f32_e32 v82, v67
	s_nop 0
	v_fma_f32 v83, -v67, v82, 1.0
	v_fmac_f32_e32 v82, v83, v82
	v_div_scale_f32 v83, vcc, 1.0, v66, 1.0
	v_mul_f32_e32 v84, v83, v82
	v_fma_f32 v85, -v67, v84, v83
	v_fmac_f32_e32 v84, v85, v82
	v_fma_f32 v67, -v67, v84, v83
	v_div_fmas_f32 v67, v67, v82, v84
	v_div_fixup_f32 v66, v67, v66, 1.0
	v_cvt_pk_bf16_f32 v66, v66, v0
	v_mul_f32_e32 v0, 0xbfb8aa3b, v68
	v_exp_f32_e32 v68, v0
	v_mul_f32_e32 v0, 0xbfb8aa3b, v69
	v_exp_f32_e32 v69, v0
	s_nop 0
	v_pk_add_f32 v[68:69], v[68:69], 1.0 op_sel_hi:[1,0]
	s_nop 0
	v_div_scale_f32 v0, s[2:3], v69, v69, 1.0
	v_rcp_f32_e32 v67, v0
	s_nop 0
	v_fma_f32 v82, -v0, v67, 1.0
	v_fmac_f32_e32 v67, v82, v67
	v_div_scale_f32 v82, vcc, 1.0, v69, 1.0
	v_mul_f32_e32 v83, v82, v67
	v_fma_f32 v84, -v0, v83, v82
	v_fmac_f32_e32 v83, v84, v67
	v_fma_f32 v0, -v0, v83, v82
	v_div_fmas_f32 v0, v0, v67, v83
	v_div_scale_f32 v67, s[2:3], v68, v68, 1.0
	v_div_fixup_f32 v0, v0, v69, 1.0
	v_rcp_f32_e32 v69, v67
	s_nop 0
	v_fma_f32 v82, -v67, v69, 1.0
	v_fmac_f32_e32 v69, v82, v69
	v_div_scale_f32 v82, vcc, 1.0, v68, 1.0
	v_mul_f32_e32 v83, v82, v69
	v_fma_f32 v84, -v67, v83, v82
	v_fmac_f32_e32 v83, v84, v69
	v_fma_f32 v67, -v67, v83, v82
	v_div_fmas_f32 v67, v67, v69, v83
	v_div_fixup_f32 v67, v67, v68, 1.0
	v_cvt_pk_bf16_f32 v67, v67, v0
	v_mul_f32_e32 v0, 0xbfb8aa3b, v70
	v_exp_f32_e32 v68, v0
	v_mul_f32_e32 v0, 0xbfb8aa3b, v71
	v_exp_f32_e32 v69, v0
	s_nop 0
	v_pk_add_f32 v[68:69], v[68:69], 1.0 op_sel_hi:[1,0]
	s_nop 0
	v_div_scale_f32 v0, s[2:3], v69, v69, 1.0
	v_rcp_f32_e32 v70, v0
	s_nop 0
; DI unsigned pk2(float a, float b) { f32v2 v = {a, b}; return __builtin_bit_cast(unsigned, __builtin_convertvector(v, bf16v2)); }
; #define SW_FOR_TOK(j) _Pragma("unroll") for (int j = 0; j < 4; j++)
; #define SW_FOR_FEAT(i, rq) _Pragma("unroll") for (int i = 0; i < 2; i++) _Pragma("unroll") for (int rq = 0; rq < 4; rq++)
; DI float sigmoidf_(float v) { return 1.f / (1.f + __expf(-v)); }
; DI void ph_ple(const Params& P, int g, int layer, bf16_t* smem) {
;     ...
;     SW_FOR_TOK(j) { const int tl_ = wn * 128 + j * 32 + l32;
;       SW_FOR_FEAT(i, rq) { const int c_ = wm * 64 + i * 32 + 8 * rq + 4 * h;
;         *(uint2*)(smem + tl_ * EPLD + c_) = make_uint2(pk2(sigmoidf_(SWV(i, j, 4 * rq)), sigmoidf_(SWV(i, j, 4 * rq + 1))), pk2(sigmoidf_(SWV(i, j, 4 * rq + 2)), sigmoidf_(SWV(i, j, 4 * rq + 3)))); } }
	v_fma_f32 v71, -v0, v70, 1.0
	v_fmac_f32_e32 v70, v71, v70
	v_div_scale_f32 v71, vcc, 1.0, v69, 1.0
	v_mul_f32_e32 v82, v71, v70
	v_fma_f32 v83, -v0, v82, v71
	v_fmac_f32_e32 v82, v83, v70
	v_fma_f32 v0, -v0, v82, v71
	v_div_fmas_f32 v0, v0, v70, v82
	v_div_fixup_f32 v0, v0, v69, 1.0
	v_div_scale_f32 v69, s[2:3], v68, v68, 1.0
	v_rcp_f32_e32 v70, v69
	s_nop 0
	v_fma_f32 v71, -v69, v70, 1.0
	v_fmac_f32_e32 v70, v71, v70
	v_div_scale_f32 v71, vcc, 1.0, v68, 1.0
	v_mul_f32_e32 v82, v71, v70
	v_fma_f32 v83, -v69, v82, v71
	v_fmac_f32_e32 v82, v83, v70
	v_fma_f32 v69, -v69, v82, v71
	v_div_fmas_f32 v69, v69, v70, v82
	v_div_fixup_f32 v68, v69, v68, 1.0
	v_cvt_pk_bf16_f32 v68, v68, v0
	v_mul_f32_e32 v0, 0xbfb8aa3b, v72
	v_exp_f32_e32 v70, v0
	v_mul_f32_e32 v0, 0xbfb8aa3b, v73
	v_exp_f32_e32 v71, v0
	s_nop 0
	v_pk_add_f32 v[70:71], v[70:71], 1.0 op_sel_hi:[1,0]
	s_nop 0
	v_div_scale_f32 v0, s[2:3], v71, v71, 1.0
	v_rcp_f32_e32 v69, v0
	s_nop 0
	v_fma_f32 v72, -v0, v69, 1.0
	v_fmac_f32_e32 v69, v72, v69
	v_div_scale_f32 v72, vcc, 1.0, v71, 1.0
	v_mul_f32_e32 v73, v72, v69
	v_fma_f32 v82, -v0, v73, v72
	v_fmac_f32_e32 v73, v82, v69
	v_fma_f32 v0, -v0, v73, v72
	v_div_fmas_f32 v0, v0, v69, v73
	v_div_scale_f32 v69, s[2:3], v70, v70, 1.0
	v_div_fixup_f32 v0, v0, v71, 1.0
	v_rcp_f32_e32 v71, v69
	s_nop 0
	v_fma_f32 v72, -v69, v71, 1.0
	v_fmac_f32_e32 v71, v72, v71
	v_div_scale_f32 v72, vcc, 1.0, v70, 1.0
	v_mul_f32_e32 v73, v72, v71
	v_fma_f32 v82, -v69, v73, v72
	v_fmac_f32_e32 v73, v82, v71
	v_fma_f32 v69, -v69, v73, v72
	v_div_fmas_f32 v69, v69, v71, v73
	v_div_fixup_f32 v69, v69, v70, 1.0
	v_cvt_pk_bf16_f32 v69, v69, v0
	v_mul_f32_e32 v0, 0xbfb8aa3b, v74
	ds_write2_b64 v191, v[66:67], v[68:69] offset0:72 offset1:74
	v_exp_f32_e32 v66, v0
	v_mul_f32_e32 v0, 0xbfb8aa3b, v75
	v_exp_f32_e32 v67, v0
	s_nop 0
	v_pk_add_f32 v[66:67], v[66:67], 1.0 op_sel_hi:[1,0]
	s_nop 0
	v_div_scale_f32 v0, s[2:3], v67, v67, 1.0
	v_rcp_f32_e32 v68, v0
	s_nop 0
	v_fma_f32 v69, -v0, v68, 1.0
	v_fmac_f32_e32 v68, v69, v68
	v_div_scale_f32 v69, vcc, 1.0, v67, 1.0
	v_mul_f32_e32 v70, v69, v68
	v_fma_f32 v71, -v0, v70, v69
	v_fmac_f32_e32 v70, v71, v68
	v_fma_f32 v0, -v0, v70, v69
	v_div_fmas_f32 v0, v0, v68, v70
	v_div_fixup_f32 v0, v0, v67, 1.0
	v_div_scale_f32 v67, s[2:3], v66, v66, 1.0
	v_rcp_f32_e32 v68, v67
	s_nop 0
	v_fma_f32 v69, -v67, v68, 1.0
	v_fmac_f32_e32 v68, v69, v68
	v_div_scale_f32 v69, vcc, 1.0, v66, 1.0
	v_mul_f32_e32 v70, v69, v68
	v_fma_f32 v71, -v67, v70, v69
	v_fmac_f32_e32 v70, v71, v68
	v_fma_f32 v67, -v67, v70, v69
	v_div_fmas_f32 v67, v67, v68, v70
	v_div_fixup_f32 v66, v67, v66, 1.0
	v_cvt_pk_bf16_f32 v66, v66, v0
	v_mul_f32_e32 v0, 0xbfb8aa3b, v76
	v_exp_f32_e32 v68, v0
	v_mul_f32_e32 v0, 0xbfb8aa3b, v77
	v_exp_f32_e32 v69, v0
	s_nop 0
	v_pk_add_f32 v[68:69], v[68:69], 1.0 op_sel_hi:[1,0]
	s_nop 0
	v_div_scale_f32 v0, s[2:3], v69, v69, 1.0
	v_rcp_f32_e32 v67, v0
	s_nop 0
	v_fma_f32 v70, -v0, v67, 1.0
	v_fmac_f32_e32 v67, v70, v67
	v_div_scale_f32 v70, vcc, 1.0, v69, 1.0
	v_mul_f32_e32 v71, v70, v67
	v_fma_f32 v72, -v0, v71, v70
	v_fmac_f32_e32 v71, v72, v67
	v_fma_f32 v0, -v0, v71, v70
	v_div_fmas_f32 v0, v0, v67, v71
	v_div_scale_f32 v67, s[2:3], v68, v68, 1.0
	v_div_fixup_f32 v0, v0, v69, 1.0
	v_rcp_f32_e32 v69, v67
	s_nop 0
	v_fma_f32 v70, -v67, v69, 1.0
	v_fmac_f32_e32 v69, v70, v69
	v_div_scale_f32 v70, vcc, 1.0, v68, 1.0
	v_mul_f32_e32 v71, v70, v69
	v_fma_f32 v72, -v67, v71, v70
	v_fmac_f32_e32 v71, v72, v69
	v_fma_f32 v67, -v67, v71, v70
	v_div_fmas_f32 v67, v67, v69, v71
	v_div_fixup_f32 v67, v67, v68, 1.0
	v_cvt_pk_bf16_f32 v67, v67, v0
	v_mul_f32_e32 v0, 0xbfb8aa3b, v78
	v_exp_f32_e32 v68, v0
	v_mul_f32_e32 v0, 0xbfb8aa3b, v79
	v_exp_f32_e32 v69, v0
	s_nop 0
	v_pk_add_f32 v[68:69], v[68:69], 1.0 op_sel_hi:[1,0]
	s_nop 0
	v_div_scale_f32 v0, s[2:3], v69, v69, 1.0
	v_rcp_f32_e32 v70, v0
	s_nop 0
	v_fma_f32 v71, -v0, v70, 1.0
	v_fmac_f32_e32 v70, v71, v70
	v_div_scale_f32 v71, vcc, 1.0, v69, 1.0
	v_mul_f32_e32 v72, v71, v70
	v_fma_f32 v73, -v0, v72, v71
	v_fmac_f32_e32 v72, v73, v70
	v_fma_f32 v0, -v0, v72, v71
	v_div_fmas_f32 v0, v0, v70, v72
	v_div_fixup_f32 v0, v0, v69, 1.0
	v_div_scale_f32 v69, s[2:3], v68, v68, 1.0
	v_rcp_f32_e32 v70, v69
	s_nop 0
	v_fma_f32 v71, -v69, v70, 1.0
	v_fmac_f32_e32 v70, v71, v70
	v_div_scale_f32 v71, vcc, 1.0, v68, 1.0
	v_mul_f32_e32 v72, v71, v70
	v_fma_f32 v73, -v69, v72, v71
	v_fmac_f32_e32 v72, v73, v70
	v_fma_f32 v69, -v69, v72, v71
	v_div_fmas_f32 v69, v69, v70, v72
	v_div_fixup_f32 v68, v69, v68, 1.0
	v_cvt_pk_bf16_f32 v68, v68, v0
	v_mul_f32_e32 v0, 0xbfb8aa3b, v80
	v_exp_f32_e32 v70, v0
	v_mul_f32_e32 v0, 0xbfb8aa3b, v81
	v_exp_f32_e32 v71, v0
	s_nop 0
	v_pk_add_f32 v[70:71], v[70:71], 1.0 op_sel_hi:[1,0]
	s_nop 0
	v_div_scale_f32 v0, s[2:3], v71, v71, 1.0
	v_rcp_f32_e32 v69, v0
	s_nop 0
	v_fma_f32 v72, -v0, v69, 1.0
	v_fmac_f32_e32 v69, v72, v69
	v_div_scale_f32 v72, vcc, 1.0, v71, 1.0
	v_mul_f32_e32 v73, v72, v69
	v_fma_f32 v74, -v0, v73, v72
	v_fmac_f32_e32 v73, v74, v69
	v_fma_f32 v0, -v0, v73, v72
	v_div_fmas_f32 v0, v0, v69, v73
	v_div_scale_f32 v69, s[2:3], v70, v70, 1.0
	v_div_fixup_f32 v0, v0, v71, 1.0
	v_rcp_f32_e32 v71, v69
	s_nop 0
	v_fma_f32 v72, -v69, v71, 1.0
	v_fmac_f32_e32 v71, v72, v71
	v_div_scale_f32 v72, vcc, 1.0, v70, 1.0
	v_mul_f32_e32 v73, v72, v71
	v_fma_f32 v74, -v69, v73, v72
	v_fmac_f32_e32 v73, v74, v71
	v_fma_f32 v69, -v69, v73, v72
	v_div_fmas_f32 v69, v69, v71, v73
	v_div_fixup_f32 v69, v69, v70, 1.0
	v_cvt_pk_bf16_f32 v69, v69, v0
	v_mul_f32_e32 v0, 0xbfb8aa3b, v50
	v_exp_f32_e32 v50, v0
	v_mul_f32_e32 v0, 0xbfb8aa3b, v51
	v_exp_f32_e32 v51, v0
; DI unsigned pk2(float a, float b) { f32v2 v = {a, b}; return __builtin_bit_cast(unsigned, __builtin_convertvector(v, bf16v2)); }
; #define SW_FOR_TOK(j) _Pragma("unroll") for (int j = 0; j < 4; j++)
; #define SW_FOR_FEAT(i, rq) _Pragma("unroll") for (int i = 0; i < 2; i++) _Pragma("unroll") for (int rq = 0; rq < 4; rq++)
; DI float sigmoidf_(float v) { return 1.f / (1.f + __expf(-v)); }
; DI void ph_ple(const Params& P, int g, int layer, bf16_t* smem) {
;     ...
;     SW_FOR_TOK(j) { const int tl_ = wn * 128 + j * 32 + l32;
;       SW_FOR_FEAT(i, rq) { const int c_ = wm * 64 + i * 32 + 8 * rq + 4 * h;
;         *(uint2*)(smem + tl_ * EPLD + c_) = make_uint2(pk2(sigmoidf_(SWV(i, j, 4 * rq)), sigmoidf_(SWV(i, j, 4 * rq + 1))), pk2(sigmoidf_(SWV(i, j, 4 * rq + 2)), sigmoidf_(SWV(i, j, 4 * rq + 3)))); } }
	ds_write2_b64 v191, v[66:67], v[68:69] offset0:76 offset1:78
	v_pk_add_f32 v[50:51], v[50:51], 1.0 op_sel_hi:[1,0]
	s_nop 0
	v_div_scale_f32 v0, s[2:3], v51, v51, 1.0
	v_rcp_f32_e32 v66, v0
	s_nop 0
	v_fma_f32 v67, -v0, v66, 1.0
	v_fmac_f32_e32 v66, v67, v66
	v_div_scale_f32 v67, vcc, 1.0, v51, 1.0
	v_mul_f32_e32 v68, v67, v66
	v_fma_f32 v69, -v0, v68, v67
	v_fmac_f32_e32 v68, v69, v66
	v_fma_f32 v0, -v0, v68, v67
	v_div_fmas_f32 v0, v0, v66, v68
	v_div_fixup_f32 v0, v0, v51, 1.0
	v_div_scale_f32 v51, s[2:3], v50, v50, 1.0
	v_rcp_f32_e32 v66, v51
	s_nop 0
	v_fma_f32 v67, -v51, v66, 1.0
	v_fmac_f32_e32 v66, v67, v66
	v_div_scale_f32 v67, vcc, 1.0, v50, 1.0
	v_mul_f32_e32 v68, v67, v66
	v_fma_f32 v69, -v51, v68, v67
	v_fmac_f32_e32 v68, v69, v66
	v_fma_f32 v51, -v51, v68, v67
	v_div_fmas_f32 v51, v51, v66, v68
	v_div_fixup_f32 v50, v51, v50, 1.0
	v_cvt_pk_bf16_f32 v50, v50, v0
	v_mul_f32_e32 v0, 0xbfb8aa3b, v52
	v_exp_f32_e32 v52, v0
	v_mul_f32_e32 v0, 0xbfb8aa3b, v53
	v_exp_f32_e32 v53, v0
	s_nop 0
	v_pk_add_f32 v[52:53], v[52:53], 1.0 op_sel_hi:[1,0]
	s_nop 0
	v_div_scale_f32 v0, s[2:3], v53, v53, 1.0
	v_rcp_f32_e32 v51, v0
	s_nop 0
	v_fma_f32 v66, -v0, v51, 1.0
	v_fmac_f32_e32 v51, v66, v51
	v_div_scale_f32 v66, vcc, 1.0, v53, 1.0
	v_mul_f32_e32 v67, v66, v51
	v_fma_f32 v68, -v0, v67, v66
	v_fmac_f32_e32 v67, v68, v51
	v_fma_f32 v0, -v0, v67, v66
	v_div_fmas_f32 v0, v0, v51, v67
	v_div_scale_f32 v51, s[2:3], v52, v52, 1.0
	v_div_fixup_f32 v0, v0, v53, 1.0
	v_rcp_f32_e32 v53, v51
	s_nop 0
	v_fma_f32 v66, -v51, v53, 1.0
	v_fmac_f32_e32 v53, v66, v53
	v_div_scale_f32 v66, vcc, 1.0, v52, 1.0
	v_mul_f32_e32 v67, v66, v53
	v_fma_f32 v68, -v51, v67, v66
	v_fmac_f32_e32 v67, v68, v53
	v_fma_f32 v51, -v51, v67, v66
	v_div_fmas_f32 v51, v51, v53, v67
	v_div_fixup_f32 v51, v51, v52, 1.0
	v_cvt_pk_bf16_f32 v51, v51, v0
	v_mul_f32_e32 v0, 0xbfb8aa3b, v54
	v_exp_f32_e32 v52, v0
	v_mul_f32_e32 v0, 0xbfb8aa3b, v55
	v_exp_f32_e32 v53, v0
	s_nop 0
	v_pk_add_f32 v[52:53], v[52:53], 1.0 op_sel_hi:[1,0]
	s_nop 0
	v_div_scale_f32 v0, s[2:3], v53, v53, 1.0
	v_rcp_f32_e32 v54, v0
	s_nop 0
	v_fma_f32 v55, -v0, v54, 1.0
	v_fmac_f32_e32 v54, v55, v54
	v_div_scale_f32 v55, vcc, 1.0, v53, 1.0
	v_mul_f32_e32 v66, v55, v54
	v_fma_f32 v67, -v0, v66, v55
	v_fmac_f32_e32 v66, v67, v54
	v_fma_f32 v0, -v0, v66, v55
	v_div_fmas_f32 v0, v0, v54, v66
	v_div_fixup_f32 v0, v0, v53, 1.0
	v_div_scale_f32 v53, s[2:3], v52, v52, 1.0
	v_rcp_f32_e32 v54, v53
	s_nop 0
	v_fma_f32 v55, -v53, v54, 1.0
	v_fmac_f32_e32 v54, v55, v54
	v_div_scale_f32 v55, vcc, 1.0, v52, 1.0
	v_mul_f32_e32 v66, v55, v54
	v_fma_f32 v67, -v53, v66, v55
	v_fmac_f32_e32 v66, v67, v54
	v_fma_f32 v53, -v53, v66, v55
	v_div_fmas_f32 v53, v53, v54, v66
	v_div_fixup_f32 v52, v53, v52, 1.0
	v_cvt_pk_bf16_f32 v52, v52, v0
	v_mul_f32_e32 v0, 0xbfb8aa3b, v56
	v_exp_f32_e32 v54, v0
	v_mul_f32_e32 v0, 0xbfb8aa3b, v57
	v_exp_f32_e32 v55, v0
	s_nop 0
	v_pk_add_f32 v[54:55], v[54:55], 1.0 op_sel_hi:[1,0]
	s_nop 0
	v_div_scale_f32 v0, s[2:3], v55, v55, 1.0
	v_rcp_f32_e32 v53, v0
	s_nop 0
	v_fma_f32 v56, -v0, v53, 1.0
	v_fmac_f32_e32 v53, v56, v53
	v_div_scale_f32 v56, vcc, 1.0, v55, 1.0
	v_mul_f32_e32 v57, v56, v53
	v_fma_f32 v66, -v0, v57, v56
	v_fmac_f32_e32 v57, v66, v53
	v_fma_f32 v0, -v0, v57, v56
	v_div_fmas_f32 v0, v0, v53, v57
	v_div_scale_f32 v53, s[2:3], v54, v54, 1.0
	v_div_fixup_f32 v0, v0, v55, 1.0
	v_rcp_f32_e32 v55, v53
	s_nop 0
	v_fma_f32 v56, -v53, v55, 1.0
	v_fmac_f32_e32 v55, v56, v55
	v_div_scale_f32 v56, vcc, 1.0, v54, 1.0
	v_mul_f32_e32 v57, v56, v55
	v_fma_f32 v66, -v53, v57, v56
	v_fmac_f32_e32 v57, v66, v55
	v_fma_f32 v53, -v53, v57, v56
	v_div_fmas_f32 v53, v53, v55, v57
	v_div_fixup_f32 v53, v53, v54, 1.0
	v_cvt_pk_bf16_f32 v53, v53, v0
	v_mul_f32_e32 v0, 0xbfb8aa3b, v58
	ds_write2_b64 v190, v[50:51], v[52:53] offset0:128 offset1:130
	v_exp_f32_e32 v50, v0
	v_mul_f32_e32 v0, 0xbfb8aa3b, v59
	v_exp_f32_e32 v51, v0
	s_nop 0
	v_pk_add_f32 v[50:51], v[50:51], 1.0 op_sel_hi:[1,0]
	s_nop 0
	v_div_scale_f32 v0, s[2:3], v51, v51, 1.0
	v_rcp_f32_e32 v52, v0
	s_nop 0
	v_fma_f32 v53, -v0, v52, 1.0
	v_fmac_f32_e32 v52, v53, v52
	v_div_scale_f32 v53, vcc, 1.0, v51, 1.0
	v_mul_f32_e32 v54, v53, v52
	v_fma_f32 v55, -v0, v54, v53
	v_fmac_f32_e32 v54, v55, v52
	v_fma_f32 v0, -v0, v54, v53
	v_div_fmas_f32 v0, v0, v52, v54
	v_div_fixup_f32 v0, v0, v51, 1.0
	v_div_scale_f32 v51, s[2:3], v50, v50, 1.0
	v_rcp_f32_e32 v52, v51
	s_nop 0
	v_fma_f32 v53, -v51, v52, 1.0
	v_fmac_f32_e32 v52, v53, v52
	v_div_scale_f32 v53, vcc, 1.0, v50, 1.0
	v_mul_f32_e32 v54, v53, v52
	v_fma_f32 v55, -v51, v54, v53
	v_fmac_f32_e32 v54, v55, v52
	v_fma_f32 v51, -v51, v54, v53
	v_div_fmas_f32 v51, v51, v52, v54
	v_div_fixup_f32 v50, v51, v50, 1.0
	v_cvt_pk_bf16_f32 v50, v50, v0
	v_mul_f32_e32 v0, 0xbfb8aa3b, v60
	v_exp_f32_e32 v52, v0
	v_mul_f32_e32 v0, 0xbfb8aa3b, v61
	v_exp_f32_e32 v53, v0
	s_nop 0
	v_pk_add_f32 v[52:53], v[52:53], 1.0 op_sel_hi:[1,0]
	s_nop 0
	v_div_scale_f32 v0, s[2:3], v53, v53, 1.0
	v_rcp_f32_e32 v51, v0
	s_nop 0
	v_fma_f32 v54, -v0, v51, 1.0
	v_fmac_f32_e32 v51, v54, v51
	v_div_scale_f32 v54, vcc, 1.0, v53, 1.0
	v_mul_f32_e32 v55, v54, v51
	v_fma_f32 v56, -v0, v55, v54
	v_fmac_f32_e32 v55, v56, v51
	v_fma_f32 v0, -v0, v55, v54
	v_div_fmas_f32 v0, v0, v51, v55
	v_div_scale_f32 v51, s[2:3], v52, v52, 1.0
	v_div_fixup_f32 v0, v0, v53, 1.0
	v_rcp_f32_e32 v53, v51
	s_nop 0
	v_fma_f32 v54, -v51, v53, 1.0
	v_fmac_f32_e32 v53, v54, v53
	v_div_scale_f32 v54, vcc, 1.0, v52, 1.0
	v_mul_f32_e32 v55, v54, v53
	v_fma_f32 v56, -v51, v55, v54
	v_fmac_f32_e32 v55, v56, v53
	v_fma_f32 v51, -v51, v55, v54
	v_div_fmas_f32 v51, v51, v53, v55
; DI unsigned pk2(float a, float b) { f32v2 v = {a, b}; return __builtin_bit_cast(unsigned, __builtin_convertvector(v, bf16v2)); }
; #define SW_FOR_TOK(j) _Pragma("unroll") for (int j = 0; j < 4; j++)
; #define SW_FOR_FEAT(i, rq) _Pragma("unroll") for (int i = 0; i < 2; i++) _Pragma("unroll") for (int rq = 0; rq < 4; rq++)
; DI float sigmoidf_(float v) { return 1.f / (1.f + __expf(-v)); }
; DI void ph_ple(const Params& P, int g, int layer, bf16_t* smem) {
;     ...
;     SW_FOR_TOK(j) { const int tl_ = wn * 128 + j * 32 + l32;
;       SW_FOR_FEAT(i, rq) { const int c_ = wm * 64 + i * 32 + 8 * rq + 4 * h;
;         *(uint2*)(smem + tl_ * EPLD + c_) = make_uint2(pk2(sigmoidf_(SWV(i, j, 4 * rq)), sigmoidf_(SWV(i, j, 4 * rq + 1))), pk2(sigmoidf_(SWV(i, j, 4 * rq + 2)), sigmoidf_(SWV(i, j, 4 * rq + 3)))); } }
	v_div_fixup_f32 v51, v51, v52, 1.0
	v_cvt_pk_bf16_f32 v51, v51, v0
	v_mul_f32_e32 v0, 0xbfb8aa3b, v62
	v_exp_f32_e32 v52, v0
	v_mul_f32_e32 v0, 0xbfb8aa3b, v63
	v_exp_f32_e32 v53, v0
	s_nop 0
	v_pk_add_f32 v[52:53], v[52:53], 1.0 op_sel_hi:[1,0]
	s_nop 0
	v_div_scale_f32 v0, s[2:3], v53, v53, 1.0
	v_rcp_f32_e32 v54, v0
	s_nop 0
	v_fma_f32 v55, -v0, v54, 1.0
	v_fmac_f32_e32 v54, v55, v54
	v_div_scale_f32 v55, vcc, 1.0, v53, 1.0
	v_mul_f32_e32 v56, v55, v54
	v_fma_f32 v57, -v0, v56, v55
	v_fmac_f32_e32 v56, v57, v54
	v_fma_f32 v0, -v0, v56, v55
	v_div_fmas_f32 v0, v0, v54, v56
	v_div_fixup_f32 v0, v0, v53, 1.0
	v_div_scale_f32 v53, s[2:3], v52, v52, 1.0
	v_rcp_f32_e32 v54, v53
	s_nop 0
	v_fma_f32 v55, -v53, v54, 1.0
	v_fmac_f32_e32 v54, v55, v54
	v_div_scale_f32 v55, vcc, 1.0, v52, 1.0
	v_mul_f32_e32 v56, v55, v54
	v_fma_f32 v57, -v53, v56, v55
	v_fmac_f32_e32 v56, v57, v54
	v_fma_f32 v53, -v53, v56, v55
	v_div_fmas_f32 v53, v53, v54, v56
	v_div_fixup_f32 v52, v53, v52, 1.0
	v_cvt_pk_bf16_f32 v52, v52, v0
	v_mul_f32_e32 v0, 0xbfb8aa3b, v64
	v_exp_f32_e32 v54, v0
	v_mul_f32_e32 v0, 0xbfb8aa3b, v65
	v_exp_f32_e32 v55, v0
	s_nop 0
	v_pk_add_f32 v[54:55], v[54:55], 1.0 op_sel_hi:[1,0]
	s_nop 0
	v_div_scale_f32 v0, s[2:3], v55, v55, 1.0
	v_rcp_f32_e32 v53, v0
	s_nop 0
	v_fma_f32 v56, -v0, v53, 1.0
	v_fmac_f32_e32 v53, v56, v53
	v_div_scale_f32 v56, vcc, 1.0, v55, 1.0
	v_mul_f32_e32 v57, v56, v53
	v_fma_f32 v58, -v0, v57, v56
	v_fmac_f32_e32 v57, v58, v53
	v_fma_f32 v0, -v0, v57, v56
	v_div_fmas_f32 v0, v0, v53, v57
	v_div_scale_f32 v53, s[2:3], v54, v54, 1.0
	v_div_fixup_f32 v0, v0, v55, 1.0
	v_rcp_f32_e32 v55, v53
	s_nop 0
	v_fma_f32 v56, -v53, v55, 1.0
	v_fmac_f32_e32 v55, v56, v55
	v_div_scale_f32 v56, vcc, 1.0, v54, 1.0
	v_mul_f32_e32 v57, v56, v55
	v_fma_f32 v58, -v53, v57, v56
	v_fmac_f32_e32 v57, v58, v55
	v_fma_f32 v53, -v53, v57, v56
	v_div_fmas_f32 v53, v53, v55, v57
	v_div_fixup_f32 v53, v53, v54, 1.0
	v_cvt_pk_bf16_f32 v53, v53, v0
	v_mul_f32_e32 v0, 0xbfb8aa3b, v34
	v_exp_f32_e32 v34, v0
	v_mul_f32_e32 v0, 0xbfb8aa3b, v35
	v_exp_f32_e32 v35, v0
	ds_write2_b64 v190, v[50:51], v[52:53] offset0:132 offset1:134
	v_pk_add_f32 v[34:35], v[34:35], 1.0 op_sel_hi:[1,0]
	s_nop 0
	v_div_scale_f32 v0, s[2:3], v35, v35, 1.0
	v_rcp_f32_e32 v50, v0
	s_nop 0
	v_fma_f32 v51, -v0, v50, 1.0
	v_fmac_f32_e32 v50, v51, v50
	v_div_scale_f32 v51, vcc, 1.0, v35, 1.0
	v_mul_f32_e32 v52, v51, v50
	v_fma_f32 v53, -v0, v52, v51
	v_fmac_f32_e32 v52, v53, v50
	v_fma_f32 v0, -v0, v52, v51
	v_div_fmas_f32 v0, v0, v50, v52
	v_div_fixup_f32 v0, v0, v35, 1.0
	v_div_scale_f32 v35, s[2:3], v34, v34, 1.0
	v_rcp_f32_e32 v50, v35
	s_nop 0
	v_fma_f32 v51, -v35, v50, 1.0
	v_fmac_f32_e32 v50, v51, v50
	v_div_scale_f32 v51, vcc, 1.0, v34, 1.0
	v_mul_f32_e32 v52, v51, v50
	v_fma_f32 v53, -v35, v52, v51
	v_fmac_f32_e32 v52, v53, v50
	v_fma_f32 v35, -v35, v52, v51
	v_div_fmas_f32 v35, v35, v50, v52
	v_div_fixup_f32 v34, v35, v34, 1.0
	v_cvt_pk_bf16_f32 v34, v34, v0
	v_mul_f32_e32 v0, 0xbfb8aa3b, v36
	v_exp_f32_e32 v36, v0
	v_mul_f32_e32 v0, 0xbfb8aa3b, v37
	v_exp_f32_e32 v37, v0
	s_nop 0
	v_pk_add_f32 v[36:37], v[36:37], 1.0 op_sel_hi:[1,0]
	s_nop 0
	v_div_scale_f32 v0, s[2:3], v37, v37, 1.0
	v_rcp_f32_e32 v35, v0
	s_nop 0
	v_fma_f32 v50, -v0, v35, 1.0
	v_fmac_f32_e32 v35, v50, v35
	v_div_scale_f32 v50, vcc, 1.0, v37, 1.0
	v_mul_f32_e32 v51, v50, v35
	v_fma_f32 v52, -v0, v51, v50
	v_fmac_f32_e32 v51, v52, v35
	v_fma_f32 v0, -v0, v51, v50
	v_div_fmas_f32 v0, v0, v35, v51
	v_div_scale_f32 v35, s[2:3], v36, v36, 1.0
	v_div_fixup_f32 v0, v0, v37, 1.0
	v_rcp_f32_e32 v37, v35
	s_nop 0
	v_fma_f32 v50, -v35, v37, 1.0
	v_fmac_f32_e32 v37, v50, v37
	v_div_scale_f32 v50, vcc, 1.0, v36, 1.0
	v_mul_f32_e32 v51, v50, v37
	v_fma_f32 v52, -v35, v51, v50
	v_fmac_f32_e32 v51, v52, v37
	v_fma_f32 v35, -v35, v51, v50
	v_div_fmas_f32 v35, v35, v37, v51
	v_div_fixup_f32 v35, v35, v36, 1.0
	v_cvt_pk_bf16_f32 v35, v35, v0
	v_mul_f32_e32 v0, 0xbfb8aa3b, v38
	v_exp_f32_e32 v36, v0
	v_mul_f32_e32 v0, 0xbfb8aa3b, v39
	v_exp_f32_e32 v37, v0
	s_nop 0
	v_pk_add_f32 v[36:37], v[36:37], 1.0 op_sel_hi:[1,0]
	s_nop 0
	v_div_scale_f32 v0, s[2:3], v37, v37, 1.0
	v_rcp_f32_e32 v38, v0
	s_nop 0
	v_fma_f32 v39, -v0, v38, 1.0
	v_fmac_f32_e32 v38, v39, v38
	v_div_scale_f32 v39, vcc, 1.0, v37, 1.0
	v_mul_f32_e32 v50, v39, v38
	v_fma_f32 v51, -v0, v50, v39
	v_fmac_f32_e32 v50, v51, v38
	v_fma_f32 v0, -v0, v50, v39
	v_div_fmas_f32 v0, v0, v38, v50
	v_div_fixup_f32 v0, v0, v37, 1.0
	v_div_scale_f32 v37, s[2:3], v36, v36, 1.0
	v_rcp_f32_e32 v38, v37
	s_nop 0
	v_fma_f32 v39, -v37, v38, 1.0
	v_fmac_f32_e32 v38, v39, v38
	v_div_scale_f32 v39, vcc, 1.0, v36, 1.0
	v_mul_f32_e32 v50, v39, v38
	v_fma_f32 v51, -v37, v50, v39
	v_fmac_f32_e32 v50, v51, v38
	v_fma_f32 v37, -v37, v50, v39
	v_div_fmas_f32 v37, v37, v38, v50
	v_div_fixup_f32 v36, v37, v36, 1.0
	v_cvt_pk_bf16_f32 v36, v36, v0
	v_mul_f32_e32 v0, 0xbfb8aa3b, v40
	v_exp_f32_e32 v38, v0
	v_mul_f32_e32 v0, 0xbfb8aa3b, v41
	v_exp_f32_e32 v39, v0
	s_nop 0
	v_pk_add_f32 v[38:39], v[38:39], 1.0 op_sel_hi:[1,0]
	s_nop 0
	v_div_scale_f32 v0, s[2:3], v39, v39, 1.0
	v_rcp_f32_e32 v37, v0
	s_nop 0
	v_fma_f32 v40, -v0, v37, 1.0
	v_fmac_f32_e32 v37, v40, v37
	v_div_scale_f32 v40, vcc, 1.0, v39, 1.0
	v_mul_f32_e32 v41, v40, v37
	v_fma_f32 v50, -v0, v41, v40
	v_fmac_f32_e32 v41, v50, v37
	v_fma_f32 v0, -v0, v41, v40
	v_div_fmas_f32 v0, v0, v37, v41
	v_div_scale_f32 v37, s[2:3], v38, v38, 1.0
	v_div_fixup_f32 v0, v0, v39, 1.0
	v_rcp_f32_e32 v39, v37
	s_nop 0
	v_fma_f32 v40, -v37, v39, 1.0
	v_fmac_f32_e32 v39, v40, v39
	v_div_scale_f32 v40, vcc, 1.0, v38, 1.0
	v_mul_f32_e32 v41, v40, v39
; DI unsigned pk2(float a, float b) { f32v2 v = {a, b}; return __builtin_bit_cast(unsigned, __builtin_convertvector(v, bf16v2)); }
; #define SW_FOR_TOK(j) _Pragma("unroll") for (int j = 0; j < 4; j++)
; #define SW_FOR_FEAT(i, rq) _Pragma("unroll") for (int i = 0; i < 2; i++) _Pragma("unroll") for (int rq = 0; rq < 4; rq++)
; DI float sigmoidf_(float v) { return 1.f / (1.f + __expf(-v)); }
; DI void ph_ple(const Params& P, int g, int layer, bf16_t* smem) {
;     ...
;     SW_FOR_TOK(j) { const int tl_ = wn * 128 + j * 32 + l32;
;       SW_FOR_FEAT(i, rq) { const int c_ = wm * 64 + i * 32 + 8 * rq + 4 * h;
;         *(uint2*)(smem + tl_ * EPLD + c_) = make_uint2(pk2(sigmoidf_(SWV(i, j, 4 * rq)), sigmoidf_(SWV(i, j, 4 * rq + 1))), pk2(sigmoidf_(SWV(i, j, 4 * rq + 2)), sigmoidf_(SWV(i, j, 4 * rq + 3)))); } }
	v_fma_f32 v50, -v37, v41, v40
	v_fmac_f32_e32 v41, v50, v39
	v_fma_f32 v37, -v37, v41, v40
	v_div_fmas_f32 v37, v37, v39, v41
	v_div_fixup_f32 v37, v37, v38, 1.0
	v_cvt_pk_bf16_f32 v37, v37, v0
	v_mul_f32_e32 v0, 0xbfb8aa3b, v42
	ds_write2_b64 v190, v[34:35], v[36:37] offset0:136 offset1:138
	v_exp_f32_e32 v34, v0
	v_mul_f32_e32 v0, 0xbfb8aa3b, v43
	v_exp_f32_e32 v35, v0
	s_nop 0
	v_pk_add_f32 v[34:35], v[34:35], 1.0 op_sel_hi:[1,0]
	s_nop 0
	v_div_scale_f32 v0, s[2:3], v35, v35, 1.0
	v_rcp_f32_e32 v36, v0
	s_nop 0
	v_fma_f32 v37, -v0, v36, 1.0
	v_fmac_f32_e32 v36, v37, v36
	v_div_scale_f32 v37, vcc, 1.0, v35, 1.0
	v_mul_f32_e32 v38, v37, v36
	v_fma_f32 v39, -v0, v38, v37
	v_fmac_f32_e32 v38, v39, v36
	v_fma_f32 v0, -v0, v38, v37
	v_div_fmas_f32 v0, v0, v36, v38
	v_div_fixup_f32 v0, v0, v35, 1.0
	v_div_scale_f32 v35, s[2:3], v34, v34, 1.0
	v_rcp_f32_e32 v36, v35
	s_nop 0
	v_fma_f32 v37, -v35, v36, 1.0
	v_fmac_f32_e32 v36, v37, v36
	v_div_scale_f32 v37, vcc, 1.0, v34, 1.0
	v_mul_f32_e32 v38, v37, v36
	v_fma_f32 v39, -v35, v38, v37
	v_fmac_f32_e32 v38, v39, v36
	v_fma_f32 v35, -v35, v38, v37
	v_div_fmas_f32 v35, v35, v36, v38
	v_div_fixup_f32 v34, v35, v34, 1.0
	v_cvt_pk_bf16_f32 v34, v34, v0
	v_mul_f32_e32 v0, 0xbfb8aa3b, v44
	v_exp_f32_e32 v36, v0
	v_mul_f32_e32 v0, 0xbfb8aa3b, v45
	v_exp_f32_e32 v37, v0
	s_nop 0
	v_pk_add_f32 v[36:37], v[36:37], 1.0 op_sel_hi:[1,0]
	s_nop 0
	v_div_scale_f32 v0, s[2:3], v37, v37, 1.0
	v_rcp_f32_e32 v35, v0
	s_nop 0
	v_fma_f32 v38, -v0, v35, 1.0
	v_fmac_f32_e32 v35, v38, v35
	v_div_scale_f32 v38, vcc, 1.0, v37, 1.0
	v_mul_f32_e32 v39, v38, v35
	v_fma_f32 v40, -v0, v39, v38
	v_fmac_f32_e32 v39, v40, v35
	v_fma_f32 v0, -v0, v39, v38
	v_div_fmas_f32 v0, v0, v35, v39
	v_div_scale_f32 v35, s[2:3], v36, v36, 1.0
	v_div_fixup_f32 v0, v0, v37, 1.0
	v_rcp_f32_e32 v37, v35
	s_nop 0
	v_fma_f32 v38, -v35, v37, 1.0
	v_fmac_f32_e32 v37, v38, v37
	v_div_scale_f32 v38, vcc, 1.0, v36, 1.0
	v_mul_f32_e32 v39, v38, v37
	v_fma_f32 v40, -v35, v39, v38
	v_fmac_f32_e32 v39, v40, v37
	v_fma_f32 v35, -v35, v39, v38
	v_div_fmas_f32 v35, v35, v37, v39
	v_div_fixup_f32 v35, v35, v36, 1.0
	v_cvt_pk_bf16_f32 v35, v35, v0
	v_mul_f32_e32 v0, 0xbfb8aa3b, v46
	v_exp_f32_e32 v36, v0
	v_mul_f32_e32 v0, 0xbfb8aa3b, v47
	v_exp_f32_e32 v37, v0
	s_nop 0
	v_pk_add_f32 v[36:37], v[36:37], 1.0 op_sel_hi:[1,0]
	s_nop 0
	v_div_scale_f32 v0, s[2:3], v37, v37, 1.0
	v_rcp_f32_e32 v38, v0
	s_nop 0
	v_fma_f32 v39, -v0, v38, 1.0
	v_fmac_f32_e32 v38, v39, v38
	v_div_scale_f32 v39, vcc, 1.0, v37, 1.0
	v_mul_f32_e32 v40, v39, v38
	v_fma_f32 v41, -v0, v40, v39
	v_fmac_f32_e32 v40, v41, v38
	v_fma_f32 v0, -v0, v40, v39
	v_div_fmas_f32 v0, v0, v38, v40
	v_div_fixup_f32 v0, v0, v37, 1.0
	v_div_scale_f32 v37, s[2:3], v36, v36, 1.0
	v_rcp_f32_e32 v38, v37
	s_nop 0
	v_fma_f32 v39, -v37, v38, 1.0
	v_fmac_f32_e32 v38, v39, v38
	v_div_scale_f32 v39, vcc, 1.0, v36, 1.0
	v_mul_f32_e32 v40, v39, v38
	v_fma_f32 v41, -v37, v40, v39
	v_fmac_f32_e32 v40, v41, v38
	v_fma_f32 v37, -v37, v40, v39
	v_div_fmas_f32 v37, v37, v38, v40
	v_div_fixup_f32 v36, v37, v36, 1.0
	v_cvt_pk_bf16_f32 v36, v36, v0
	v_mul_f32_e32 v0, 0xbfb8aa3b, v48
	v_exp_f32_e32 v38, v0
	v_mul_f32_e32 v0, 0xbfb8aa3b, v49
	v_exp_f32_e32 v39, v0
	s_nop 0
	v_pk_add_f32 v[38:39], v[38:39], 1.0 op_sel_hi:[1,0]
	s_nop 0
	v_div_scale_f32 v0, s[2:3], v39, v39, 1.0
	v_rcp_f32_e32 v37, v0
	s_nop 0
	v_fma_f32 v40, -v0, v37, 1.0
	v_fmac_f32_e32 v37, v40, v37
	v_div_scale_f32 v40, vcc, 1.0, v39, 1.0
	v_mul_f32_e32 v41, v40, v37
	v_fma_f32 v42, -v0, v41, v40
	v_fmac_f32_e32 v41, v42, v37
	v_fma_f32 v0, -v0, v41, v40
	v_div_fmas_f32 v0, v0, v37, v41
	v_div_scale_f32 v37, s[2:3], v38, v38, 1.0
	v_div_fixup_f32 v0, v0, v39, 1.0
	v_rcp_f32_e32 v39, v37
	s_nop 0
	v_fma_f32 v40, -v37, v39, 1.0
	v_fmac_f32_e32 v39, v40, v39
	v_div_scale_f32 v40, vcc, 1.0, v38, 1.0
	v_mul_f32_e32 v41, v40, v39
	v_fma_f32 v42, -v37, v41, v40
	v_fmac_f32_e32 v41, v42, v39
	v_fma_f32 v37, -v37, v41, v40
	v_div_fmas_f32 v37, v37, v39, v41
	v_div_fixup_f32 v37, v37, v38, 1.0
	v_cvt_pk_bf16_f32 v37, v37, v0
	v_mul_f32_e32 v0, 0xbfb8aa3b, v18
	v_exp_f32_e32 v18, v0
	v_mul_f32_e32 v0, 0xbfb8aa3b, v19
	v_exp_f32_e32 v19, v0
	ds_write2_b64 v190, v[34:35], v[36:37] offset0:140 offset1:142
	v_pk_add_f32 v[18:19], v[18:19], 1.0 op_sel_hi:[1,0]
	s_nop 0
	v_div_scale_f32 v0, s[2:3], v19, v19, 1.0
	v_rcp_f32_e32 v34, v0
	s_nop 0
	v_fma_f32 v35, -v0, v34, 1.0
	v_fmac_f32_e32 v34, v35, v34
	v_div_scale_f32 v35, vcc, 1.0, v19, 1.0
	v_mul_f32_e32 v36, v35, v34
	v_fma_f32 v37, -v0, v36, v35
	v_fmac_f32_e32 v36, v37, v34
	v_fma_f32 v0, -v0, v36, v35
	v_div_fmas_f32 v0, v0, v34, v36
	v_div_fixup_f32 v0, v0, v19, 1.0
	v_div_scale_f32 v19, s[2:3], v18, v18, 1.0
	v_rcp_f32_e32 v34, v19
	s_nop 0
	v_fma_f32 v35, -v19, v34, 1.0
	v_fmac_f32_e32 v34, v35, v34
	v_div_scale_f32 v35, vcc, 1.0, v18, 1.0
	v_mul_f32_e32 v36, v35, v34
	v_fma_f32 v37, -v19, v36, v35
	v_fmac_f32_e32 v36, v37, v34
	v_fma_f32 v19, -v19, v36, v35
	v_div_fmas_f32 v19, v19, v34, v36
	v_div_fixup_f32 v18, v19, v18, 1.0
	v_cvt_pk_bf16_f32 v18, v18, v0
	v_mul_f32_e32 v0, 0xbfb8aa3b, v20
	v_exp_f32_e32 v20, v0
	v_mul_f32_e32 v0, 0xbfb8aa3b, v21
	v_exp_f32_e32 v21, v0
	s_nop 0
	v_pk_add_f32 v[20:21], v[20:21], 1.0 op_sel_hi:[1,0]
	s_nop 0
	v_div_scale_f32 v0, s[2:3], v21, v21, 1.0
	v_rcp_f32_e32 v19, v0
	s_nop 0
	v_fma_f32 v34, -v0, v19, 1.0
	v_fmac_f32_e32 v19, v34, v19
	v_div_scale_f32 v34, vcc, 1.0, v21, 1.0
	v_mul_f32_e32 v35, v34, v19
	v_fma_f32 v36, -v0, v35, v34
	v_fmac_f32_e32 v35, v36, v19
	v_fma_f32 v0, -v0, v35, v34
	v_div_fmas_f32 v0, v0, v19, v35
	v_div_scale_f32 v19, s[2:3], v20, v20, 1.0
; DI unsigned pk2(float a, float b) { f32v2 v = {a, b}; return __builtin_bit_cast(unsigned, __builtin_convertvector(v, bf16v2)); }
; #define SW_FOR_TOK(j) _Pragma("unroll") for (int j = 0; j < 4; j++)
; #define SW_FOR_FEAT(i, rq) _Pragma("unroll") for (int i = 0; i < 2; i++) _Pragma("unroll") for (int rq = 0; rq < 4; rq++)
; DI float sigmoidf_(float v) { return 1.f / (1.f + __expf(-v)); }
; DI void ph_ple(const Params& P, int g, int layer, bf16_t* smem) {
;     ...
;     SW_FOR_TOK(j) { const int tl_ = wn * 128 + j * 32 + l32;
;       SW_FOR_FEAT(i, rq) { const int c_ = wm * 64 + i * 32 + 8 * rq + 4 * h;
;         *(uint2*)(smem + tl_ * EPLD + c_) = make_uint2(pk2(sigmoidf_(SWV(i, j, 4 * rq)), sigmoidf_(SWV(i, j, 4 * rq + 1))), pk2(sigmoidf_(SWV(i, j, 4 * rq + 2)), sigmoidf_(SWV(i, j, 4 * rq + 3)))); } }
	v_div_fixup_f32 v0, v0, v21, 1.0
	v_rcp_f32_e32 v21, v19
	s_nop 0
	v_fma_f32 v34, -v19, v21, 1.0
	v_fmac_f32_e32 v21, v34, v21
	v_div_scale_f32 v34, vcc, 1.0, v20, 1.0
	v_mul_f32_e32 v35, v34, v21
	v_fma_f32 v36, -v19, v35, v34
	v_fmac_f32_e32 v35, v36, v21
	v_fma_f32 v19, -v19, v35, v34
	v_div_fmas_f32 v19, v19, v21, v35
	v_div_fixup_f32 v19, v19, v20, 1.0
	v_cvt_pk_bf16_f32 v19, v19, v0
	v_mul_f32_e32 v0, 0xbfb8aa3b, v22
	v_exp_f32_e32 v20, v0
	v_mul_f32_e32 v0, 0xbfb8aa3b, v23
	v_exp_f32_e32 v21, v0
	s_nop 0
	v_pk_add_f32 v[20:21], v[20:21], 1.0 op_sel_hi:[1,0]
	s_nop 0
	v_div_scale_f32 v0, s[2:3], v21, v21, 1.0
	v_rcp_f32_e32 v22, v0
	s_nop 0
	v_fma_f32 v23, -v0, v22, 1.0
	v_fmac_f32_e32 v22, v23, v22
	v_div_scale_f32 v23, vcc, 1.0, v21, 1.0
	v_mul_f32_e32 v34, v23, v22
	v_fma_f32 v35, -v0, v34, v23
	v_fmac_f32_e32 v34, v35, v22
	v_fma_f32 v0, -v0, v34, v23
	v_div_fmas_f32 v0, v0, v22, v34
	v_div_fixup_f32 v0, v0, v21, 1.0
	v_div_scale_f32 v21, s[2:3], v20, v20, 1.0
	v_rcp_f32_e32 v22, v21
	s_nop 0
	v_fma_f32 v23, -v21, v22, 1.0
	v_fmac_f32_e32 v22, v23, v22
	v_div_scale_f32 v23, vcc, 1.0, v20, 1.0
	v_mul_f32_e32 v34, v23, v22
	v_fma_f32 v35, -v21, v34, v23
	v_fmac_f32_e32 v34, v35, v22
	v_fma_f32 v21, -v21, v34, v23
	v_div_fmas_f32 v21, v21, v22, v34
	v_div_fixup_f32 v20, v21, v20, 1.0
	v_cvt_pk_bf16_f32 v20, v20, v0
	v_mul_f32_e32 v0, 0xbfb8aa3b, v24
	v_exp_f32_e32 v22, v0
	v_mul_f32_e32 v0, 0xbfb8aa3b, v25
	v_exp_f32_e32 v23, v0
	s_nop 0
	v_pk_add_f32 v[22:23], v[22:23], 1.0 op_sel_hi:[1,0]
	s_nop 0
	v_div_scale_f32 v0, s[2:3], v23, v23, 1.0
	v_rcp_f32_e32 v21, v0
	s_nop 0
	v_fma_f32 v24, -v0, v21, 1.0
	v_fmac_f32_e32 v21, v24, v21
	v_div_scale_f32 v24, vcc, 1.0, v23, 1.0
	v_mul_f32_e32 v25, v24, v21
	v_fma_f32 v34, -v0, v25, v24
	v_fmac_f32_e32 v25, v34, v21
	v_fma_f32 v0, -v0, v25, v24
	v_div_fmas_f32 v0, v0, v21, v25
	v_div_scale_f32 v21, s[2:3], v22, v22, 1.0
	v_div_fixup_f32 v0, v0, v23, 1.0
	v_rcp_f32_e32 v23, v21
	s_nop 0
	v_fma_f32 v24, -v21, v23, 1.0
	v_fmac_f32_e32 v23, v24, v23
	v_div_scale_f32 v24, vcc, 1.0, v22, 1.0
	v_mul_f32_e32 v25, v24, v23
	v_fma_f32 v34, -v21, v25, v24
	v_fmac_f32_e32 v25, v34, v23
	v_fma_f32 v21, -v21, v25, v24
	v_div_fmas_f32 v21, v21, v23, v25
	v_div_fixup_f32 v21, v21, v22, 1.0
	v_cvt_pk_bf16_f32 v21, v21, v0
	v_mul_f32_e32 v0, 0xbfb8aa3b, v26
	ds_write2_b64 v189, v[18:19], v[20:21] offset0:192 offset1:194
	v_exp_f32_e32 v18, v0
	v_mul_f32_e32 v0, 0xbfb8aa3b, v27
	v_exp_f32_e32 v19, v0
	s_nop 0
	v_pk_add_f32 v[18:19], v[18:19], 1.0 op_sel_hi:[1,0]
	s_nop 0
	v_div_scale_f32 v0, s[2:3], v19, v19, 1.0
	v_rcp_f32_e32 v20, v0
	s_nop 0
	v_fma_f32 v21, -v0, v20, 1.0
	v_fmac_f32_e32 v20, v21, v20
	v_div_scale_f32 v21, vcc, 1.0, v19, 1.0
	v_mul_f32_e32 v22, v21, v20
	v_fma_f32 v23, -v0, v22, v21
	v_fmac_f32_e32 v22, v23, v20
	v_fma_f32 v0, -v0, v22, v21
	v_div_fmas_f32 v0, v0, v20, v22
	v_div_fixup_f32 v0, v0, v19, 1.0
	v_div_scale_f32 v19, s[2:3], v18, v18, 1.0
	v_rcp_f32_e32 v20, v19
	s_nop 0
	v_fma_f32 v21, -v19, v20, 1.0
	v_fmac_f32_e32 v20, v21, v20
	v_div_scale_f32 v21, vcc, 1.0, v18, 1.0
	v_mul_f32_e32 v22, v21, v20
	v_fma_f32 v23, -v19, v22, v21
	v_fmac_f32_e32 v22, v23, v20
	v_fma_f32 v19, -v19, v22, v21
	v_div_fmas_f32 v19, v19, v20, v22
	v_div_fixup_f32 v18, v19, v18, 1.0
	v_cvt_pk_bf16_f32 v18, v18, v0
	v_mul_f32_e32 v0, 0xbfb8aa3b, v28
	v_exp_f32_e32 v20, v0
	v_mul_f32_e32 v0, 0xbfb8aa3b, v29
	v_exp_f32_e32 v21, v0
	s_nop 0
	v_pk_add_f32 v[20:21], v[20:21], 1.0 op_sel_hi:[1,0]
	s_nop 0
	v_div_scale_f32 v0, s[2:3], v21, v21, 1.0
	v_rcp_f32_e32 v19, v0
	s_nop 0
	v_fma_f32 v22, -v0, v19, 1.0
	v_fmac_f32_e32 v19, v22, v19
	v_div_scale_f32 v22, vcc, 1.0, v21, 1.0
	v_mul_f32_e32 v23, v22, v19
	v_fma_f32 v24, -v0, v23, v22
	v_fmac_f32_e32 v23, v24, v19
	v_fma_f32 v0, -v0, v23, v22
	v_div_fmas_f32 v0, v0, v19, v23
	v_div_scale_f32 v19, s[2:3], v20, v20, 1.0
	v_div_fixup_f32 v0, v0, v21, 1.0
	v_rcp_f32_e32 v21, v19
	s_nop 0
	v_fma_f32 v22, -v19, v21, 1.0
	v_fmac_f32_e32 v21, v22, v21
	v_div_scale_f32 v22, vcc, 1.0, v20, 1.0
	v_mul_f32_e32 v23, v22, v21
	v_fma_f32 v24, -v19, v23, v22
	v_fmac_f32_e32 v23, v24, v21
	v_fma_f32 v19, -v19, v23, v22
	v_div_fmas_f32 v19, v19, v21, v23
	v_div_fixup_f32 v19, v19, v20, 1.0
	v_cvt_pk_bf16_f32 v19, v19, v0
	v_mul_f32_e32 v0, 0xbfb8aa3b, v30
	v_exp_f32_e32 v20, v0
	v_mul_f32_e32 v0, 0xbfb8aa3b, v31
	v_exp_f32_e32 v21, v0
	s_nop 0
	v_pk_add_f32 v[20:21], v[20:21], 1.0 op_sel_hi:[1,0]
	s_nop 0
	v_div_scale_f32 v0, s[2:3], v21, v21, 1.0
	v_rcp_f32_e32 v22, v0
	s_nop 0
	v_fma_f32 v23, -v0, v22, 1.0
	v_fmac_f32_e32 v22, v23, v22
	v_div_scale_f32 v23, vcc, 1.0, v21, 1.0
	v_mul_f32_e32 v24, v23, v22
	v_fma_f32 v25, -v0, v24, v23
	v_fmac_f32_e32 v24, v25, v22
	v_fma_f32 v0, -v0, v24, v23
	v_div_fmas_f32 v0, v0, v22, v24
	v_div_fixup_f32 v0, v0, v21, 1.0
	v_div_scale_f32 v21, s[2:3], v20, v20, 1.0
	v_rcp_f32_e32 v22, v21
	s_nop 0
	v_fma_f32 v23, -v21, v22, 1.0
	v_fmac_f32_e32 v22, v23, v22
	v_div_scale_f32 v23, vcc, 1.0, v20, 1.0
	v_mul_f32_e32 v24, v23, v22
	v_fma_f32 v25, -v21, v24, v23
	v_fmac_f32_e32 v24, v25, v22
	v_fma_f32 v21, -v21, v24, v23
	v_div_fmas_f32 v21, v21, v22, v24
	v_div_fixup_f32 v20, v21, v20, 1.0
	v_cvt_pk_bf16_f32 v20, v20, v0
	v_mul_f32_e32 v0, 0xbfb8aa3b, v32
	v_exp_f32_e32 v22, v0
	v_mul_f32_e32 v0, 0xbfb8aa3b, v33
	v_exp_f32_e32 v23, v0
	s_nop 0
	v_pk_add_f32 v[22:23], v[22:23], 1.0 op_sel_hi:[1,0]
	s_nop 0
	v_div_scale_f32 v0, s[2:3], v23, v23, 1.0
	v_rcp_f32_e32 v21, v0
	s_nop 0
	v_fma_f32 v24, -v0, v21, 1.0
	v_fmac_f32_e32 v21, v24, v21
	v_div_scale_f32 v24, vcc, 1.0, v23, 1.0
	v_mul_f32_e32 v25, v24, v21
	v_fma_f32 v26, -v0, v25, v24
; DI unsigned pk2(float a, float b) { f32v2 v = {a, b}; return __builtin_bit_cast(unsigned, __builtin_convertvector(v, bf16v2)); }
; #define SW_FOR_TOK(j) _Pragma("unroll") for (int j = 0; j < 4; j++)
; #define SW_FOR_FEAT(i, rq) _Pragma("unroll") for (int i = 0; i < 2; i++) _Pragma("unroll") for (int rq = 0; rq < 4; rq++)
; DI float sigmoidf_(float v) { return 1.f / (1.f + __expf(-v)); }
; DI void ph_ple(const Params& P, int g, int layer, bf16_t* smem) {
;     ...
;     SW_FOR_TOK(j) { const int tl_ = wn * 128 + j * 32 + l32;
;       SW_FOR_FEAT(i, rq) { const int c_ = wm * 64 + i * 32 + 8 * rq + 4 * h;
;         *(uint2*)(smem + tl_ * EPLD + c_) = make_uint2(pk2(sigmoidf_(SWV(i, j, 4 * rq)), sigmoidf_(SWV(i, j, 4 * rq + 1))), pk2(sigmoidf_(SWV(i, j, 4 * rq + 2)), sigmoidf_(SWV(i, j, 4 * rq + 3)))); } }
	v_fmac_f32_e32 v25, v26, v21
	v_fma_f32 v0, -v0, v25, v24
	v_div_fmas_f32 v0, v0, v21, v25
	v_div_scale_f32 v21, s[2:3], v22, v22, 1.0
	v_div_fixup_f32 v0, v0, v23, 1.0
	v_rcp_f32_e32 v23, v21
	s_nop 0
	v_fma_f32 v24, -v21, v23, 1.0
	v_fmac_f32_e32 v23, v24, v23
	v_div_scale_f32 v24, vcc, 1.0, v22, 1.0
	v_mul_f32_e32 v25, v24, v23
	v_fma_f32 v26, -v21, v25, v24
	v_fmac_f32_e32 v25, v26, v23
	v_fma_f32 v21, -v21, v25, v24
	v_div_fmas_f32 v21, v21, v23, v25
	v_div_fixup_f32 v21, v21, v22, 1.0
	v_cvt_pk_bf16_f32 v21, v21, v0
	v_mul_f32_e32 v0, 0xbfb8aa3b, v2
	v_exp_f32_e32 v2, v0
	v_mul_f32_e32 v0, 0xbfb8aa3b, v3
	v_exp_f32_e32 v3, v0
	ds_write2_b64 v189, v[18:19], v[20:21] offset0:196 offset1:198
	v_pk_add_f32 v[2:3], v[2:3], 1.0 op_sel_hi:[1,0]
	s_nop 0
	v_div_scale_f32 v0, s[2:3], v3, v3, 1.0
	v_rcp_f32_e32 v18, v0
	s_nop 0
	v_fma_f32 v19, -v0, v18, 1.0
	v_fmac_f32_e32 v18, v19, v18
	v_div_scale_f32 v19, vcc, 1.0, v3, 1.0
	v_mul_f32_e32 v20, v19, v18
	v_fma_f32 v21, -v0, v20, v19
	v_fmac_f32_e32 v20, v21, v18
	v_fma_f32 v0, -v0, v20, v19
	v_div_fmas_f32 v0, v0, v18, v20
	v_div_fixup_f32 v0, v0, v3, 1.0
	v_div_scale_f32 v3, s[2:3], v2, v2, 1.0
	v_rcp_f32_e32 v18, v3
	s_nop 0
	v_fma_f32 v19, -v3, v18, 1.0
	v_fmac_f32_e32 v18, v19, v18
	v_div_scale_f32 v19, vcc, 1.0, v2, 1.0
	v_mul_f32_e32 v20, v19, v18
	v_fma_f32 v21, -v3, v20, v19
	v_fmac_f32_e32 v20, v21, v18
	v_fma_f32 v3, -v3, v20, v19
	v_div_fmas_f32 v3, v3, v18, v20
	v_div_fixup_f32 v2, v3, v2, 1.0
	v_cvt_pk_bf16_f32 v2, v2, v0
	v_mul_f32_e32 v0, 0xbfb8aa3b, v4
	v_exp_f32_e32 v4, v0
	v_mul_f32_e32 v0, 0xbfb8aa3b, v5
	v_exp_f32_e32 v5, v0
	s_nop 0
	v_pk_add_f32 v[4:5], v[4:5], 1.0 op_sel_hi:[1,0]
	s_nop 0
	v_div_scale_f32 v0, s[2:3], v5, v5, 1.0
	v_rcp_f32_e32 v3, v0
	s_nop 0
	v_fma_f32 v18, -v0, v3, 1.0
	v_fmac_f32_e32 v3, v18, v3
	v_div_scale_f32 v18, vcc, 1.0, v5, 1.0
	v_mul_f32_e32 v19, v18, v3
	v_fma_f32 v20, -v0, v19, v18
	v_fmac_f32_e32 v19, v20, v3
	v_fma_f32 v0, -v0, v19, v18
	v_div_fmas_f32 v0, v0, v3, v19
	v_div_scale_f32 v3, s[2:3], v4, v4, 1.0
	v_div_fixup_f32 v0, v0, v5, 1.0
	v_rcp_f32_e32 v5, v3
	s_nop 0
	v_fma_f32 v18, -v3, v5, 1.0
	v_fmac_f32_e32 v5, v18, v5
	v_div_scale_f32 v18, vcc, 1.0, v4, 1.0
	v_mul_f32_e32 v19, v18, v5
	v_fma_f32 v20, -v3, v19, v18
	v_fmac_f32_e32 v19, v20, v5
	v_fma_f32 v3, -v3, v19, v18
	v_div_fmas_f32 v3, v3, v5, v19
	v_div_fixup_f32 v3, v3, v4, 1.0
	v_cvt_pk_bf16_f32 v3, v3, v0
	v_mul_f32_e32 v0, 0xbfb8aa3b, v6
	v_exp_f32_e32 v4, v0
	v_mul_f32_e32 v0, 0xbfb8aa3b, v7
	v_exp_f32_e32 v5, v0
	s_nop 0
	v_pk_add_f32 v[4:5], v[4:5], 1.0 op_sel_hi:[1,0]
	s_nop 0
	v_div_scale_f32 v0, s[2:3], v5, v5, 1.0
	v_rcp_f32_e32 v6, v0
	s_nop 0
	v_fma_f32 v7, -v0, v6, 1.0
	v_fmac_f32_e32 v6, v7, v6
	v_div_scale_f32 v7, vcc, 1.0, v5, 1.0
	v_mul_f32_e32 v18, v7, v6
	v_fma_f32 v19, -v0, v18, v7
	v_fmac_f32_e32 v18, v19, v6
	v_fma_f32 v0, -v0, v18, v7
	v_div_fmas_f32 v0, v0, v6, v18
	v_div_fixup_f32 v0, v0, v5, 1.0
	v_div_scale_f32 v5, s[2:3], v4, v4, 1.0
	v_rcp_f32_e32 v6, v5
	s_nop 0
	v_fma_f32 v7, -v5, v6, 1.0
	v_fmac_f32_e32 v6, v7, v6
	v_div_scale_f32 v7, vcc, 1.0, v4, 1.0
	v_mul_f32_e32 v18, v7, v6
	v_fma_f32 v19, -v5, v18, v7
	v_fmac_f32_e32 v18, v19, v6
	v_fma_f32 v5, -v5, v18, v7
	v_div_fmas_f32 v5, v5, v6, v18
	v_div_fixup_f32 v4, v5, v4, 1.0
	v_cvt_pk_bf16_f32 v4, v4, v0
	v_mul_f32_e32 v0, 0xbfb8aa3b, v8
	v_exp_f32_e32 v6, v0
	v_mul_f32_e32 v0, 0xbfb8aa3b, v9
	v_exp_f32_e32 v7, v0
	s_nop 0
	v_pk_add_f32 v[6:7], v[6:7], 1.0 op_sel_hi:[1,0]
	s_nop 0
	v_div_scale_f32 v0, s[2:3], v7, v7, 1.0
	v_rcp_f32_e32 v5, v0
	s_nop 0
	v_fma_f32 v8, -v0, v5, 1.0
	v_fmac_f32_e32 v5, v8, v5
	v_div_scale_f32 v8, vcc, 1.0, v7, 1.0
	v_mul_f32_e32 v9, v8, v5
	v_fma_f32 v18, -v0, v9, v8
	v_fmac_f32_e32 v9, v18, v5
	v_fma_f32 v0, -v0, v9, v8
	v_div_fmas_f32 v0, v0, v5, v9
	v_div_scale_f32 v5, s[2:3], v6, v6, 1.0
	v_div_fixup_f32 v0, v0, v7, 1.0
	v_rcp_f32_e32 v7, v5
	s_nop 0
	v_fma_f32 v8, -v5, v7, 1.0
	v_fmac_f32_e32 v7, v8, v7
	v_div_scale_f32 v8, vcc, 1.0, v6, 1.0
	v_mul_f32_e32 v9, v8, v7
	v_fma_f32 v18, -v5, v9, v8
	v_fmac_f32_e32 v9, v18, v7
; DI unsigned pk2(float a, float b) { f32v2 v = {a, b}; return __builtin_bit_cast(unsigned, __builtin_convertvector(v, bf16v2)); }
; DI float sigmoidf_(float v) { return 1.f / (1.f + __expf(-v)); }
; DI size_t tix(size_t t, int f, int KT) { return ((t >> 7) * KT + (f >> 6)) * 8192 + (t & 127) * 64 + (f & 63); }
; #define SW_FOR_TOK(j) _Pragma("unroll") for (int j = 0; j < 4; j++)
; #define SW_FOR_FEAT(i, rq) _Pragma("unroll") for (int i = 0; i < 2; i++) _Pragma("unroll") for (int rq = 0; rq < 4; rq++)
; DI void ph_ple(const Params& P, int g, int layer, bf16_t* smem) {
;     ...
;     SW_FOR_TOK(j) { const int tl_ = wn * 128 + j * 32 + l32;
;       SW_FOR_FEAT(i, rq) { const int c_ = wm * 64 + i * 32 + 8 * rq + 4 * h;
;         *(uint2*)(smem + tl_ * EPLD + c_) = make_uint2(pk2(sigmoidf_(SWV(i, j, 4 * rq)), sigmoidf_(SWV(i, j, 4 * rq + 1))), pk2(sigmoidf_(SWV(i, j, 4 * rq + 2)), sigmoidf_(SWV(i, j, 4 * rq + 3)))); } }
;     __syncthreads();
; #pragma unroll 8
;     for (int k = 0; k < 16; k++) {
;       const int c = tid + 256 * k; const int ch8 = c & 7, row = (c >> 3) & 255, fh = c >> 11;
;       const int f = fh * 64 + ch8 * 8; const size_t tg = (size_t)m0 + row;
;       const uint4 sg = *(const uint4*)(smem + row * EPLD + f);
;       bf16_t* ep = x2b + tix(tg, n0 + f, 16);
;       const uint4 eu = *(const uint4*)ep;
;       float* yp = y + tg * 1024 + n0 + f;
;       const uint4 xu = *(const uint4*)(x1b + tix(tg, n0 + f, 16));
	v_fma_f32 v5, -v5, v9, v8
	v_div_fmas_f32 v5, v5, v7, v9
	v_div_fixup_f32 v5, v5, v6, 1.0
	v_cvt_pk_bf16_f32 v5, v5, v0
	v_mul_f32_e32 v0, 0xbfb8aa3b, v10
	ds_write2_b64 v189, v[2:3], v[4:5] offset0:200 offset1:202
	v_exp_f32_e32 v2, v0
	v_mul_f32_e32 v0, 0xbfb8aa3b, v11
	v_exp_f32_e32 v3, v0
	s_nop 0
	v_pk_add_f32 v[2:3], v[2:3], 1.0 op_sel_hi:[1,0]
	s_nop 0
	v_div_scale_f32 v0, s[2:3], v3, v3, 1.0
	v_rcp_f32_e32 v4, v0
	s_nop 0
	v_fma_f32 v5, -v0, v4, 1.0
	v_fmac_f32_e32 v4, v5, v4
	v_div_scale_f32 v5, vcc, 1.0, v3, 1.0
	v_mul_f32_e32 v6, v5, v4
	v_fma_f32 v7, -v0, v6, v5
	v_fmac_f32_e32 v6, v7, v4
	v_fma_f32 v0, -v0, v6, v5
	v_div_fmas_f32 v0, v0, v4, v6
	v_div_fixup_f32 v0, v0, v3, 1.0
	v_div_scale_f32 v3, s[2:3], v2, v2, 1.0
	v_rcp_f32_e32 v4, v3
	s_nop 0
	v_fma_f32 v5, -v3, v4, 1.0
	v_fmac_f32_e32 v4, v5, v4
	v_div_scale_f32 v5, vcc, 1.0, v2, 1.0
	v_mul_f32_e32 v6, v5, v4
	v_fma_f32 v7, -v3, v6, v5
	v_fmac_f32_e32 v6, v7, v4
	v_fma_f32 v3, -v3, v6, v5
	v_div_fmas_f32 v3, v3, v4, v6
	v_div_fixup_f32 v2, v3, v2, 1.0
	v_cvt_pk_bf16_f32 v2, v2, v0
	v_mul_f32_e32 v0, 0xbfb8aa3b, v12
	v_exp_f32_e32 v4, v0
	v_mul_f32_e32 v0, 0xbfb8aa3b, v13
	v_exp_f32_e32 v5, v0
	s_nop 0
	v_pk_add_f32 v[4:5], v[4:5], 1.0 op_sel_hi:[1,0]
	s_nop 0
	v_div_scale_f32 v0, s[2:3], v5, v5, 1.0
	v_rcp_f32_e32 v3, v0
	s_nop 0
	v_fma_f32 v6, -v0, v3, 1.0
	v_fmac_f32_e32 v3, v6, v3
	v_div_scale_f32 v6, vcc, 1.0, v5, 1.0
	v_mul_f32_e32 v7, v6, v3
	v_fma_f32 v8, -v0, v7, v6
	v_fmac_f32_e32 v7, v8, v3
	v_fma_f32 v0, -v0, v7, v6
	v_div_fmas_f32 v0, v0, v3, v7
	v_div_scale_f32 v3, s[2:3], v4, v4, 1.0
	v_div_fixup_f32 v0, v0, v5, 1.0
	v_rcp_f32_e32 v5, v3
	s_nop 0
	v_fma_f32 v6, -v3, v5, 1.0
	v_fmac_f32_e32 v5, v6, v5
	v_div_scale_f32 v6, vcc, 1.0, v4, 1.0
	v_mul_f32_e32 v7, v6, v5
	v_fma_f32 v8, -v3, v7, v6
	v_fmac_f32_e32 v7, v8, v5
	v_fma_f32 v3, -v3, v7, v6
	v_div_fmas_f32 v3, v3, v5, v7
	v_div_fixup_f32 v3, v3, v4, 1.0
	v_cvt_pk_bf16_f32 v3, v3, v0
	v_mul_f32_e32 v0, 0xbfb8aa3b, v14
	v_exp_f32_e32 v4, v0
	v_mul_f32_e32 v0, 0xbfb8aa3b, v15
	v_exp_f32_e32 v5, v0
	s_nop 0
	v_pk_add_f32 v[4:5], v[4:5], 1.0 op_sel_hi:[1,0]
	s_nop 0
	v_div_scale_f32 v0, s[2:3], v5, v5, 1.0
	v_rcp_f32_e32 v6, v0
	s_nop 0
	v_fma_f32 v7, -v0, v6, 1.0
	v_fmac_f32_e32 v6, v7, v6
	v_div_scale_f32 v7, vcc, 1.0, v5, 1.0
	v_mul_f32_e32 v8, v7, v6
	v_fma_f32 v9, -v0, v8, v7
	v_fmac_f32_e32 v8, v9, v6
	v_fma_f32 v0, -v0, v8, v7
	v_div_fmas_f32 v0, v0, v6, v8
	v_div_fixup_f32 v0, v0, v5, 1.0
	v_div_scale_f32 v5, s[2:3], v4, v4, 1.0
	v_rcp_f32_e32 v6, v5
	s_nop 0
	v_fma_f32 v7, -v5, v6, 1.0
	v_fmac_f32_e32 v6, v7, v6
	v_div_scale_f32 v7, vcc, 1.0, v4, 1.0
	v_mul_f32_e32 v8, v7, v6
	v_fma_f32 v9, -v5, v8, v7
	v_fmac_f32_e32 v8, v9, v6
	v_fma_f32 v5, -v5, v8, v7
	v_div_fmas_f32 v5, v5, v6, v8
	v_div_fixup_f32 v4, v5, v4, 1.0
	v_cvt_pk_bf16_f32 v4, v4, v0
	v_mul_f32_e32 v0, 0xbfb8aa3b, v16
	v_exp_f32_e32 v6, v0
	v_mul_f32_e32 v0, 0xbfb8aa3b, v17
	v_exp_f32_e32 v7, v0
	s_nop 0
	v_pk_add_f32 v[6:7], v[6:7], 1.0 op_sel_hi:[1,0]
	s_nop 0
	v_div_scale_f32 v0, s[2:3], v7, v7, 1.0
	v_rcp_f32_e32 v5, v0
	s_nop 0
	v_fma_f32 v8, -v0, v5, 1.0
	v_fmac_f32_e32 v5, v8, v5
	v_div_scale_f32 v8, vcc, 1.0, v7, 1.0
	v_mul_f32_e32 v9, v8, v5
	v_fma_f32 v10, -v0, v9, v8
	v_fmac_f32_e32 v9, v10, v5
	v_fma_f32 v0, -v0, v9, v8
	v_div_fmas_f32 v0, v0, v5, v9
	v_div_scale_f32 v5, s[2:3], v6, v6, 1.0
	v_div_fixup_f32 v0, v0, v7, 1.0
	v_rcp_f32_e32 v7, v5
	s_lshl_b64 s[2:3], s[8:9], 2
	s_add_u32 s10, s6, s2
	s_addc_u32 s11, s7, s3
	v_fma_f32 v8, -v5, v7, 1.0
	v_fmac_f32_e32 v7, v8, v7
	v_div_scale_f32 v8, vcc, 1.0, v6, 1.0
	v_mul_f32_e32 v9, v8, v7
	v_fma_f32 v10, -v5, v9, v8
	v_fmac_f32_e32 v9, v10, v7
	v_fma_f32 v5, -v5, v9, v8
	v_div_fmas_f32 v5, v5, v7, v9
	v_div_fixup_f32 v5, v5, v6, 1.0
	v_cvt_pk_bf16_f32 v5, v5, v0
	ds_write2_b64 v189, v[2:3], v[4:5] offset0:204 offset1:206
	v_lshlrev_b64 v[2:3], 12, v[168:169]
	v_and_b32_e32 v7, 0x7ffff, v171
	v_and_b32_e32 v6, -16, v170
	v_or_b32_e32 v0, v172, v162
	v_lshl_add_u64 v[8:9], s[10:11], 0, v[2:3]
	s_mov_b32 s2, 0
	s_waitcnt lgkmcnt(0)
	s_barrier
